# de-serialised residual GEMM epilogues and P5 tile epilogues (loads hoisted, counted waits); pipelined LDS reads in gdn substitution and KK/QK loops; load hoists in compress/token_prep/phase-C
# speedup vs baseline: 1.0169x; 1.0143x over previous
.Lkk_loop:
	s_add_i32 s26, s26, 8
	v_add_u32_e32 v103, s26, v38
	v_add_u32_e32 v112, s26, v37
	v_add_u32_e32 v113, 0x4000, v103
	ds_read2_b64 v[104:107], v103 offset1:65
	ds_read2_b64 v[108:111], v112 offset1:65
	v_add_u32_e32 v124, 0x4204, v103
	v_add_u32_e32 v126, 0x440c, v103
	ds_read2_b32 v[116:117], v103 offset0:65 offset1:66
	ds_read2_b32 v[118:119], v112 offset0:65 offset1:66
	ds_read2_b32 v[120:121], v112 offset0:195 offset1:196
	ds_read2_b32 v[122:123], v103 offset0:195 offset1:196
	ds_read2_b64 v[112:115], v113 offset0:32 offset1:97
	ds_read2_b32 v[124:125], v124 offset1:1
	ds_read2_b32 v[126:127], v126 offset1:1
	s_waitcnt lgkmcnt(9)
	v_mov_b32_e32 v64, v44
	v_mov_b32_e32 v65, v54
	v_mov_b32_e32 v66, v46
	v_mov_b32_e32 v67, v56
	v_mov_b32_e32 v54, v45
	v_mov_b32_e32 v56, v47
	v_pk_fma_f32 v[32:33], v[48:49], v[64:65], v[32:33] op_sel_hi:[0,1,1]
	v_pk_fma_f32 v[30:31], v[40:41], v[64:65], v[30:31] op_sel_hi:[0,1,1]
	v_pk_fma_f32 v[28:29], v[48:49], v[66:67], v[28:29] op_sel_hi:[0,1,1]
	v_pk_fma_f32 v[26:27], v[40:41], v[66:67], v[26:27] op_sel_hi:[0,1,1]
	v_pk_fma_f32 v[24:25], v[64:65], v[60:61], v[24:25] op_sel_hi:[1,0,1]
	v_pk_fma_f32 v[22:23], v[64:65], v[52:53], v[22:23] op_sel_hi:[1,0,1]
	v_pk_fma_f32 v[20:21], v[60:61], v[66:67], v[20:21] op_sel_hi:[0,1,1]
	v_pk_fma_f32 v[18:19], v[52:53], v[66:67], v[18:19] op_sel_hi:[0,1,1]
	v_pk_fma_f32 v[16:17], v[64:65], v[50:51], v[16:17] op_sel_hi:[1,0,1]
	v_pk_fma_f32 v[14:15], v[64:65], v[42:43], v[14:15] op_sel_hi:[1,0,1]
	v_pk_fma_f32 v[12:13], v[50:51], v[66:67], v[12:13] op_sel_hi:[0,1,1]
	v_pk_fma_f32 v[10:11], v[42:43], v[66:67], v[10:11] op_sel_hi:[0,1,1]
	v_pk_fma_f32 v[8:9], v[64:65], v[62:63], v[8:9] op_sel_hi:[1,0,1]
	v_pk_fma_f32 v[6:7], v[64:65], v[58:59], v[6:7] op_sel_hi:[1,0,1]
	v_pk_fma_f32 v[4:5], v[66:67], v[62:63], v[4:5] op_sel_hi:[1,0,1]
	v_pk_fma_f32 v[2:3], v[66:67], v[58:59], v[2:3] op_sel_hi:[1,0,1]
	v_pk_fma_f32 v[32:33], v[48:49], v[54:55], v[32:33] op_sel:[1,0,0]
	v_pk_fma_f32 v[30:31], v[40:41], v[54:55], v[30:31] op_sel:[1,0,0]
	v_pk_fma_f32 v[28:29], v[48:49], v[56:57], v[28:29] op_sel:[1,0,0]
	v_pk_fma_f32 v[26:27], v[40:41], v[56:57], v[26:27] op_sel:[1,0,0]
	v_pk_fma_f32 v[24:25], v[54:55], v[60:61], v[24:25] op_sel:[0,1,0]
	v_pk_fma_f32 v[22:23], v[54:55], v[52:53], v[22:23] op_sel:[0,1,0]
	v_pk_fma_f32 v[20:21], v[60:61], v[56:57], v[20:21] op_sel:[1,0,0]
	v_pk_fma_f32 v[18:19], v[52:53], v[56:57], v[18:19] op_sel:[1,0,0]
	v_pk_fma_f32 v[16:17], v[54:55], v[50:51], v[16:17] op_sel:[0,1,0]
	v_pk_fma_f32 v[14:15], v[54:55], v[42:43], v[14:15] op_sel:[0,1,0]
	v_pk_fma_f32 v[12:13], v[50:51], v[56:57], v[12:13] op_sel:[1,0,0]
	v_pk_fma_f32 v[10:11], v[42:43], v[56:57], v[10:11] op_sel:[1,0,0]
	v_pk_fma_f32 v[8:9], v[54:55], v[62:63], v[8:9] op_sel:[0,1,0]
	v_pk_fma_f32 v[6:7], v[54:55], v[58:59], v[6:7] op_sel:[0,1,0]
	v_pk_fma_f32 v[4:5], v[56:57], v[62:63], v[4:5] op_sel:[0,1,0]
	v_pk_fma_f32 v[2:3], v[56:57], v[58:59], v[2:3] op_sel:[0,1,0]
	s_add_i32 s26, s26, 8
	v_add_u32_e32 v39, s26, v38
	v_add_u32_e32 v48, s26, v37
	v_add_u32_e32 v49, 0x4000, v39
	ds_read2_b64 v[40:43], v39 offset1:65
	ds_read2_b64 v[44:47], v48 offset1:65
	v_add_u32_e32 v60, 0x4204, v39
	v_add_u32_e32 v62, 0x440c, v39
	ds_read2_b32 v[52:53], v39 offset0:65 offset1:66
	ds_read2_b32 v[54:55], v48 offset0:65 offset1:66
	ds_read2_b32 v[56:57], v48 offset0:195 offset1:196
	ds_read2_b32 v[58:59], v39 offset0:195 offset1:196
	ds_read2_b64 v[48:51], v49 offset0:32 offset1:97
	ds_read2_b32 v[60:61], v60 offset1:1
	ds_read2_b32 v[62:63], v62 offset1:1
	s_waitcnt lgkmcnt(9)
	v_mov_b32_e32 v64, v108
	v_mov_b32_e32 v65, v118
	v_mov_b32_e32 v66, v110
	v_mov_b32_e32 v67, v120
	v_mov_b32_e32 v118, v109
	v_mov_b32_e32 v120, v111
	v_pk_fma_f32 v[32:33], v[112:113], v[64:65], v[32:33] op_sel_hi:[0,1,1]
	v_pk_fma_f32 v[30:31], v[104:105], v[64:65], v[30:31] op_sel_hi:[0,1,1]
	v_pk_fma_f32 v[28:29], v[112:113], v[66:67], v[28:29] op_sel_hi:[0,1,1]
	v_pk_fma_f32 v[26:27], v[104:105], v[66:67], v[26:27] op_sel_hi:[0,1,1]
	v_pk_fma_f32 v[24:25], v[64:65], v[124:125], v[24:25] op_sel_hi:[1,0,1]
	v_pk_fma_f32 v[22:23], v[64:65], v[116:117], v[22:23] op_sel_hi:[1,0,1]
	v_pk_fma_f32 v[20:21], v[124:125], v[66:67], v[20:21] op_sel_hi:[0,1,1]
	v_pk_fma_f32 v[18:19], v[116:117], v[66:67], v[18:19] op_sel_hi:[0,1,1]
	v_pk_fma_f32 v[16:17], v[64:65], v[114:115], v[16:17] op_sel_hi:[1,0,1]
	v_pk_fma_f32 v[14:15], v[64:65], v[106:107], v[14:15] op_sel_hi:[1,0,1]
	v_pk_fma_f32 v[12:13], v[114:115], v[66:67], v[12:13] op_sel_hi:[0,1,1]
	v_pk_fma_f32 v[10:11], v[106:107], v[66:67], v[10:11] op_sel_hi:[0,1,1]
	v_pk_fma_f32 v[8:9], v[64:65], v[126:127], v[8:9] op_sel_hi:[1,0,1]
	v_pk_fma_f32 v[6:7], v[64:65], v[122:123], v[6:7] op_sel_hi:[1,0,1]
	v_pk_fma_f32 v[4:5], v[66:67], v[126:127], v[4:5] op_sel_hi:[1,0,1]
	v_pk_fma_f32 v[2:3], v[66:67], v[122:123], v[2:3] op_sel_hi:[1,0,1]
	v_pk_fma_f32 v[32:33], v[112:113], v[118:119], v[32:33] op_sel:[1,0,0]
	v_pk_fma_f32 v[30:31], v[104:105], v[118:119], v[30:31] op_sel:[1,0,0]
	v_pk_fma_f32 v[28:29], v[112:113], v[120:121], v[28:29] op_sel:[1,0,0]
	v_pk_fma_f32 v[26:27], v[104:105], v[120:121], v[26:27] op_sel:[1,0,0]
	v_pk_fma_f32 v[24:25], v[118:119], v[124:125], v[24:25] op_sel:[0,1,0]
	v_pk_fma_f32 v[22:23], v[118:119], v[116:117], v[22:23] op_sel:[0,1,0]
	v_pk_fma_f32 v[20:21], v[124:125], v[120:121], v[20:21] op_sel:[1,0,0]
	v_pk_fma_f32 v[18:19], v[116:117], v[120:121], v[18:19] op_sel:[1,0,0]
	v_pk_fma_f32 v[16:17], v[118:119], v[114:115], v[16:17] op_sel:[0,1,0]
	v_pk_fma_f32 v[14:15], v[118:119], v[106:107], v[14:15] op_sel:[0,1,0]
	v_pk_fma_f32 v[12:13], v[114:115], v[120:121], v[12:13] op_sel:[1,0,0]
	v_pk_fma_f32 v[10:11], v[106:107], v[120:121], v[10:11] op_sel:[1,0,0]
	v_pk_fma_f32 v[8:9], v[118:119], v[126:127], v[8:9] op_sel:[0,1,0]
	v_pk_fma_f32 v[6:7], v[118:119], v[122:123], v[6:7] op_sel:[0,1,0]
	v_pk_fma_f32 v[4:5], v[120:121], v[126:127], v[4:5] op_sel:[0,1,0]
	v_pk_fma_f32 v[2:3], v[120:121], v[122:123], v[2:3] op_sel:[0,1,0]
	s_cmpk_lg_i32 s26, 0x100
	s_cbranch_scc1 .Lkk_loop
	s_waitcnt lgkmcnt(0)

.LBB0_416:
	s_or_b64 exec, exec, s[40:41]
	s_waitcnt lgkmcnt(0)
	s_barrier
	s_and_saveexec_b64 s[48:49], s[46:47]
	s_cbranch_execz .LBB0_256
	v_add_u32_e32 v0, 0x8200, v1
	v_add_u32_e32 v2, 0x4000, v1
	v_cndmask_b32_e64 v3, v233, v252, s[44:45]
	v_cndmask_b32_e64 v69, v2, v0, s[44:45]
	v_add_u32_e32 v0, v1, v3
	ds_read_b32 v8, v0
	ds_read_b128 v[12:15], v129 offset:50944
	v_mov_b32_e32 v0, 0x10400
	v_mov_b32_e32 v4, 0x10600
	ds_read_b128 v[0:3], v0
	ds_read_b128 v[4:7], v4
	s_waitcnt lgkmcnt(0)
	v_cndmask_b32_e64 v0, v4, v0, s[44:45]
	ds_read_b32 v4, v129 offset:50176
	v_fma_f32 v0, v8, v0, 0
	ds_read2_b32 v[8:9], v69 offset0:65 offset1:130
	v_cndmask_b32_e64 v1, v5, v1, s[44:45]
	v_cndmask_b32_e64 v2, v6, v2, s[44:45]
	s_waitcnt lgkmcnt(1)
	v_mul_f32_e32 v4, v0, v4
	v_cndmask_b32_e64 v3, v7, v3, s[44:45]
	s_waitcnt lgkmcnt(0)
	v_fma_f32 v1, v8, v1, -v4
	ds_read_b64 v[4:5], v129 offset:50432
	v_add_f32_e32 v1, 0, v1
	v_mov_b32_e32 v8, 0x10610
	s_waitcnt lgkmcnt(0)
	v_mul_f32_e32 v4, v0, v4
	v_fma_f32 v2, v9, v2, -v4
	v_fma_f32 v4, -v1, v5, 0
	v_add_f32_e32 v2, v2, v4
	v_add_u32_e32 v4, 0x200, v69
	ds_read2_b32 v[16:17], v4 offset0:67 offset1:132
	ds_read_b96 v[4:6], v129 offset:50688
	ds_read_b128 v[8:11], v8
	s_waitcnt lgkmcnt(1)
	v_mul_f32_e32 v4, v0, v4
	v_fma_f32 v3, v16, v3, -v4
	v_fma_f32 v4, -v1, v5, 0
	v_fma_f32 v5, -v2, v6, 0
	v_add_f32_e32 v3, v3, v4
	v_mov_b32_e32 v4, 0x10410
	v_add_f32_e32 v3, v3, v5
	ds_read_b128 v[4:7], v4
	s_waitcnt lgkmcnt(0)
	v_cndmask_b32_e64 v4, v8, v4, s[44:45]
	v_mul_f32_e32 v8, v0, v12
	v_fma_f32 v4, v17, v4, -v8
	v_fma_f32 v8, -v1, v13, 0
	v_fma_f32 v12, -v2, v14, 0
	v_fma_f32 v13, -v3, v15, 0
	v_add_f32_e32 v4, v4, v8
	v_add_f32_e32 v8, v12, v13
	v_add_f32_e32 v4, v4, v8
	v_add_u32_e32 v8, 0x400, v69
	ds_read_b128 v[12:15], v129 offset:51200
	ds_read2_b32 v[16:17], v8 offset0:69 offset1:134
	v_cndmask_b32_e64 v5, v9, v5, s[44:45]
	v_cndmask_b32_e64 v6, v10, v6, s[44:45]
	v_cndmask_b32_e64 v7, v11, v7, s[44:45]
	s_waitcnt lgkmcnt(1)
	v_mul_f32_e32 v8, v0, v12
	s_waitcnt lgkmcnt(0)
	v_fma_f32 v5, v16, v5, -v8
	v_fma_f32 v8, -v1, v13, 0
	ds_read_b32 v13, v129 offset:51216
	v_fma_f32 v9, -v2, v14, 0
	v_fma_f32 v12, -v3, v15, 0
	s_waitcnt lgkmcnt(0)
	v_fma_f32 v5, -v4, v13, v5
	v_add_f32_e32 v5, v8, v5
	v_add_f32_e32 v8, v9, v12
	ds_read_b128 v[12:15], v129 offset:51456
	v_add_f32_e32 v5, v8, v5
	s_waitcnt lgkmcnt(0)
	v_mul_f32_e32 v8, v0, v12
	v_fma_f32 v6, v17, v6, -v8
	ds_read_b64 v[8:9], v129 offset:51472
	ds_read_b128 v[16:19], v129 offset:51968
	v_fma_f32 v10, -v1, v13, 0
	v_fma_f32 v12, -v2, v14, 0
	v_fma_f32 v13, -v3, v15, 0
	s_waitcnt lgkmcnt(1)
	v_fma_f32 v6, -v4, v8, v6
	v_fma_f32 v8, -v5, v9, v10
	v_add_f32_e32 v6, v6, v8
	v_add_f32_e32 v8, v12, v13
	v_add_f32_e32 v6, v8, v6
	v_add_u32_e32 v8, 0x600, v69
	ds_read2_b32 v[20:21], v8 offset0:71 offset1:136
	ds_read_b128 v[8:11], v129 offset:51712
	s_waitcnt lgkmcnt(0)
	v_mul_f32_e32 v8, v0, v8
	v_fma_f32 v7, v20, v7, -v8
	v_fma_f32 v12, -v1, v9, 0
	v_fma_f32 v13, -v2, v10, 0
	ds_read_b96 v[8:10], v129 offset:51728
	v_fma_f32 v11, -v3, v11, 0
	v_fma_f32 v20, -v2, v18, 0
	s_waitcnt lgkmcnt(0)
	v_fma_f32 v7, -v4, v8, v7
	v_fma_f32 v8, -v5, v9, v12
	v_fma_f32 v9, -v6, v10, v13
	v_add_f32_e32 v7, v7, v8
	v_add_f32_e32 v8, v11, v9
	v_add_f32_e32 v7, v7, v8
	v_mov_b32_e32 v8, 0x10420
	v_mov_b32_e32 v12, 0x10620
	ds_read_b128 v[8:11], v8
	ds_read_b128 v[12:15], v12
	s_waitcnt lgkmcnt(0)
	v_cndmask_b32_e64 v8, v12, v8, s[44:45]
	v_mul_f32_e32 v12, v0, v16
	v_fma_f32 v8, v21, v8, -v12
	v_fma_f32 v12, -v1, v17, 0
	v_fma_f32 v21, -v3, v19, 0
	ds_read_b128 v[16:19], v129 offset:51984
	v_cndmask_b32_e64 v9, v13, v9, s[44:45]
	v_cndmask_b32_e64 v10, v14, v10, s[44:45]
	v_cndmask_b32_e64 v11, v15, v11, s[44:45]
	s_waitcnt lgkmcnt(0)
	v_fma_f32 v8, -v4, v16, v8
	v_fma_f32 v12, -v5, v17, v12
	v_fma_f32 v16, -v6, v18, v20
	v_fma_f32 v17, -v7, v19, v21
	v_add_f32_e32 v8, v8, v12
	v_add_f32_e32 v12, v16, v17
	v_add_f32_e32 v8, v8, v12
	v_add_u32_e32 v12, 0x800, v69
	ds_read_b128 v[16:19], v129 offset:52224
	ds_read2_b32 v[20:21], v12 offset0:73 offset1:138
	s_waitcnt lgkmcnt(1)
	v_mul_f32_e32 v12, v0, v16
	s_waitcnt lgkmcnt(0)
	v_fma_f32 v9, v20, v9, -v12
	v_fma_f32 v12, -v1, v17, 0
	v_fma_f32 v13, -v2, v18, 0
	v_fma_f32 v20, -v3, v19, 0
	ds_read_b128 v[16:19], v129 offset:52240
	s_waitcnt lgkmcnt(0)
	v_fma_f32 v12, -v5, v17, v12
	ds_read_b32 v17, v129 offset:52256
	v_fma_f32 v9, -v4, v16, v9
	v_fma_f32 v13, -v6, v18, v13
	v_fma_f32 v16, -v7, v19, v20
	s_waitcnt lgkmcnt(0)
	v_fma_f32 v9, -v8, v17, v9
	v_add_f32_e32 v9, v12, v9
	v_add_f32_e32 v12, v13, v16
	ds_read_b128 v[16:19], v129 offset:52480
	v_add_f32_e32 v9, v12, v9
	s_waitcnt lgkmcnt(0)
	v_mul_f32_e32 v12, v0, v16
	v_fma_f32 v10, v21, v10, -v12
	v_fma_f32 v12, -v1, v17, 0
	v_fma_f32 v13, -v2, v18, 0
	v_fma_f32 v14, -v3, v19, 0
	ds_read_b128 v[16:19], v129 offset:52496
	ds_read_b128 v[20:23], v129 offset:52992
	s_waitcnt lgkmcnt(1)
	v_fma_f32 v10, -v4, v16, v10
	v_fma_f32 v16, -v5, v17, v12
	v_fma_f32 v17, -v6, v18, v13
	ds_read_b64 v[12:13], v129 offset:52512
	v_fma_f32 v14, -v7, v19, v14
	s_waitcnt lgkmcnt(0)
	v_fma_f32 v10, -v8, v12, v10
	v_fma_f32 v12, -v9, v13, v16
	v_add_f32_e32 v10, v10, v12
	v_add_f32_e32 v12, v17, v14
	v_add_f32_e32 v10, v12, v10
	v_add_u32_e32 v12, 0xa00, v69
	ds_read2_b32 v[24:25], v12 offset0:75 offset1:140
	ds_read_b128 v[12:15], v129 offset:52736
	s_waitcnt lgkmcnt(0)
	v_mul_f32_e32 v12, v0, v12
	v_fma_f32 v11, v24, v11, -v12
	v_fma_f32 v16, -v1, v13, 0
	v_fma_f32 v17, -v2, v14, 0
	v_fma_f32 v18, -v3, v15, 0
	ds_read_b128 v[12:15], v129 offset:52752
	v_fma_f32 v24, -v2, v22, 0
	s_waitcnt lgkmcnt(0)
	v_fma_f32 v11, -v4, v12, v11
	v_fma_f32 v16, -v5, v13, v16
	v_fma_f32 v17, -v6, v14, v17
	ds_read_b96 v[12:14], v129 offset:52768
	v_fma_f32 v15, -v7, v15, v18
	s_waitcnt lgkmcnt(0)
	v_fma_f32 v11, -v8, v12, v11
	v_fma_f32 v12, -v9, v13, v16
	v_fma_f32 v13, -v10, v14, v17
	v_add_f32_e32 v11, v11, v12
	v_add_f32_e32 v12, v15, v13
	v_add_f32_e32 v11, v11, v12
	v_mov_b32_e32 v12, 0x10430
	v_mov_b32_e32 v16, 0x10630
	ds_read_b128 v[12:15], v12
	ds_read_b128 v[16:19], v16
	s_waitcnt lgkmcnt(0)
	v_cndmask_b32_e64 v12, v16, v12, s[44:45]
	v_mul_f32_e32 v16, v0, v20
	v_fma_f32 v12, v25, v12, -v16
	v_fma_f32 v16, -v1, v21, 0
	v_fma_f32 v25, -v3, v23, 0
	ds_read_b128 v[20:23], v129 offset:53008
	v_cndmask_b32_e64 v13, v17, v13, s[44:45]
	v_cndmask_b32_e64 v14, v18, v14, s[44:45]
	v_cndmask_b32_e64 v15, v19, v15, s[44:45]
	s_waitcnt lgkmcnt(0)
	v_fma_f32 v12, -v4, v20, v12
	v_fma_f32 v16, -v5, v21, v16
	v_fma_f32 v24, -v6, v22, v24
	v_fma_f32 v25, -v7, v23, v25
	ds_read_b128 v[20:23], v129 offset:53024
	s_waitcnt lgkmcnt(0)
	v_fma_f32 v12, -v8, v20, v12
	v_fma_f32 v16, -v9, v21, v16
	v_fma_f32 v20, -v10, v22, v24
	v_fma_f32 v21, -v11, v23, v25
	v_add_f32_e32 v12, v12, v16
	v_add_f32_e32 v16, v20, v21
	v_add_f32_e32 v12, v12, v16
	v_add_u32_e32 v16, 0xc00, v69
	ds_read_b128 v[20:23], v129 offset:53248
	ds_read2_b32 v[24:25], v16 offset0:77 offset1:142
	s_waitcnt lgkmcnt(1)
	v_mul_f32_e32 v16, v0, v20
	s_waitcnt lgkmcnt(0)
	v_fma_f32 v13, v24, v13, -v16
	v_fma_f32 v16, -v1, v21, 0
	v_fma_f32 v17, -v2, v22, 0
	v_fma_f32 v24, -v3, v23, 0
	ds_read_b128 v[20:23], v129 offset:53264
	s_waitcnt lgkmcnt(0)
	v_fma_f32 v13, -v4, v20, v13
	v_fma_f32 v16, -v5, v21, v16
	v_fma_f32 v17, -v6, v22, v17
	v_fma_f32 v24, -v7, v23, v24
	ds_read_b128 v[20:23], v129 offset:53280
	s_waitcnt lgkmcnt(0)
	v_fma_f32 v16, -v9, v21, v16
	ds_read_b32 v21, v129 offset:53296
	v_fma_f32 v13, -v8, v20, v13
	v_fma_f32 v17, -v10, v22, v17
	v_fma_f32 v20, -v11, v23, v24
	s_waitcnt lgkmcnt(0)
	v_fma_f32 v13, -v12, v21, v13
	v_add_f32_e32 v13, v16, v13
	v_add_f32_e32 v16, v17, v20
	ds_read_b128 v[20:23], v129 offset:53504
	v_add_f32_e32 v13, v16, v13
	s_waitcnt lgkmcnt(0)
	v_mul_f32_e32 v16, v0, v20
	v_fma_f32 v14, v25, v14, -v16
	v_fma_f32 v16, -v1, v21, 0
	v_fma_f32 v17, -v2, v22, 0
	v_fma_f32 v18, -v3, v23, 0
	ds_read_b128 v[20:23], v129 offset:53520
	ds_read_b128 v[24:27], v129 offset:54016
	s_waitcnt lgkmcnt(1)
	v_fma_f32 v14, -v4, v20, v14
	v_fma_f32 v16, -v5, v21, v16
	v_fma_f32 v17, -v6, v22, v17
	v_fma_f32 v18, -v7, v23, v18
	ds_read_b128 v[20:23], v129 offset:53536
	s_waitcnt lgkmcnt(0)
	v_fma_f32 v14, -v8, v20, v14
	v_fma_f32 v20, -v9, v21, v16
	v_fma_f32 v21, -v10, v22, v17
	ds_read_b64 v[16:17], v129 offset:53552
	v_fma_f32 v18, -v11, v23, v18
	s_waitcnt lgkmcnt(0)
	v_fma_f32 v14, -v12, v16, v14
	v_fma_f32 v16, -v13, v17, v20
	v_add_f32_e32 v14, v14, v16
	v_add_f32_e32 v16, v21, v18
	v_add_f32_e32 v14, v16, v14
	v_add_u32_e32 v16, 0xe00, v69
	ds_read2_b32 v[28:29], v16 offset0:79 offset1:144
	ds_read_b128 v[16:19], v129 offset:53760
	s_waitcnt lgkmcnt(0)
	v_mul_f32_e32 v16, v0, v16
	v_fma_f32 v15, v28, v15, -v16
	v_fma_f32 v20, -v1, v17, 0
	v_fma_f32 v21, -v2, v18, 0
	v_fma_f32 v22, -v3, v19, 0
	ds_read_b128 v[16:19], v129 offset:53776
	v_fma_f32 v28, -v2, v26, 0
	s_waitcnt lgkmcnt(0)
	v_fma_f32 v15, -v4, v16, v15
	v_fma_f32 v20, -v5, v17, v20
	v_fma_f32 v21, -v6, v18, v21
	v_fma_f32 v22, -v7, v19, v22
	ds_read_b128 v[16:19], v129 offset:53792
	s_waitcnt lgkmcnt(0)
	v_fma_f32 v15, -v8, v16, v15
	v_fma_f32 v20, -v9, v17, v20
	v_fma_f32 v21, -v10, v18, v21
	ds_read_b96 v[16:18], v129 offset:53808
	v_fma_f32 v19, -v11, v19, v22
	s_waitcnt lgkmcnt(0)
	v_fma_f32 v15, -v12, v16, v15
	v_fma_f32 v16, -v13, v17, v20
	v_fma_f32 v17, -v14, v18, v21
	v_add_f32_e32 v15, v15, v16
	v_add_f32_e32 v16, v19, v17
	v_add_f32_e32 v15, v15, v16
	v_mov_b32_e32 v16, 0x10440
	v_mov_b32_e32 v20, 0x10640
	ds_read_b128 v[16:19], v16
	ds_read_b128 v[20:23], v20
	s_waitcnt lgkmcnt(0)
	v_cndmask_b32_e64 v16, v20, v16, s[44:45]
	v_mul_f32_e32 v20, v0, v24
	v_fma_f32 v16, v29, v16, -v20
	v_fma_f32 v20, -v1, v25, 0
	v_fma_f32 v29, -v3, v27, 0
	ds_read_b128 v[24:27], v129 offset:54032
	v_cndmask_b32_e64 v17, v21, v17, s[44:45]
	v_cndmask_b32_e64 v18, v22, v18, s[44:45]
	v_cndmask_b32_e64 v19, v23, v19, s[44:45]
	s_waitcnt lgkmcnt(0)
	v_fma_f32 v16, -v4, v24, v16
	v_fma_f32 v20, -v5, v25, v20
	v_fma_f32 v28, -v6, v26, v28
	v_fma_f32 v29, -v7, v27, v29
	ds_read_b128 v[24:27], v129 offset:54048
	s_waitcnt lgkmcnt(0)
	v_fma_f32 v16, -v8, v24, v16
	v_fma_f32 v20, -v9, v25, v20
	v_fma_f32 v28, -v10, v26, v28
	v_fma_f32 v29, -v11, v27, v29
	ds_read_b128 v[24:27], v129 offset:54064
	s_waitcnt lgkmcnt(0)
	v_fma_f32 v16, -v12, v24, v16
	v_fma_f32 v20, -v13, v25, v20
	v_fma_f32 v24, -v14, v26, v28
	v_fma_f32 v25, -v15, v27, v29
	v_add_f32_e32 v16, v16, v20
	v_add_f32_e32 v20, v24, v25
	v_add_f32_e32 v16, v16, v20
	v_add_u32_e32 v20, 0x1000, v69
	ds_read_b128 v[24:27], v129 offset:54272
	ds_read2_b32 v[28:29], v20 offset0:81 offset1:146
	s_waitcnt lgkmcnt(1)
	v_mul_f32_e32 v20, v0, v24
	s_waitcnt lgkmcnt(0)
	v_fma_f32 v17, v28, v17, -v20
	v_fma_f32 v20, -v1, v25, 0
	v_fma_f32 v21, -v2, v26, 0
	v_fma_f32 v28, -v3, v27, 0
	ds_read_b128 v[100:103], v129 offset:54288
	ds_read_b128 v[24:27], v129 offset:54304
	s_waitcnt lgkmcnt(1)
	v_fma_f32 v17, -v4, v100, v17
	v_fma_f32 v20, -v5, v101, v20
	v_fma_f32 v21, -v6, v102, v21
	v_fma_f32 v28, -v7, v103, v28
	s_waitcnt lgkmcnt(0)
	v_fma_f32 v17, -v8, v24, v17
	v_fma_f32 v20, -v9, v25, v20
	v_fma_f32 v21, -v10, v26, v21
	v_fma_f32 v28, -v11, v27, v28
	ds_read_b128 v[24:27], v129 offset:54320
	s_waitcnt lgkmcnt(0)
	v_fma_f32 v20, -v13, v25, v20
	ds_read_b32 v25, v129 offset:54336
	v_fma_f32 v17, -v12, v24, v17
	v_fma_f32 v21, -v14, v26, v21
	v_fma_f32 v24, -v15, v27, v28
	s_waitcnt lgkmcnt(0)
	v_fma_f32 v17, -v16, v25, v17
	v_add_f32_e32 v17, v20, v17
	v_add_f32_e32 v20, v21, v24
	ds_read_b128 v[24:27], v129 offset:54528
	v_add_f32_e32 v17, v20, v17
	s_waitcnt lgkmcnt(0)
	v_mul_f32_e32 v20, v0, v24
	v_fma_f32 v18, v29, v18, -v20
	v_fma_f32 v20, -v1, v25, 0
	v_fma_f32 v21, -v2, v26, 0
	v_fma_f32 v22, -v3, v27, 0
	ds_read_b128 v[24:27], v129 offset:54544
	ds_read_b128 v[28:31], v129 offset:55040
	s_waitcnt lgkmcnt(1)
	v_fma_f32 v18, -v4, v24, v18
	v_fma_f32 v20, -v5, v25, v20
	v_fma_f32 v21, -v6, v26, v21
	v_fma_f32 v22, -v7, v27, v22
	ds_read_b128 v[24:27], v129 offset:54560
	s_waitcnt lgkmcnt(0)
	v_fma_f32 v18, -v8, v24, v18
	v_fma_f32 v20, -v9, v25, v20
	v_fma_f32 v21, -v10, v26, v21
	v_fma_f32 v22, -v11, v27, v22
	ds_read_b128 v[24:27], v129 offset:54576
	s_waitcnt lgkmcnt(0)
	v_fma_f32 v18, -v12, v24, v18
	v_fma_f32 v24, -v13, v25, v20
	v_fma_f32 v25, -v14, v26, v21
	ds_read_b64 v[20:21], v129 offset:54592
	v_fma_f32 v22, -v15, v27, v22
	s_waitcnt lgkmcnt(0)
	v_fma_f32 v18, -v16, v20, v18
	v_fma_f32 v20, -v17, v21, v24
	v_add_f32_e32 v18, v18, v20
	v_add_f32_e32 v20, v25, v22
	v_add_f32_e32 v18, v20, v18
	v_add_u32_e32 v20, 0x1200, v69
	ds_read2_b32 v[32:33], v20 offset0:83 offset1:148
	ds_read_b128 v[20:23], v129 offset:54784
	s_waitcnt lgkmcnt(0)
	v_mul_f32_e32 v20, v0, v20
	v_fma_f32 v19, v32, v19, -v20
	v_fma_f32 v24, -v1, v21, 0
	v_fma_f32 v25, -v2, v22, 0
	v_fma_f32 v26, -v3, v23, 0
	ds_read_b128 v[20:23], v129 offset:54800
	v_fma_f32 v32, -v2, v30, 0
	s_waitcnt lgkmcnt(0)
	v_fma_f32 v19, -v4, v20, v19
	v_fma_f32 v24, -v5, v21, v24
	v_fma_f32 v25, -v6, v22, v25
	v_fma_f32 v26, -v7, v23, v26
	ds_read_b128 v[20:23], v129 offset:54816
	s_waitcnt lgkmcnt(0)
	v_fma_f32 v19, -v8, v20, v19
	v_fma_f32 v24, -v9, v21, v24
	v_fma_f32 v25, -v10, v22, v25
	v_fma_f32 v26, -v11, v23, v26
	ds_read_b128 v[20:23], v129 offset:54832
	s_waitcnt lgkmcnt(0)
	v_fma_f32 v19, -v12, v20, v19
	v_fma_f32 v24, -v13, v21, v24
	v_fma_f32 v25, -v14, v22, v25
	ds_read_b96 v[20:22], v129 offset:54848
	v_fma_f32 v23, -v15, v23, v26
	s_waitcnt lgkmcnt(0)
	v_fma_f32 v19, -v16, v20, v19
	v_fma_f32 v20, -v17, v21, v24
	v_fma_f32 v21, -v18, v22, v25
	v_add_f32_e32 v19, v19, v20
	v_add_f32_e32 v20, v23, v21
	v_add_f32_e32 v19, v19, v20
	v_mov_b32_e32 v20, 0x10450
	v_mov_b32_e32 v24, 0x10650
	ds_read_b128 v[20:23], v20
	ds_read_b128 v[24:27], v24
	s_waitcnt lgkmcnt(0)
	v_cndmask_b32_e64 v20, v24, v20, s[44:45]
	v_mul_f32_e32 v24, v0, v28
	v_fma_f32 v20, v33, v20, -v24
	v_fma_f32 v24, -v1, v29, 0
	v_fma_f32 v33, -v3, v31, 0
	ds_read_b128 v[28:31], v129 offset:55056
	v_cndmask_b32_e64 v21, v25, v21, s[44:45]
	v_cndmask_b32_e64 v22, v26, v22, s[44:45]
	v_cndmask_b32_e64 v23, v27, v23, s[44:45]
	s_waitcnt lgkmcnt(0)
	v_fma_f32 v20, -v4, v28, v20
	v_fma_f32 v24, -v5, v29, v24
	v_fma_f32 v32, -v6, v30, v32
	v_fma_f32 v33, -v7, v31, v33
	ds_read_b128 v[100:103], v129 offset:55072
	ds_read_b128 v[28:31], v129 offset:55088
	s_waitcnt lgkmcnt(1)
	v_fma_f32 v20, -v8, v100, v20
	v_fma_f32 v24, -v9, v101, v24
	v_fma_f32 v32, -v10, v102, v32
	v_fma_f32 v33, -v11, v103, v33
	s_waitcnt lgkmcnt(0)
	v_fma_f32 v20, -v12, v28, v20
	v_fma_f32 v24, -v13, v29, v24
	v_fma_f32 v32, -v14, v30, v32
	v_fma_f32 v33, -v15, v31, v33
	ds_read_b128 v[28:31], v129 offset:55104
	s_waitcnt lgkmcnt(0)
	v_fma_f32 v20, -v16, v28, v20
	v_fma_f32 v24, -v17, v29, v24
	v_fma_f32 v28, -v18, v30, v32
	v_fma_f32 v29, -v19, v31, v33
	v_add_f32_e32 v20, v20, v24
	v_add_f32_e32 v24, v28, v29
	v_add_f32_e32 v20, v20, v24
	v_add_u32_e32 v24, 0x1400, v69
	ds_read_b128 v[28:31], v129 offset:55296
	ds_read2_b32 v[32:33], v24 offset0:85 offset1:150
	s_waitcnt lgkmcnt(1)
	v_mul_f32_e32 v24, v0, v28
	s_waitcnt lgkmcnt(0)
	v_fma_f32 v21, v32, v21, -v24
	v_fma_f32 v24, -v1, v29, 0
	v_fma_f32 v25, -v2, v30, 0
	v_fma_f32 v32, -v3, v31, 0
	ds_read_b128 v[104:107], v129 offset:55312
	ds_read_b128 v[100:103], v129 offset:55328
	ds_read_b128 v[28:31], v129 offset:55344
	s_waitcnt lgkmcnt(2)
	v_fma_f32 v21, -v4, v104, v21
	v_fma_f32 v24, -v5, v105, v24
	v_fma_f32 v25, -v6, v106, v25
	v_fma_f32 v32, -v7, v107, v32
	s_waitcnt lgkmcnt(1)
	v_fma_f32 v21, -v8, v100, v21
	v_fma_f32 v24, -v9, v101, v24
	v_fma_f32 v25, -v10, v102, v25
	v_fma_f32 v32, -v11, v103, v32
	s_waitcnt lgkmcnt(0)
	v_fma_f32 v21, -v12, v28, v21
	v_fma_f32 v24, -v13, v29, v24
	v_fma_f32 v25, -v14, v30, v25
	v_fma_f32 v32, -v15, v31, v32
	ds_read_b128 v[28:31], v129 offset:55360
	s_waitcnt lgkmcnt(0)
	v_fma_f32 v24, -v17, v29, v24
	ds_read_b32 v29, v129 offset:55376
	v_fma_f32 v21, -v16, v28, v21
	v_fma_f32 v25, -v18, v30, v25
	v_fma_f32 v28, -v19, v31, v32
	s_waitcnt lgkmcnt(0)
	v_fma_f32 v21, -v20, v29, v21
	v_add_f32_e32 v21, v24, v21
	v_add_f32_e32 v24, v25, v28
	ds_read_b128 v[28:31], v129 offset:55552
	v_add_f32_e32 v21, v24, v21
	s_waitcnt lgkmcnt(0)
	v_mul_f32_e32 v24, v0, v28
	v_fma_f32 v22, v33, v22, -v24
	v_fma_f32 v24, -v1, v29, 0
	v_fma_f32 v25, -v2, v30, 0
	v_fma_f32 v26, -v3, v31, 0
	ds_read_b128 v[28:31], v129 offset:55568
	ds_read_b128 v[32:35], v129 offset:56064
	s_waitcnt lgkmcnt(1)
	v_fma_f32 v22, -v4, v28, v22
	v_fma_f32 v24, -v5, v29, v24
	v_fma_f32 v25, -v6, v30, v25
	v_fma_f32 v26, -v7, v31, v26
	ds_read_b128 v[100:103], v129 offset:55584
	ds_read_b128 v[28:31], v129 offset:55600
	s_waitcnt lgkmcnt(1)
	v_fma_f32 v22, -v8, v100, v22
	v_fma_f32 v24, -v9, v101, v24
	v_fma_f32 v25, -v10, v102, v25
	v_fma_f32 v26, -v11, v103, v26
	s_waitcnt lgkmcnt(0)
	v_fma_f32 v22, -v12, v28, v22
	v_fma_f32 v24, -v13, v29, v24
	v_fma_f32 v25, -v14, v30, v25
	v_fma_f32 v26, -v15, v31, v26
	ds_read_b128 v[28:31], v129 offset:55616
	s_waitcnt lgkmcnt(0)
	v_fma_f32 v22, -v16, v28, v22
	v_fma_f32 v28, -v17, v29, v24
	v_fma_f32 v29, -v18, v30, v25
	ds_read_b64 v[24:25], v129 offset:55632
	v_fma_f32 v26, -v19, v31, v26
	s_waitcnt lgkmcnt(0)
	v_fma_f32 v22, -v20, v24, v22
	v_fma_f32 v24, -v21, v25, v28
	v_add_f32_e32 v22, v22, v24
	v_add_f32_e32 v24, v29, v26
	v_add_f32_e32 v22, v24, v22
	v_add_u32_e32 v24, 0x1600, v69
	ds_read2_b32 v[36:37], v24 offset0:87 offset1:152
	ds_read_b128 v[24:27], v129 offset:55808
	s_waitcnt lgkmcnt(0)
	v_mul_f32_e32 v24, v0, v24
	v_fma_f32 v23, v36, v23, -v24
	v_fma_f32 v28, -v1, v25, 0
	v_fma_f32 v29, -v2, v26, 0
	v_fma_f32 v30, -v3, v27, 0
	ds_read_b128 v[24:27], v129 offset:55824
	v_fma_f32 v36, -v2, v34, 0
	s_waitcnt lgkmcnt(0)
	v_fma_f32 v23, -v4, v24, v23
	v_fma_f32 v28, -v5, v25, v28
	v_fma_f32 v29, -v6, v26, v29
	v_fma_f32 v30, -v7, v27, v30
	ds_read_b128 v[100:103], v129 offset:55840
	ds_read_b128 v[24:27], v129 offset:55856
	s_waitcnt lgkmcnt(1)
	v_fma_f32 v23, -v8, v100, v23
	v_fma_f32 v28, -v9, v101, v28
	v_fma_f32 v29, -v10, v102, v29
	v_fma_f32 v30, -v11, v103, v30
	s_waitcnt lgkmcnt(0)
	v_fma_f32 v23, -v12, v24, v23
	v_fma_f32 v28, -v13, v25, v28
	v_fma_f32 v29, -v14, v26, v29
	v_fma_f32 v30, -v15, v27, v30
	ds_read_b128 v[24:27], v129 offset:55872
	s_waitcnt lgkmcnt(0)
	v_fma_f32 v23, -v16, v24, v23
	v_fma_f32 v28, -v17, v25, v28
	v_fma_f32 v29, -v18, v26, v29
	ds_read_b96 v[24:26], v129 offset:55888
	v_fma_f32 v27, -v19, v27, v30
	s_waitcnt lgkmcnt(0)
	v_fma_f32 v23, -v20, v24, v23
	v_fma_f32 v24, -v21, v25, v28
	v_fma_f32 v25, -v22, v26, v29
	v_add_f32_e32 v23, v23, v24
	v_add_f32_e32 v24, v27, v25
	v_add_f32_e32 v23, v23, v24
	v_mov_b32_e32 v24, 0x10460
	v_mov_b32_e32 v28, 0x10660
	ds_read_b128 v[24:27], v24
	ds_read_b128 v[28:31], v28
	s_waitcnt lgkmcnt(0)
	v_cndmask_b32_e64 v24, v28, v24, s[44:45]
	v_mul_f32_e32 v28, v0, v32
	v_fma_f32 v24, v37, v24, -v28
	v_fma_f32 v28, -v1, v33, 0
	v_fma_f32 v37, -v3, v35, 0
	ds_read_b128 v[32:35], v129 offset:56080
	v_cndmask_b32_e64 v25, v29, v25, s[44:45]
	v_cndmask_b32_e64 v26, v30, v26, s[44:45]
	v_cndmask_b32_e64 v27, v31, v27, s[44:45]
	s_waitcnt lgkmcnt(0)
	v_fma_f32 v24, -v4, v32, v24
	v_fma_f32 v28, -v5, v33, v28
	v_fma_f32 v36, -v6, v34, v36
	v_fma_f32 v37, -v7, v35, v37
	ds_read_b128 v[104:107], v129 offset:56096
	ds_read_b128 v[100:103], v129 offset:56112
	ds_read_b128 v[32:35], v129 offset:56128
	s_waitcnt lgkmcnt(2)
	v_fma_f32 v24, -v8, v104, v24
	v_fma_f32 v28, -v9, v105, v28
	v_fma_f32 v36, -v10, v106, v36
	v_fma_f32 v37, -v11, v107, v37
	s_waitcnt lgkmcnt(1)
	v_fma_f32 v24, -v12, v100, v24
	v_fma_f32 v28, -v13, v101, v28
	v_fma_f32 v36, -v14, v102, v36
	v_fma_f32 v37, -v15, v103, v37
	s_waitcnt lgkmcnt(0)
	v_fma_f32 v24, -v16, v32, v24
	v_fma_f32 v28, -v17, v33, v28
	v_fma_f32 v36, -v18, v34, v36
	v_fma_f32 v37, -v19, v35, v37
	ds_read_b128 v[32:35], v129 offset:56144
	s_waitcnt lgkmcnt(0)
	v_fma_f32 v24, -v20, v32, v24
	v_fma_f32 v28, -v21, v33, v28
	v_fma_f32 v32, -v22, v34, v36
	v_fma_f32 v33, -v23, v35, v37
	v_add_f32_e32 v24, v24, v28
	v_add_f32_e32 v28, v32, v33
	v_add_f32_e32 v24, v24, v28
	v_add_u32_e32 v28, 0x1800, v69
	ds_read_b128 v[32:35], v129 offset:56320
	ds_read2_b32 v[36:37], v28 offset0:89 offset1:154
	s_waitcnt lgkmcnt(1)
	v_mul_f32_e32 v28, v0, v32
	s_waitcnt lgkmcnt(0)
	v_fma_f32 v25, v36, v25, -v28
	v_fma_f32 v28, -v1, v33, 0
	v_fma_f32 v29, -v2, v34, 0
	v_fma_f32 v36, -v3, v35, 0
	ds_read_b128 v[108:111], v129 offset:56336
	ds_read_b128 v[104:107], v129 offset:56352
	ds_read_b128 v[100:103], v129 offset:56368
	ds_read_b128 v[32:35], v129 offset:56384
	s_waitcnt lgkmcnt(3)
	v_fma_f32 v25, -v4, v108, v25
	v_fma_f32 v28, -v5, v109, v28
	v_fma_f32 v29, -v6, v110, v29
	v_fma_f32 v36, -v7, v111, v36
	s_waitcnt lgkmcnt(2)
	v_fma_f32 v25, -v8, v104, v25
	v_fma_f32 v28, -v9, v105, v28
	v_fma_f32 v29, -v10, v106, v29
	v_fma_f32 v36, -v11, v107, v36
	s_waitcnt lgkmcnt(1)
	v_fma_f32 v25, -v12, v100, v25
	v_fma_f32 v28, -v13, v101, v28
	v_fma_f32 v29, -v14, v102, v29
	v_fma_f32 v36, -v15, v103, v36
	s_waitcnt lgkmcnt(0)
	v_fma_f32 v25, -v16, v32, v25
	v_fma_f32 v28, -v17, v33, v28
	v_fma_f32 v29, -v18, v34, v29
	v_fma_f32 v36, -v19, v35, v36
	ds_read_b128 v[32:35], v129 offset:56400
	s_waitcnt lgkmcnt(0)
	v_fma_f32 v28, -v21, v33, v28
	ds_read_b32 v33, v129 offset:56416
	v_fma_f32 v25, -v20, v32, v25
	v_fma_f32 v29, -v22, v34, v29
	v_fma_f32 v32, -v23, v35, v36
	s_waitcnt lgkmcnt(0)
	v_fma_f32 v25, -v24, v33, v25
	v_add_f32_e32 v25, v28, v25
	v_add_f32_e32 v28, v29, v32
	ds_read_b128 v[32:35], v129 offset:56576
	v_add_f32_e32 v25, v28, v25
	s_waitcnt lgkmcnt(0)
	v_mul_f32_e32 v28, v0, v32
	v_fma_f32 v26, v37, v26, -v28
	v_fma_f32 v28, -v1, v33, 0
	v_fma_f32 v29, -v2, v34, 0
	v_fma_f32 v30, -v3, v35, 0
	ds_read_b128 v[32:35], v129 offset:56592
	ds_read_b128 v[36:39], v129 offset:57088
	s_waitcnt lgkmcnt(1)
	v_fma_f32 v26, -v4, v32, v26
	v_fma_f32 v28, -v5, v33, v28
	v_fma_f32 v29, -v6, v34, v29
	v_fma_f32 v30, -v7, v35, v30
	ds_read_b128 v[104:107], v129 offset:56608
	ds_read_b128 v[100:103], v129 offset:56624
	ds_read_b128 v[32:35], v129 offset:56640
	s_waitcnt lgkmcnt(2)
	v_fma_f32 v26, -v8, v104, v26
	v_fma_f32 v28, -v9, v105, v28
	v_fma_f32 v29, -v10, v106, v29
	v_fma_f32 v30, -v11, v107, v30
	s_waitcnt lgkmcnt(1)
	v_fma_f32 v26, -v12, v100, v26
	v_fma_f32 v28, -v13, v101, v28
	v_fma_f32 v29, -v14, v102, v29
	v_fma_f32 v30, -v15, v103, v30
	s_waitcnt lgkmcnt(0)
	v_fma_f32 v26, -v16, v32, v26
	v_fma_f32 v28, -v17, v33, v28
	v_fma_f32 v29, -v18, v34, v29
	v_fma_f32 v30, -v19, v35, v30
	ds_read_b128 v[32:35], v129 offset:56656
	s_waitcnt lgkmcnt(0)
	v_fma_f32 v26, -v20, v32, v26
	v_fma_f32 v32, -v21, v33, v28
	v_fma_f32 v33, -v22, v34, v29
	ds_read_b64 v[28:29], v129 offset:56672
	v_fma_f32 v30, -v23, v35, v30
	s_waitcnt lgkmcnt(0)
	v_fma_f32 v26, -v24, v28, v26
	v_fma_f32 v28, -v25, v29, v32
	v_add_f32_e32 v26, v26, v28
	v_add_f32_e32 v28, v33, v30
	v_add_f32_e32 v26, v28, v26
	v_add_u32_e32 v28, 0x1a00, v69
	ds_read2_b32 v[40:41], v28 offset0:91 offset1:156
	ds_read_b128 v[28:31], v129 offset:56832
	s_waitcnt lgkmcnt(0)
	v_mul_f32_e32 v28, v0, v28
	v_fma_f32 v27, v40, v27, -v28
	v_fma_f32 v32, -v1, v29, 0
	v_fma_f32 v33, -v2, v30, 0
	v_fma_f32 v34, -v3, v31, 0
	ds_read_b128 v[28:31], v129 offset:56848
	v_fma_f32 v40, -v2, v38, 0
	s_waitcnt lgkmcnt(0)
	v_fma_f32 v27, -v4, v28, v27
	v_fma_f32 v32, -v5, v29, v32
	v_fma_f32 v33, -v6, v30, v33
	v_fma_f32 v34, -v7, v31, v34
	ds_read_b128 v[104:107], v129 offset:56864
	ds_read_b128 v[100:103], v129 offset:56880
	ds_read_b128 v[28:31], v129 offset:56896
	s_waitcnt lgkmcnt(2)
	v_fma_f32 v27, -v8, v104, v27
	v_fma_f32 v32, -v9, v105, v32
	v_fma_f32 v33, -v10, v106, v33
	v_fma_f32 v34, -v11, v107, v34
	s_waitcnt lgkmcnt(1)
	v_fma_f32 v27, -v12, v100, v27
	v_fma_f32 v32, -v13, v101, v32
	v_fma_f32 v33, -v14, v102, v33
	v_fma_f32 v34, -v15, v103, v34
	s_waitcnt lgkmcnt(0)
	v_fma_f32 v27, -v16, v28, v27
	v_fma_f32 v32, -v17, v29, v32
	v_fma_f32 v33, -v18, v30, v33
	v_fma_f32 v34, -v19, v31, v34
	ds_read_b128 v[28:31], v129 offset:56912
	s_waitcnt lgkmcnt(0)
	v_fma_f32 v27, -v20, v28, v27
	v_fma_f32 v32, -v21, v29, v32
	v_fma_f32 v33, -v22, v30, v33
	ds_read_b96 v[28:30], v129 offset:56928
	v_fma_f32 v31, -v23, v31, v34
	s_waitcnt lgkmcnt(0)
	v_fma_f32 v27, -v24, v28, v27
	v_fma_f32 v28, -v25, v29, v32
	v_fma_f32 v29, -v26, v30, v33
	v_add_f32_e32 v27, v27, v28
	v_add_f32_e32 v28, v31, v29
	v_add_f32_e32 v27, v27, v28
	v_mov_b32_e32 v28, 0x10470
	v_mov_b32_e32 v32, 0x10670
	ds_read_b128 v[28:31], v28
	ds_read_b128 v[32:35], v32
	s_waitcnt lgkmcnt(0)
	v_cndmask_b32_e64 v28, v32, v28, s[44:45]
	v_mul_f32_e32 v32, v0, v36
	v_fma_f32 v28, v41, v28, -v32
	v_fma_f32 v32, -v1, v37, 0
	v_fma_f32 v41, -v3, v39, 0
	ds_read_b128 v[36:39], v129 offset:57104
	v_cndmask_b32_e64 v29, v33, v29, s[44:45]
	v_cndmask_b32_e64 v30, v34, v30, s[44:45]
	v_cndmask_b32_e64 v31, v35, v31, s[44:45]
	s_waitcnt lgkmcnt(0)
	v_fma_f32 v28, -v4, v36, v28
	v_fma_f32 v32, -v5, v37, v32
	v_fma_f32 v40, -v6, v38, v40
	v_fma_f32 v41, -v7, v39, v41
	ds_read_b128 v[108:111], v129 offset:57120
	ds_read_b128 v[104:107], v129 offset:57136
	ds_read_b128 v[100:103], v129 offset:57152
	ds_read_b128 v[36:39], v129 offset:57168
	s_waitcnt lgkmcnt(3)
	v_fma_f32 v28, -v8, v108, v28
	v_fma_f32 v32, -v9, v109, v32
	v_fma_f32 v40, -v10, v110, v40
	v_fma_f32 v41, -v11, v111, v41
	s_waitcnt lgkmcnt(2)
	v_fma_f32 v28, -v12, v104, v28
	v_fma_f32 v32, -v13, v105, v32
	v_fma_f32 v40, -v14, v106, v40
	v_fma_f32 v41, -v15, v107, v41
	s_waitcnt lgkmcnt(1)
	v_fma_f32 v28, -v16, v100, v28
	v_fma_f32 v32, -v17, v101, v32
	v_fma_f32 v40, -v18, v102, v40
	v_fma_f32 v41, -v19, v103, v41
	s_waitcnt lgkmcnt(0)
	v_fma_f32 v28, -v20, v36, v28
	v_fma_f32 v32, -v21, v37, v32
	v_fma_f32 v40, -v22, v38, v40
	v_fma_f32 v41, -v23, v39, v41
	ds_read_b128 v[36:39], v129 offset:57184
	s_waitcnt lgkmcnt(0)
	v_fma_f32 v28, -v24, v36, v28
	v_fma_f32 v32, -v25, v37, v32
	v_fma_f32 v36, -v26, v38, v40
	v_fma_f32 v37, -v27, v39, v41
	v_add_f32_e32 v28, v28, v32
	v_add_f32_e32 v32, v36, v37
	v_add_f32_e32 v28, v28, v32
	v_add_u32_e32 v32, 0x1c00, v69
	ds_read_b128 v[36:39], v129 offset:57344
	ds_read2_b32 v[40:41], v32 offset0:93 offset1:158
	s_waitcnt lgkmcnt(1)
	v_mul_f32_e32 v32, v0, v36
	s_waitcnt lgkmcnt(0)
	v_fma_f32 v29, v40, v29, -v32
	v_fma_f32 v32, -v1, v37, 0
	v_fma_f32 v33, -v2, v38, 0
	v_fma_f32 v40, -v3, v39, 0
	ds_read_b128 v[36:39], v129 offset:57360
	ds_read_b128 v[108:111], v129 offset:57376
	ds_read_b128 v[104:107], v129 offset:57392
	ds_read_b128 v[100:103], v129 offset:57408
	s_waitcnt lgkmcnt(3)
	v_fma_f32 v29, -v4, v36, v29
	v_fma_f32 v32, -v5, v37, v32
	v_fma_f32 v33, -v6, v38, v33
	v_fma_f32 v40, -v7, v39, v40
	ds_read_b128 v[36:39], v129 offset:57424
	s_waitcnt lgkmcnt(3)
	v_fma_f32 v29, -v8, v108, v29
	v_fma_f32 v32, -v9, v109, v32
	v_fma_f32 v33, -v10, v110, v33
	v_fma_f32 v40, -v11, v111, v40
	s_waitcnt lgkmcnt(2)
	v_fma_f32 v29, -v12, v104, v29
	v_fma_f32 v32, -v13, v105, v32
	v_fma_f32 v33, -v14, v106, v33
	v_fma_f32 v40, -v15, v107, v40
	s_waitcnt lgkmcnt(1)
	v_fma_f32 v29, -v16, v100, v29
	v_fma_f32 v32, -v17, v101, v32
	v_fma_f32 v33, -v18, v102, v33
	v_fma_f32 v40, -v19, v103, v40
	s_waitcnt lgkmcnt(0)
	v_fma_f32 v29, -v20, v36, v29
	v_fma_f32 v32, -v21, v37, v32
	v_fma_f32 v33, -v22, v38, v33
	v_fma_f32 v40, -v23, v39, v40
	ds_read_b128 v[36:39], v129 offset:57440
	s_waitcnt lgkmcnt(0)
	v_fma_f32 v32, -v25, v37, v32
	ds_read_b32 v37, v129 offset:57456
	v_fma_f32 v29, -v24, v36, v29
	v_fma_f32 v33, -v26, v38, v33
	v_fma_f32 v36, -v27, v39, v40
	s_waitcnt lgkmcnt(0)
	v_fma_f32 v29, -v28, v37, v29
	v_add_f32_e32 v29, v32, v29
	v_add_f32_e32 v32, v33, v36
	ds_read_b128 v[36:39], v129 offset:57600
	v_add_f32_e32 v29, v32, v29
	s_waitcnt lgkmcnt(0)
	v_mul_f32_e32 v32, v0, v36
	v_fma_f32 v30, v41, v30, -v32
	v_fma_f32 v32, -v1, v37, 0
	v_fma_f32 v33, -v2, v38, 0
	v_fma_f32 v34, -v3, v39, 0
	ds_read_b128 v[36:39], v129 offset:57616
	ds_read_b128 v[40:43], v129 offset:58112
	s_waitcnt lgkmcnt(1)
	v_fma_f32 v30, -v4, v36, v30
	v_fma_f32 v32, -v5, v37, v32
	v_fma_f32 v33, -v6, v38, v33
	v_fma_f32 v34, -v7, v39, v34
	ds_read_b128 v[108:111], v129 offset:57632
	ds_read_b128 v[104:107], v129 offset:57648
	ds_read_b128 v[100:103], v129 offset:57664
	ds_read_b128 v[36:39], v129 offset:57680
	s_waitcnt lgkmcnt(3)
	v_fma_f32 v30, -v8, v108, v30
	v_fma_f32 v32, -v9, v109, v32
	v_fma_f32 v33, -v10, v110, v33
	v_fma_f32 v34, -v11, v111, v34
	s_waitcnt lgkmcnt(2)
	v_fma_f32 v30, -v12, v104, v30
	v_fma_f32 v32, -v13, v105, v32
	v_fma_f32 v33, -v14, v106, v33
	v_fma_f32 v34, -v15, v107, v34
	s_waitcnt lgkmcnt(1)
	v_fma_f32 v30, -v16, v100, v30
	v_fma_f32 v32, -v17, v101, v32
	v_fma_f32 v33, -v18, v102, v33
	v_fma_f32 v34, -v19, v103, v34
	s_waitcnt lgkmcnt(0)
	v_fma_f32 v30, -v20, v36, v30
	v_fma_f32 v32, -v21, v37, v32
	v_fma_f32 v33, -v22, v38, v33
	v_fma_f32 v34, -v23, v39, v34
	ds_read_b128 v[36:39], v129 offset:57696
	s_waitcnt lgkmcnt(0)
	v_fma_f32 v30, -v24, v36, v30
	v_fma_f32 v36, -v25, v37, v32
	v_fma_f32 v37, -v26, v38, v33
	ds_read_b64 v[32:33], v129 offset:57712
	v_fma_f32 v34, -v27, v39, v34
	s_waitcnt lgkmcnt(0)
	v_fma_f32 v30, -v28, v32, v30
	v_fma_f32 v32, -v29, v33, v36
	v_add_f32_e32 v30, v30, v32
	v_add_f32_e32 v32, v37, v34
	v_add_f32_e32 v30, v32, v30
	v_add_u32_e32 v32, 0x1e00, v69
	ds_read2_b32 v[44:45], v32 offset0:95 offset1:160
	ds_read_b128 v[32:35], v129 offset:57856
	s_waitcnt lgkmcnt(0)
	v_mul_f32_e32 v32, v0, v32
	v_fma_f32 v31, v44, v31, -v32
	v_fma_f32 v36, -v1, v33, 0
	v_fma_f32 v37, -v2, v34, 0
	v_fma_f32 v38, -v3, v35, 0
	ds_read_b128 v[32:35], v129 offset:57872
	v_fma_f32 v44, -v2, v42, 0
	s_waitcnt lgkmcnt(0)
	v_fma_f32 v31, -v4, v32, v31
	v_fma_f32 v36, -v5, v33, v36
	v_fma_f32 v37, -v6, v34, v37
	v_fma_f32 v38, -v7, v35, v38
	ds_read_b128 v[108:111], v129 offset:57888
	ds_read_b128 v[104:107], v129 offset:57904
	ds_read_b128 v[100:103], v129 offset:57920
	ds_read_b128 v[32:35], v129 offset:57936
	s_waitcnt lgkmcnt(3)
	v_fma_f32 v31, -v8, v108, v31
	v_fma_f32 v36, -v9, v109, v36
	v_fma_f32 v37, -v10, v110, v37
	v_fma_f32 v38, -v11, v111, v38
	s_waitcnt lgkmcnt(2)
	v_fma_f32 v31, -v12, v104, v31
	v_fma_f32 v36, -v13, v105, v36
	v_fma_f32 v37, -v14, v106, v37
	v_fma_f32 v38, -v15, v107, v38
	s_waitcnt lgkmcnt(1)
	v_fma_f32 v31, -v16, v100, v31
	v_fma_f32 v36, -v17, v101, v36
	v_fma_f32 v37, -v18, v102, v37
	v_fma_f32 v38, -v19, v103, v38
	s_waitcnt lgkmcnt(0)
	v_fma_f32 v31, -v20, v32, v31
	v_fma_f32 v36, -v21, v33, v36
	v_fma_f32 v37, -v22, v34, v37
	v_fma_f32 v38, -v23, v35, v38
	ds_read_b128 v[32:35], v129 offset:57952
	s_waitcnt lgkmcnt(0)
	v_fma_f32 v31, -v24, v32, v31
	v_fma_f32 v36, -v25, v33, v36
	v_fma_f32 v37, -v26, v34, v37
	ds_read_b96 v[32:34], v129 offset:57968
	v_fma_f32 v35, -v27, v35, v38
	s_waitcnt lgkmcnt(0)
	v_fma_f32 v31, -v28, v32, v31
	v_fma_f32 v32, -v29, v33, v36
	v_fma_f32 v33, -v30, v34, v37
	v_add_f32_e32 v31, v31, v32
	v_add_f32_e32 v32, v35, v33
	v_add_f32_e32 v31, v31, v32
	v_mov_b32_e32 v32, 0x10480
	v_mov_b32_e32 v36, 0x10680
	ds_read_b128 v[32:35], v32
	ds_read_b128 v[36:39], v36
	s_waitcnt lgkmcnt(0)
	v_cndmask_b32_e64 v32, v36, v32, s[44:45]
	v_mul_f32_e32 v36, v0, v40
	v_fma_f32 v32, v45, v32, -v36
	v_fma_f32 v36, -v1, v41, 0
	v_fma_f32 v45, -v3, v43, 0
	ds_read_b128 v[40:43], v129 offset:58128
	v_cndmask_b32_e64 v33, v37, v33, s[44:45]
	v_cndmask_b32_e64 v34, v38, v34, s[44:45]
	v_cndmask_b32_e64 v35, v39, v35, s[44:45]
	s_waitcnt lgkmcnt(0)
	v_fma_f32 v32, -v4, v40, v32
	v_fma_f32 v36, -v5, v41, v36
	v_fma_f32 v44, -v6, v42, v44
	v_fma_f32 v45, -v7, v43, v45
	ds_read_b128 v[40:43], v129 offset:58144
	ds_read_b128 v[108:111], v129 offset:58160
	ds_read_b128 v[104:107], v129 offset:58176
	ds_read_b128 v[100:103], v129 offset:58192
	s_waitcnt lgkmcnt(3)
	v_fma_f32 v32, -v8, v40, v32
	v_fma_f32 v36, -v9, v41, v36
	v_fma_f32 v44, -v10, v42, v44
	v_fma_f32 v45, -v11, v43, v45
	ds_read_b128 v[40:43], v129 offset:58208
	s_waitcnt lgkmcnt(3)
	v_fma_f32 v32, -v12, v108, v32
	v_fma_f32 v36, -v13, v109, v36
	v_fma_f32 v44, -v14, v110, v44
	v_fma_f32 v45, -v15, v111, v45
	s_waitcnt lgkmcnt(2)
	v_fma_f32 v32, -v16, v104, v32
	v_fma_f32 v36, -v17, v105, v36
	v_fma_f32 v44, -v18, v106, v44
	v_fma_f32 v45, -v19, v107, v45
	s_waitcnt lgkmcnt(1)
	v_fma_f32 v32, -v20, v100, v32
	v_fma_f32 v36, -v21, v101, v36
	v_fma_f32 v44, -v22, v102, v44
	v_fma_f32 v45, -v23, v103, v45
	s_waitcnt lgkmcnt(0)
	v_fma_f32 v32, -v24, v40, v32
	v_fma_f32 v36, -v25, v41, v36
	v_fma_f32 v44, -v26, v42, v44
	v_fma_f32 v45, -v27, v43, v45
	ds_read_b128 v[40:43], v129 offset:58224
	s_waitcnt lgkmcnt(0)
	v_fma_f32 v32, -v28, v40, v32
	v_fma_f32 v36, -v29, v41, v36
	v_fma_f32 v40, -v30, v42, v44
	v_fma_f32 v41, -v31, v43, v45
	v_add_f32_e32 v32, v32, v36
	v_add_f32_e32 v36, v40, v41
	v_add_f32_e32 v32, v32, v36
	v_add_u32_e32 v36, 0x2000, v69
	ds_read_b128 v[40:43], v129 offset:58368
	ds_read2_b32 v[44:45], v36 offset0:97 offset1:162
	s_waitcnt lgkmcnt(1)
	v_mul_f32_e32 v36, v0, v40
	s_waitcnt lgkmcnt(0)
	v_fma_f32 v33, v44, v33, -v36
	v_fma_f32 v36, -v1, v41, 0
	v_fma_f32 v37, -v2, v42, 0
	v_fma_f32 v44, -v3, v43, 0
	ds_read_b128 v[100:103], v129 offset:58384
	ds_read_b128 v[40:43], v129 offset:58400
	ds_read_b128 v[108:111], v129 offset:58416
	ds_read_b128 v[104:107], v129 offset:58432
	s_waitcnt lgkmcnt(3)
	v_fma_f32 v33, -v4, v100, v33
	v_fma_f32 v36, -v5, v101, v36
	v_fma_f32 v37, -v6, v102, v37
	v_fma_f32 v44, -v7, v103, v44
	ds_read_b128 v[100:103], v129 offset:58448
	s_waitcnt lgkmcnt(3)
	v_fma_f32 v33, -v8, v40, v33
	v_fma_f32 v36, -v9, v41, v36
	v_fma_f32 v37, -v10, v42, v37
	v_fma_f32 v44, -v11, v43, v44
	ds_read_b128 v[40:43], v129 offset:58464
	s_waitcnt lgkmcnt(3)
	v_fma_f32 v33, -v12, v108, v33
	v_fma_f32 v36, -v13, v109, v36
	v_fma_f32 v37, -v14, v110, v37
	v_fma_f32 v44, -v15, v111, v44
	s_waitcnt lgkmcnt(2)
	v_fma_f32 v33, -v16, v104, v33
	v_fma_f32 v36, -v17, v105, v36
	v_fma_f32 v37, -v18, v106, v37
	v_fma_f32 v44, -v19, v107, v44
	s_waitcnt lgkmcnt(1)
	v_fma_f32 v33, -v20, v100, v33
	v_fma_f32 v36, -v21, v101, v36
	v_fma_f32 v37, -v22, v102, v37
	v_fma_f32 v44, -v23, v103, v44
	s_waitcnt lgkmcnt(0)
	v_fma_f32 v33, -v24, v40, v33
	v_fma_f32 v36, -v25, v41, v36
	v_fma_f32 v37, -v26, v42, v37
	v_fma_f32 v44, -v27, v43, v44
	ds_read_b128 v[40:43], v129 offset:58480
	s_waitcnt lgkmcnt(0)
	v_fma_f32 v36, -v29, v41, v36
	ds_read_b32 v41, v129 offset:58496
	v_fma_f32 v33, -v28, v40, v33
	v_fma_f32 v37, -v30, v42, v37
	v_fma_f32 v40, -v31, v43, v44
	s_waitcnt lgkmcnt(0)
	v_fma_f32 v33, -v32, v41, v33
	v_add_f32_e32 v33, v36, v33
	v_add_f32_e32 v36, v37, v40
	ds_read_b128 v[40:43], v129 offset:58624
	v_add_f32_e32 v33, v36, v33
	s_waitcnt lgkmcnt(0)
	v_mul_f32_e32 v36, v0, v40
	v_fma_f32 v34, v45, v34, -v36
	v_fma_f32 v36, -v1, v41, 0
	v_fma_f32 v37, -v2, v42, 0
	v_fma_f32 v38, -v3, v43, 0
	ds_read_b128 v[40:43], v129 offset:58640
	ds_read_b128 v[44:47], v129 offset:59136
	s_waitcnt lgkmcnt(1)
	v_fma_f32 v34, -v4, v40, v34
	v_fma_f32 v36, -v5, v41, v36
	v_fma_f32 v37, -v6, v42, v37
	v_fma_f32 v38, -v7, v43, v38
	ds_read_b128 v[40:43], v129 offset:58656
	ds_read_b128 v[108:111], v129 offset:58672
	ds_read_b128 v[104:107], v129 offset:58688
	ds_read_b128 v[100:103], v129 offset:58704
	s_waitcnt lgkmcnt(3)
	v_fma_f32 v34, -v8, v40, v34
	v_fma_f32 v36, -v9, v41, v36
	v_fma_f32 v37, -v10, v42, v37
	v_fma_f32 v38, -v11, v43, v38
	ds_read_b128 v[40:43], v129 offset:58720
	s_waitcnt lgkmcnt(3)
	v_fma_f32 v34, -v12, v108, v34
	v_fma_f32 v36, -v13, v109, v36
	v_fma_f32 v37, -v14, v110, v37
	v_fma_f32 v38, -v15, v111, v38
	s_waitcnt lgkmcnt(2)
	v_fma_f32 v34, -v16, v104, v34
	v_fma_f32 v36, -v17, v105, v36
	v_fma_f32 v37, -v18, v106, v37
	v_fma_f32 v38, -v19, v107, v38
	s_waitcnt lgkmcnt(1)
	v_fma_f32 v34, -v20, v100, v34
	v_fma_f32 v36, -v21, v101, v36
	v_fma_f32 v37, -v22, v102, v37
	v_fma_f32 v38, -v23, v103, v38
	s_waitcnt lgkmcnt(0)
	v_fma_f32 v34, -v24, v40, v34
	v_fma_f32 v36, -v25, v41, v36
	v_fma_f32 v37, -v26, v42, v37
	v_fma_f32 v38, -v27, v43, v38
	ds_read_b128 v[40:43], v129 offset:58736
	s_waitcnt lgkmcnt(0)
	v_fma_f32 v34, -v28, v40, v34
	v_fma_f32 v40, -v29, v41, v36
	v_fma_f32 v41, -v30, v42, v37
	ds_read_b64 v[36:37], v129 offset:58752
	v_fma_f32 v38, -v31, v43, v38
	s_waitcnt lgkmcnt(0)
	v_fma_f32 v34, -v32, v36, v34
	v_fma_f32 v36, -v33, v37, v40
	v_add_f32_e32 v34, v34, v36
	v_add_f32_e32 v36, v41, v38
	v_add_f32_e32 v34, v36, v34
	v_add_u32_e32 v36, 0x2200, v69
	ds_read2_b32 v[48:49], v36 offset0:99 offset1:164
	ds_read_b128 v[36:39], v129 offset:58880
	s_waitcnt lgkmcnt(0)
	v_mul_f32_e32 v36, v0, v36
	v_fma_f32 v35, v48, v35, -v36
	v_fma_f32 v40, -v1, v37, 0
	v_fma_f32 v41, -v2, v38, 0
	v_fma_f32 v42, -v3, v39, 0
	ds_read_b128 v[36:39], v129 offset:58896
	v_fma_f32 v48, -v2, v46, 0
	s_waitcnt lgkmcnt(0)
	v_fma_f32 v35, -v4, v36, v35
	v_fma_f32 v40, -v5, v37, v40
	v_fma_f32 v41, -v6, v38, v41
	v_fma_f32 v42, -v7, v39, v42
	ds_read_b128 v[36:39], v129 offset:58912
	ds_read_b128 v[108:111], v129 offset:58928
	ds_read_b128 v[104:107], v129 offset:58944
	ds_read_b128 v[100:103], v129 offset:58960
	s_waitcnt lgkmcnt(3)
	v_fma_f32 v35, -v8, v36, v35
	v_fma_f32 v40, -v9, v37, v40
	v_fma_f32 v41, -v10, v38, v41
	v_fma_f32 v42, -v11, v39, v42
	ds_read_b128 v[36:39], v129 offset:58976
	s_waitcnt lgkmcnt(3)
	v_fma_f32 v35, -v12, v108, v35
	v_fma_f32 v40, -v13, v109, v40
	v_fma_f32 v41, -v14, v110, v41
	v_fma_f32 v42, -v15, v111, v42
	s_waitcnt lgkmcnt(2)
	v_fma_f32 v35, -v16, v104, v35
	v_fma_f32 v40, -v17, v105, v40
	v_fma_f32 v41, -v18, v106, v41
	v_fma_f32 v42, -v19, v107, v42
	s_waitcnt lgkmcnt(1)
	v_fma_f32 v35, -v20, v100, v35
	v_fma_f32 v40, -v21, v101, v40
	v_fma_f32 v41, -v22, v102, v41
	v_fma_f32 v42, -v23, v103, v42
	s_waitcnt lgkmcnt(0)
	v_fma_f32 v35, -v24, v36, v35
	v_fma_f32 v40, -v25, v37, v40
	v_fma_f32 v41, -v26, v38, v41
	v_fma_f32 v42, -v27, v39, v42
	ds_read_b128 v[36:39], v129 offset:58992
	s_waitcnt lgkmcnt(0)
	v_fma_f32 v35, -v28, v36, v35
	v_fma_f32 v40, -v29, v37, v40
	v_fma_f32 v41, -v30, v38, v41
	ds_read_b96 v[36:38], v129 offset:59008
	v_fma_f32 v39, -v31, v39, v42
	s_waitcnt lgkmcnt(0)
	v_fma_f32 v35, -v32, v36, v35
	v_fma_f32 v36, -v33, v37, v40
	v_fma_f32 v37, -v34, v38, v41
	v_add_f32_e32 v35, v35, v36
	v_add_f32_e32 v36, v39, v37
	v_add_f32_e32 v35, v35, v36
	v_mov_b32_e32 v36, 0x10490
	v_mov_b32_e32 v40, 0x10690
	ds_read_b128 v[36:39], v36
	ds_read_b128 v[40:43], v40
	s_waitcnt lgkmcnt(0)
	v_cndmask_b32_e64 v36, v40, v36, s[44:45]
	v_mul_f32_e32 v40, v0, v44
	v_fma_f32 v36, v49, v36, -v40
	v_fma_f32 v40, -v1, v45, 0
	v_fma_f32 v49, -v3, v47, 0
	ds_read_b128 v[44:47], v129 offset:59152
	v_cndmask_b32_e64 v37, v41, v37, s[44:45]
	v_cndmask_b32_e64 v38, v42, v38, s[44:45]
	v_cndmask_b32_e64 v39, v43, v39, s[44:45]
	s_waitcnt lgkmcnt(0)
	v_fma_f32 v36, -v4, v44, v36
	v_fma_f32 v40, -v5, v45, v40
	v_fma_f32 v48, -v6, v46, v48
	v_fma_f32 v49, -v7, v47, v49
	ds_read_b128 v[100:103], v129 offset:59168
	ds_read_b128 v[44:47], v129 offset:59184
	ds_read_b128 v[108:111], v129 offset:59200
	ds_read_b128 v[104:107], v129 offset:59216
	s_waitcnt lgkmcnt(3)
	v_fma_f32 v36, -v8, v100, v36
	v_fma_f32 v40, -v9, v101, v40
	v_fma_f32 v48, -v10, v102, v48
	v_fma_f32 v49, -v11, v103, v49
	ds_read_b128 v[100:103], v129 offset:59232
	s_waitcnt lgkmcnt(3)
	v_fma_f32 v36, -v12, v44, v36
	v_fma_f32 v40, -v13, v45, v40
	v_fma_f32 v48, -v14, v46, v48
	v_fma_f32 v49, -v15, v47, v49
	ds_read_b128 v[44:47], v129 offset:59248
	s_waitcnt lgkmcnt(3)
	v_fma_f32 v36, -v16, v108, v36
	v_fma_f32 v40, -v17, v109, v40
	v_fma_f32 v48, -v18, v110, v48
	v_fma_f32 v49, -v19, v111, v49
	s_waitcnt lgkmcnt(2)
	v_fma_f32 v36, -v20, v104, v36
	v_fma_f32 v40, -v21, v105, v40
	v_fma_f32 v48, -v22, v106, v48
	v_fma_f32 v49, -v23, v107, v49
	s_waitcnt lgkmcnt(1)
	v_fma_f32 v36, -v24, v100, v36
	v_fma_f32 v40, -v25, v101, v40
	v_fma_f32 v48, -v26, v102, v48
	v_fma_f32 v49, -v27, v103, v49
	s_waitcnt lgkmcnt(0)
	v_fma_f32 v36, -v28, v44, v36
	v_fma_f32 v40, -v29, v45, v40
	v_fma_f32 v48, -v30, v46, v48
	v_fma_f32 v49, -v31, v47, v49
	ds_read_b128 v[44:47], v129 offset:59264
	s_waitcnt lgkmcnt(0)
	v_fma_f32 v36, -v32, v44, v36
	v_fma_f32 v40, -v33, v45, v40
	v_fma_f32 v44, -v34, v46, v48
	v_fma_f32 v45, -v35, v47, v49
	v_add_f32_e32 v36, v36, v40
	v_add_f32_e32 v40, v44, v45
	v_add_f32_e32 v36, v36, v40
	v_add_u32_e32 v40, 0x2400, v69
	ds_read_b128 v[44:47], v129 offset:59392
	ds_read2_b32 v[48:49], v40 offset0:101 offset1:166
	s_waitcnt lgkmcnt(1)
	v_mul_f32_e32 v40, v0, v44
	s_waitcnt lgkmcnt(0)
	v_fma_f32 v37, v48, v37, -v40
	v_fma_f32 v40, -v1, v45, 0
	v_fma_f32 v41, -v2, v46, 0
	v_fma_f32 v48, -v3, v47, 0
	ds_read_b128 v[104:107], v129 offset:59408
	ds_read_b128 v[100:103], v129 offset:59424
	ds_read_b128 v[44:47], v129 offset:59440
	ds_read_b128 v[108:111], v129 offset:59456
	s_waitcnt lgkmcnt(3)
	v_fma_f32 v37, -v4, v104, v37
	v_fma_f32 v40, -v5, v105, v40
	v_fma_f32 v41, -v6, v106, v41
	v_fma_f32 v48, -v7, v107, v48
	ds_read_b128 v[104:107], v129 offset:59472
	s_waitcnt lgkmcnt(3)
	v_fma_f32 v37, -v8, v100, v37
	v_fma_f32 v40, -v9, v101, v40
	v_fma_f32 v41, -v10, v102, v41
	v_fma_f32 v48, -v11, v103, v48
	ds_read_b128 v[100:103], v129 offset:59488
	s_waitcnt lgkmcnt(3)
	v_fma_f32 v37, -v12, v44, v37
	v_fma_f32 v40, -v13, v45, v40
	v_fma_f32 v41, -v14, v46, v41
	v_fma_f32 v48, -v15, v47, v48
	ds_read_b128 v[44:47], v129 offset:59504
	s_waitcnt lgkmcnt(3)
	v_fma_f32 v37, -v16, v108, v37
	v_fma_f32 v40, -v17, v109, v40
	v_fma_f32 v41, -v18, v110, v41
	v_fma_f32 v48, -v19, v111, v48
	s_waitcnt lgkmcnt(2)
	v_fma_f32 v37, -v20, v104, v37
	v_fma_f32 v40, -v21, v105, v40
	v_fma_f32 v41, -v22, v106, v41
	v_fma_f32 v48, -v23, v107, v48
	s_waitcnt lgkmcnt(1)
	v_fma_f32 v37, -v24, v100, v37
	v_fma_f32 v40, -v25, v101, v40
	v_fma_f32 v41, -v26, v102, v41
	v_fma_f32 v48, -v27, v103, v48
	s_waitcnt lgkmcnt(0)
	v_fma_f32 v37, -v28, v44, v37
	v_fma_f32 v40, -v29, v45, v40
	v_fma_f32 v41, -v30, v46, v41
	v_fma_f32 v48, -v31, v47, v48
	ds_read_b128 v[44:47], v129 offset:59520
	s_waitcnt lgkmcnt(0)
	v_fma_f32 v40, -v33, v45, v40
	ds_read_b32 v45, v129 offset:59536
	v_fma_f32 v37, -v32, v44, v37
	v_fma_f32 v41, -v34, v46, v41
	v_fma_f32 v44, -v35, v47, v48
	s_waitcnt lgkmcnt(0)
	v_fma_f32 v37, -v36, v45, v37
	v_add_f32_e32 v37, v40, v37
	v_add_f32_e32 v40, v41, v44
	ds_read_b128 v[44:47], v129 offset:59648
	v_add_f32_e32 v37, v40, v37
	s_waitcnt lgkmcnt(0)
	v_mul_f32_e32 v40, v0, v44
	v_fma_f32 v38, v49, v38, -v40
	v_fma_f32 v40, -v1, v45, 0
	v_fma_f32 v41, -v2, v46, 0
	v_fma_f32 v42, -v3, v47, 0
	ds_read_b128 v[44:47], v129 offset:59664
	ds_read_b128 v[48:51], v129 offset:60160
	s_waitcnt lgkmcnt(1)
	v_fma_f32 v38, -v4, v44, v38
	v_fma_f32 v40, -v5, v45, v40
	v_fma_f32 v41, -v6, v46, v41
	v_fma_f32 v42, -v7, v47, v42
	ds_read_b128 v[100:103], v129 offset:59680
	ds_read_b128 v[44:47], v129 offset:59696
	ds_read_b128 v[108:111], v129 offset:59712
	ds_read_b128 v[104:107], v129 offset:59728
	s_waitcnt lgkmcnt(3)
	v_fma_f32 v38, -v8, v100, v38
	v_fma_f32 v40, -v9, v101, v40
	v_fma_f32 v41, -v10, v102, v41
	v_fma_f32 v42, -v11, v103, v42
	ds_read_b128 v[100:103], v129 offset:59744
	s_waitcnt lgkmcnt(3)
	v_fma_f32 v38, -v12, v44, v38
	v_fma_f32 v40, -v13, v45, v40
	v_fma_f32 v41, -v14, v46, v41
	v_fma_f32 v42, -v15, v47, v42
	ds_read_b128 v[44:47], v129 offset:59760
	s_waitcnt lgkmcnt(3)
	v_fma_f32 v38, -v16, v108, v38
	v_fma_f32 v40, -v17, v109, v40
	v_fma_f32 v41, -v18, v110, v41
	v_fma_f32 v42, -v19, v111, v42
	s_waitcnt lgkmcnt(2)
	v_fma_f32 v38, -v20, v104, v38
	v_fma_f32 v40, -v21, v105, v40
	v_fma_f32 v41, -v22, v106, v41
	v_fma_f32 v42, -v23, v107, v42
	s_waitcnt lgkmcnt(1)
	v_fma_f32 v38, -v24, v100, v38
	v_fma_f32 v40, -v25, v101, v40
	v_fma_f32 v41, -v26, v102, v41
	v_fma_f32 v42, -v27, v103, v42
	s_waitcnt lgkmcnt(0)
	v_fma_f32 v38, -v28, v44, v38
	v_fma_f32 v40, -v29, v45, v40
	v_fma_f32 v41, -v30, v46, v41
	v_fma_f32 v42, -v31, v47, v42
	ds_read_b128 v[44:47], v129 offset:59776
	s_waitcnt lgkmcnt(0)
	v_fma_f32 v38, -v32, v44, v38
	v_fma_f32 v44, -v33, v45, v40
	v_fma_f32 v45, -v34, v46, v41
	ds_read_b64 v[40:41], v129 offset:59792
	v_fma_f32 v42, -v35, v47, v42
	s_waitcnt lgkmcnt(0)
	v_fma_f32 v38, -v36, v40, v38
	v_fma_f32 v40, -v37, v41, v44
	v_add_f32_e32 v38, v38, v40
	v_add_f32_e32 v40, v45, v42
	v_add_f32_e32 v38, v40, v38
	v_add_u32_e32 v40, 0x2600, v69
	ds_read2_b32 v[52:53], v40 offset0:103 offset1:168
	ds_read_b128 v[40:43], v129 offset:59904
	s_waitcnt lgkmcnt(0)
	v_mul_f32_e32 v40, v0, v40
	v_fma_f32 v39, v52, v39, -v40
	v_fma_f32 v44, -v1, v41, 0
	v_fma_f32 v45, -v2, v42, 0
	v_fma_f32 v46, -v3, v43, 0
	ds_read_b128 v[40:43], v129 offset:59920
	v_fma_f32 v52, -v2, v50, 0
	s_waitcnt lgkmcnt(0)
	v_fma_f32 v39, -v4, v40, v39
	v_fma_f32 v44, -v5, v41, v44
	v_fma_f32 v45, -v6, v42, v45
	v_fma_f32 v46, -v7, v43, v46
	ds_read_b128 v[100:103], v129 offset:59936
	ds_read_b128 v[40:43], v129 offset:59952
	ds_read_b128 v[108:111], v129 offset:59968
	ds_read_b128 v[104:107], v129 offset:59984
	s_waitcnt lgkmcnt(3)
	v_fma_f32 v39, -v8, v100, v39
	v_fma_f32 v44, -v9, v101, v44
	v_fma_f32 v45, -v10, v102, v45
	v_fma_f32 v46, -v11, v103, v46
	ds_read_b128 v[100:103], v129 offset:60000
	s_waitcnt lgkmcnt(3)
	v_fma_f32 v39, -v12, v40, v39
	v_fma_f32 v44, -v13, v41, v44
	v_fma_f32 v45, -v14, v42, v45
	v_fma_f32 v46, -v15, v43, v46
	ds_read_b128 v[40:43], v129 offset:60016
	s_waitcnt lgkmcnt(3)
	v_fma_f32 v39, -v16, v108, v39
	v_fma_f32 v44, -v17, v109, v44
	v_fma_f32 v45, -v18, v110, v45
	v_fma_f32 v46, -v19, v111, v46
	s_waitcnt lgkmcnt(2)
	v_fma_f32 v39, -v20, v104, v39
	v_fma_f32 v44, -v21, v105, v44
	v_fma_f32 v45, -v22, v106, v45
	v_fma_f32 v46, -v23, v107, v46
	s_waitcnt lgkmcnt(1)
	v_fma_f32 v39, -v24, v100, v39
	v_fma_f32 v44, -v25, v101, v44
	v_fma_f32 v45, -v26, v102, v45
	v_fma_f32 v46, -v27, v103, v46
	s_waitcnt lgkmcnt(0)
	v_fma_f32 v39, -v28, v40, v39
	v_fma_f32 v44, -v29, v41, v44
	v_fma_f32 v45, -v30, v42, v45
	v_fma_f32 v46, -v31, v43, v46
	ds_read_b128 v[40:43], v129 offset:60032
	s_waitcnt lgkmcnt(0)
	v_fma_f32 v39, -v32, v40, v39
	v_fma_f32 v44, -v33, v41, v44
	v_fma_f32 v45, -v34, v42, v45
	ds_read_b96 v[40:42], v129 offset:60048
	v_fma_f32 v43, -v35, v43, v46
	s_waitcnt lgkmcnt(0)
	v_fma_f32 v39, -v36, v40, v39
	v_fma_f32 v40, -v37, v41, v44
	v_fma_f32 v41, -v38, v42, v45
	v_add_f32_e32 v39, v39, v40
	v_add_f32_e32 v40, v43, v41
	v_add_f32_e32 v39, v39, v40
	v_mov_b32_e32 v40, 0x104a0
	v_mov_b32_e32 v44, 0x106a0
	ds_read_b128 v[40:43], v40
	ds_read_b128 v[44:47], v44
	s_waitcnt lgkmcnt(0)
	v_cndmask_b32_e64 v40, v44, v40, s[44:45]
	v_mul_f32_e32 v44, v0, v48
	v_fma_f32 v40, v53, v40, -v44
	v_fma_f32 v44, -v1, v49, 0
	v_fma_f32 v53, -v3, v51, 0
	ds_read_b128 v[48:51], v129 offset:60176
	v_cndmask_b32_e64 v41, v45, v41, s[44:45]
	v_cndmask_b32_e64 v42, v46, v42, s[44:45]
	v_cndmask_b32_e64 v43, v47, v43, s[44:45]
	s_waitcnt lgkmcnt(0)
	v_fma_f32 v40, -v4, v48, v40
	v_fma_f32 v44, -v5, v49, v44
	v_fma_f32 v52, -v6, v50, v52
	v_fma_f32 v53, -v7, v51, v53
	ds_read_b128 v[104:107], v129 offset:60192
	ds_read_b128 v[100:103], v129 offset:60208
	ds_read_b128 v[48:51], v129 offset:60224
	ds_read_b128 v[108:111], v129 offset:60240
	s_waitcnt lgkmcnt(3)
	v_fma_f32 v40, -v8, v104, v40
	v_fma_f32 v44, -v9, v105, v44
	v_fma_f32 v52, -v10, v106, v52
	v_fma_f32 v53, -v11, v107, v53
	ds_read_b128 v[104:107], v129 offset:60256
	s_waitcnt lgkmcnt(3)
	v_fma_f32 v40, -v12, v100, v40
	v_fma_f32 v44, -v13, v101, v44
	v_fma_f32 v52, -v14, v102, v52
	v_fma_f32 v53, -v15, v103, v53
	ds_read_b128 v[100:103], v129 offset:60272
	s_waitcnt lgkmcnt(3)
	v_fma_f32 v40, -v16, v48, v40
	v_fma_f32 v44, -v17, v49, v44
	v_fma_f32 v52, -v18, v50, v52
	v_fma_f32 v53, -v19, v51, v53
	ds_read_b128 v[48:51], v129 offset:60288
	s_waitcnt lgkmcnt(3)
	v_fma_f32 v40, -v20, v108, v40
	v_fma_f32 v44, -v21, v109, v44
	v_fma_f32 v52, -v22, v110, v52
	v_fma_f32 v53, -v23, v111, v53
	s_waitcnt lgkmcnt(2)
	v_fma_f32 v40, -v24, v104, v40
	v_fma_f32 v44, -v25, v105, v44
	v_fma_f32 v52, -v26, v106, v52
	v_fma_f32 v53, -v27, v107, v53
	s_waitcnt lgkmcnt(1)
	v_fma_f32 v40, -v28, v100, v40
	v_fma_f32 v44, -v29, v101, v44
	v_fma_f32 v52, -v30, v102, v52
	v_fma_f32 v53, -v31, v103, v53
	s_waitcnt lgkmcnt(0)
	v_fma_f32 v40, -v32, v48, v40
	v_fma_f32 v44, -v33, v49, v44
	v_fma_f32 v52, -v34, v50, v52
	v_fma_f32 v53, -v35, v51, v53
	ds_read_b128 v[48:51], v129 offset:60304
	s_waitcnt lgkmcnt(0)
	v_fma_f32 v40, -v36, v48, v40
	v_fma_f32 v44, -v37, v49, v44
	v_fma_f32 v48, -v38, v50, v52
	v_fma_f32 v49, -v39, v51, v53
	v_add_f32_e32 v40, v40, v44
	v_add_f32_e32 v44, v48, v49
	v_add_f32_e32 v40, v40, v44
	v_add_u32_e32 v44, 0x2800, v69
	ds_read_b128 v[48:51], v129 offset:60416
	ds_read2_b32 v[52:53], v44 offset0:105 offset1:170
	s_waitcnt lgkmcnt(1)
	v_mul_f32_e32 v44, v0, v48
	s_waitcnt lgkmcnt(0)
	v_fma_f32 v41, v52, v41, -v44
	v_fma_f32 v44, -v1, v49, 0
	v_fma_f32 v45, -v2, v50, 0
	v_fma_f32 v52, -v3, v51, 0
	ds_read_b128 v[108:111], v129 offset:60432
	ds_read_b128 v[104:107], v129 offset:60448
	ds_read_b128 v[100:103], v129 offset:60464
	ds_read_b128 v[48:51], v129 offset:60480
	s_waitcnt lgkmcnt(3)
	v_fma_f32 v41, -v4, v108, v41
	v_fma_f32 v44, -v5, v109, v44
	v_fma_f32 v45, -v6, v110, v45
	v_fma_f32 v52, -v7, v111, v52
	ds_read_b128 v[108:111], v129 offset:60496
	s_waitcnt lgkmcnt(3)
	v_fma_f32 v41, -v8, v104, v41
	v_fma_f32 v44, -v9, v105, v44
	v_fma_f32 v45, -v10, v106, v45
	v_fma_f32 v52, -v11, v107, v52
	ds_read_b128 v[104:107], v129 offset:60512
	s_waitcnt lgkmcnt(3)
	v_fma_f32 v41, -v12, v100, v41
	v_fma_f32 v44, -v13, v101, v44
	v_fma_f32 v45, -v14, v102, v45
	v_fma_f32 v52, -v15, v103, v52
	ds_read_b128 v[100:103], v129 offset:60528
	s_waitcnt lgkmcnt(3)
	v_fma_f32 v41, -v16, v48, v41
	v_fma_f32 v44, -v17, v49, v44
	v_fma_f32 v45, -v18, v50, v45
	v_fma_f32 v52, -v19, v51, v52
	ds_read_b128 v[48:51], v129 offset:60544
	s_waitcnt lgkmcnt(3)
	v_fma_f32 v41, -v20, v108, v41
	v_fma_f32 v44, -v21, v109, v44
	v_fma_f32 v45, -v22, v110, v45
	v_fma_f32 v52, -v23, v111, v52
	s_waitcnt lgkmcnt(2)
	v_fma_f32 v41, -v24, v104, v41
	v_fma_f32 v44, -v25, v105, v44
	v_fma_f32 v45, -v26, v106, v45
	v_fma_f32 v52, -v27, v107, v52
	s_waitcnt lgkmcnt(1)
	v_fma_f32 v41, -v28, v100, v41
	v_fma_f32 v44, -v29, v101, v44
	v_fma_f32 v45, -v30, v102, v45
	v_fma_f32 v52, -v31, v103, v52
	s_waitcnt lgkmcnt(0)
	v_fma_f32 v41, -v32, v48, v41
	v_fma_f32 v44, -v33, v49, v44
	v_fma_f32 v45, -v34, v50, v45
	v_fma_f32 v52, -v35, v51, v52
	ds_read_b128 v[48:51], v129 offset:60560
	s_waitcnt lgkmcnt(0)
	v_fma_f32 v44, -v37, v49, v44
	ds_read_b32 v49, v129 offset:60576
	v_fma_f32 v41, -v36, v48, v41
	v_fma_f32 v45, -v38, v50, v45
	v_fma_f32 v48, -v39, v51, v52
	s_waitcnt lgkmcnt(0)
	v_fma_f32 v41, -v40, v49, v41
	v_add_f32_e32 v41, v44, v41
	v_add_f32_e32 v44, v45, v48
	ds_read_b128 v[48:51], v129 offset:60672
	v_add_f32_e32 v41, v44, v41
	s_waitcnt lgkmcnt(0)
	v_mul_f32_e32 v44, v0, v48
	v_fma_f32 v42, v53, v42, -v44
	v_fma_f32 v44, -v1, v49, 0
	v_fma_f32 v45, -v2, v50, 0
	v_fma_f32 v46, -v3, v51, 0
	ds_read_b128 v[48:51], v129 offset:60688
	ds_read_b128 v[52:55], v129 offset:61184
	s_waitcnt lgkmcnt(1)
	v_fma_f32 v42, -v4, v48, v42
	v_fma_f32 v44, -v5, v49, v44
	v_fma_f32 v45, -v6, v50, v45
	v_fma_f32 v46, -v7, v51, v46
	ds_read_b128 v[104:107], v129 offset:60704
	ds_read_b128 v[100:103], v129 offset:60720
	ds_read_b128 v[48:51], v129 offset:60736
	ds_read_b128 v[108:111], v129 offset:60752
	s_waitcnt lgkmcnt(3)
	v_fma_f32 v42, -v8, v104, v42
	v_fma_f32 v44, -v9, v105, v44
	v_fma_f32 v45, -v10, v106, v45
	v_fma_f32 v46, -v11, v107, v46
	ds_read_b128 v[104:107], v129 offset:60768
	s_waitcnt lgkmcnt(3)
	v_fma_f32 v42, -v12, v100, v42
	v_fma_f32 v44, -v13, v101, v44
	v_fma_f32 v45, -v14, v102, v45
	v_fma_f32 v46, -v15, v103, v46
	ds_read_b128 v[100:103], v129 offset:60784
	s_waitcnt lgkmcnt(3)
	v_fma_f32 v42, -v16, v48, v42
	v_fma_f32 v44, -v17, v49, v44
	v_fma_f32 v45, -v18, v50, v45
	v_fma_f32 v46, -v19, v51, v46
	ds_read_b128 v[48:51], v129 offset:60800
	s_waitcnt lgkmcnt(3)
	v_fma_f32 v42, -v20, v108, v42
	v_fma_f32 v44, -v21, v109, v44
	v_fma_f32 v45, -v22, v110, v45
	v_fma_f32 v46, -v23, v111, v46
	s_waitcnt lgkmcnt(2)
	v_fma_f32 v42, -v24, v104, v42
	v_fma_f32 v44, -v25, v105, v44
	v_fma_f32 v45, -v26, v106, v45
	v_fma_f32 v46, -v27, v107, v46
	s_waitcnt lgkmcnt(1)
	v_fma_f32 v42, -v28, v100, v42
	v_fma_f32 v44, -v29, v101, v44
	v_fma_f32 v45, -v30, v102, v45
	v_fma_f32 v46, -v31, v103, v46
	s_waitcnt lgkmcnt(0)
	v_fma_f32 v42, -v32, v48, v42
	v_fma_f32 v44, -v33, v49, v44
	v_fma_f32 v45, -v34, v50, v45
	v_fma_f32 v46, -v35, v51, v46
	ds_read_b128 v[48:51], v129 offset:60816
	s_waitcnt lgkmcnt(0)
	v_fma_f32 v42, -v36, v48, v42
	v_fma_f32 v48, -v37, v49, v44
	v_fma_f32 v49, -v38, v50, v45
	ds_read_b64 v[44:45], v129 offset:60832
	v_fma_f32 v46, -v39, v51, v46
	s_waitcnt lgkmcnt(0)
	v_fma_f32 v42, -v40, v44, v42
	v_fma_f32 v44, -v41, v45, v48
	v_add_f32_e32 v42, v42, v44
	v_add_f32_e32 v44, v49, v46
	v_add_f32_e32 v42, v44, v42
	v_add_u32_e32 v44, 0x2a00, v69
	ds_read2_b32 v[56:57], v44 offset0:107 offset1:172
	ds_read_b128 v[44:47], v129 offset:60928
	s_waitcnt lgkmcnt(0)
	v_mul_f32_e32 v44, v0, v44
	v_fma_f32 v43, v56, v43, -v44
	v_fma_f32 v48, -v1, v45, 0
	v_fma_f32 v49, -v2, v46, 0
	v_fma_f32 v50, -v3, v47, 0
	ds_read_b128 v[44:47], v129 offset:60944
	v_fma_f32 v56, -v2, v54, 0
	s_waitcnt lgkmcnt(0)
	v_fma_f32 v43, -v4, v44, v43
	v_fma_f32 v48, -v5, v45, v48
	v_fma_f32 v49, -v6, v46, v49
	v_fma_f32 v50, -v7, v47, v50
	ds_read_b128 v[104:107], v129 offset:60960
	ds_read_b128 v[100:103], v129 offset:60976
	ds_read_b128 v[44:47], v129 offset:60992
	ds_read_b128 v[108:111], v129 offset:61008
	s_waitcnt lgkmcnt(3)
	v_fma_f32 v43, -v8, v104, v43
	v_fma_f32 v48, -v9, v105, v48
	v_fma_f32 v49, -v10, v106, v49
	v_fma_f32 v50, -v11, v107, v50
	ds_read_b128 v[104:107], v129 offset:61024
	s_waitcnt lgkmcnt(3)
	v_fma_f32 v43, -v12, v100, v43
	v_fma_f32 v48, -v13, v101, v48
	v_fma_f32 v49, -v14, v102, v49
	v_fma_f32 v50, -v15, v103, v50
	ds_read_b128 v[100:103], v129 offset:61040
	s_waitcnt lgkmcnt(3)
	v_fma_f32 v43, -v16, v44, v43
	v_fma_f32 v48, -v17, v45, v48
	v_fma_f32 v49, -v18, v46, v49
	v_fma_f32 v50, -v19, v47, v50
	ds_read_b128 v[44:47], v129 offset:61056
	s_waitcnt lgkmcnt(3)
	v_fma_f32 v43, -v20, v108, v43
	v_fma_f32 v48, -v21, v109, v48
	v_fma_f32 v49, -v22, v110, v49
	v_fma_f32 v50, -v23, v111, v50
	s_waitcnt lgkmcnt(2)
	v_fma_f32 v43, -v24, v104, v43
	v_fma_f32 v48, -v25, v105, v48
	v_fma_f32 v49, -v26, v106, v49
	v_fma_f32 v50, -v27, v107, v50
	s_waitcnt lgkmcnt(1)
	v_fma_f32 v43, -v28, v100, v43
	v_fma_f32 v48, -v29, v101, v48
	v_fma_f32 v49, -v30, v102, v49
	v_fma_f32 v50, -v31, v103, v50
	s_waitcnt lgkmcnt(0)
	v_fma_f32 v43, -v32, v44, v43
	v_fma_f32 v48, -v33, v45, v48
	v_fma_f32 v49, -v34, v46, v49
	v_fma_f32 v50, -v35, v47, v50
	ds_read_b128 v[44:47], v129 offset:61072
	s_waitcnt lgkmcnt(0)
	v_fma_f32 v43, -v36, v44, v43
	v_fma_f32 v48, -v37, v45, v48
	v_fma_f32 v49, -v38, v46, v49
	ds_read_b96 v[44:46], v129 offset:61088
	v_fma_f32 v47, -v39, v47, v50
	s_waitcnt lgkmcnt(0)
	v_fma_f32 v43, -v40, v44, v43
	v_fma_f32 v44, -v41, v45, v48
	v_fma_f32 v45, -v42, v46, v49
	v_add_f32_e32 v43, v43, v44
	v_add_f32_e32 v44, v47, v45
	v_add_f32_e32 v43, v43, v44
	v_mov_b32_e32 v44, 0x104b0
	v_mov_b32_e32 v48, 0x106b0
	ds_read_b128 v[44:47], v44
	ds_read_b128 v[48:51], v48
	s_waitcnt lgkmcnt(0)
	v_cndmask_b32_e64 v44, v48, v44, s[44:45]
	v_mul_f32_e32 v48, v0, v52
	v_fma_f32 v44, v57, v44, -v48
	v_fma_f32 v48, -v1, v53, 0
	v_fma_f32 v57, -v3, v55, 0
	ds_read_b128 v[52:55], v129 offset:61200
	v_cndmask_b32_e64 v45, v49, v45, s[44:45]
	v_cndmask_b32_e64 v46, v50, v46, s[44:45]
	v_cndmask_b32_e64 v47, v51, v47, s[44:45]
	s_waitcnt lgkmcnt(0)
	v_fma_f32 v44, -v4, v52, v44
	v_fma_f32 v48, -v5, v53, v48
	v_fma_f32 v56, -v6, v54, v56
	v_fma_f32 v57, -v7, v55, v57
	ds_read_b128 v[108:111], v129 offset:61216
	ds_read_b128 v[104:107], v129 offset:61232
	ds_read_b128 v[100:103], v129 offset:61248
	ds_read_b128 v[52:55], v129 offset:61264
	s_waitcnt lgkmcnt(3)
	v_fma_f32 v44, -v8, v108, v44
	v_fma_f32 v48, -v9, v109, v48
	v_fma_f32 v56, -v10, v110, v56
	v_fma_f32 v57, -v11, v111, v57
	ds_read_b128 v[108:111], v129 offset:61280
	s_waitcnt lgkmcnt(3)
	v_fma_f32 v44, -v12, v104, v44
	v_fma_f32 v48, -v13, v105, v48
	v_fma_f32 v56, -v14, v106, v56
	v_fma_f32 v57, -v15, v107, v57
	ds_read_b128 v[104:107], v129 offset:61296
	s_waitcnt lgkmcnt(3)
	v_fma_f32 v44, -v16, v100, v44
	v_fma_f32 v48, -v17, v101, v48
	v_fma_f32 v56, -v18, v102, v56
	v_fma_f32 v57, -v19, v103, v57
	ds_read_b128 v[100:103], v129 offset:61312
	s_waitcnt lgkmcnt(3)
	v_fma_f32 v44, -v20, v52, v44
	v_fma_f32 v48, -v21, v53, v48
	v_fma_f32 v56, -v22, v54, v56
	v_fma_f32 v57, -v23, v55, v57
	ds_read_b128 v[52:55], v129 offset:61328
	s_waitcnt lgkmcnt(3)
	v_fma_f32 v44, -v24, v108, v44
	v_fma_f32 v48, -v25, v109, v48
	v_fma_f32 v56, -v26, v110, v56
	v_fma_f32 v57, -v27, v111, v57
	s_waitcnt lgkmcnt(2)
	v_fma_f32 v44, -v28, v104, v44
	v_fma_f32 v48, -v29, v105, v48
	v_fma_f32 v56, -v30, v106, v56
	v_fma_f32 v57, -v31, v107, v57
	s_waitcnt lgkmcnt(1)
	v_fma_f32 v44, -v32, v100, v44
	v_fma_f32 v48, -v33, v101, v48
	v_fma_f32 v56, -v34, v102, v56
	v_fma_f32 v57, -v35, v103, v57
	s_waitcnt lgkmcnt(0)
	v_fma_f32 v44, -v36, v52, v44
	v_fma_f32 v48, -v37, v53, v48
	v_fma_f32 v56, -v38, v54, v56
	v_fma_f32 v57, -v39, v55, v57
	ds_read_b128 v[52:55], v129 offset:61344
	s_waitcnt lgkmcnt(0)
	v_fma_f32 v44, -v40, v52, v44
	v_fma_f32 v48, -v41, v53, v48
	v_fma_f32 v52, -v42, v54, v56
	v_fma_f32 v53, -v43, v55, v57
	v_add_f32_e32 v44, v44, v48
	v_add_f32_e32 v48, v52, v53
	v_add_f32_e32 v44, v44, v48
	v_add_u32_e32 v48, 0x2c00, v69
	ds_read_b128 v[52:55], v129 offset:61440
	ds_read2_b32 v[56:57], v48 offset0:109 offset1:174
	s_waitcnt lgkmcnt(1)
	v_mul_f32_e32 v48, v0, v52
	s_waitcnt lgkmcnt(0)
	v_fma_f32 v45, v56, v45, -v48
	v_fma_f32 v48, -v1, v53, 0
	v_fma_f32 v49, -v2, v54, 0
	v_fma_f32 v56, -v3, v55, 0
	ds_read_b128 v[52:55], v129 offset:61456
	ds_read_b128 v[108:111], v129 offset:61472
	ds_read_b128 v[104:107], v129 offset:61488
	ds_read_b128 v[100:103], v129 offset:61504
	s_waitcnt lgkmcnt(3)
	v_fma_f32 v45, -v4, v52, v45
	v_fma_f32 v48, -v5, v53, v48
	v_fma_f32 v49, -v6, v54, v49
	v_fma_f32 v56, -v7, v55, v56
	ds_read_b128 v[52:55], v129 offset:61520
	s_waitcnt lgkmcnt(3)
	v_fma_f32 v45, -v8, v108, v45
	v_fma_f32 v48, -v9, v109, v48
	v_fma_f32 v49, -v10, v110, v49
	v_fma_f32 v56, -v11, v111, v56
	ds_read_b128 v[108:111], v129 offset:61536
	s_waitcnt lgkmcnt(3)
	v_fma_f32 v45, -v12, v104, v45
	v_fma_f32 v48, -v13, v105, v48
	v_fma_f32 v49, -v14, v106, v49
	v_fma_f32 v56, -v15, v107, v56
	ds_read_b128 v[104:107], v129 offset:61552
	s_waitcnt lgkmcnt(3)
	v_fma_f32 v45, -v16, v100, v45
	v_fma_f32 v48, -v17, v101, v48
	v_fma_f32 v49, -v18, v102, v49
	v_fma_f32 v56, -v19, v103, v56
	ds_read_b128 v[100:103], v129 offset:61568
	s_waitcnt lgkmcnt(3)
	v_fma_f32 v45, -v20, v52, v45
	v_fma_f32 v48, -v21, v53, v48
	v_fma_f32 v49, -v22, v54, v49
	v_fma_f32 v56, -v23, v55, v56
	ds_read_b128 v[52:55], v129 offset:61584
	s_waitcnt lgkmcnt(3)
	v_fma_f32 v45, -v24, v108, v45
	v_fma_f32 v48, -v25, v109, v48
	v_fma_f32 v49, -v26, v110, v49
	v_fma_f32 v56, -v27, v111, v56
	s_waitcnt lgkmcnt(2)
	v_fma_f32 v45, -v28, v104, v45
	v_fma_f32 v48, -v29, v105, v48
	v_fma_f32 v49, -v30, v106, v49
	v_fma_f32 v56, -v31, v107, v56
	s_waitcnt lgkmcnt(1)
	v_fma_f32 v45, -v32, v100, v45
	v_fma_f32 v48, -v33, v101, v48
	v_fma_f32 v49, -v34, v102, v49
	v_fma_f32 v56, -v35, v103, v56
	s_waitcnt lgkmcnt(0)
	v_fma_f32 v45, -v36, v52, v45
	v_fma_f32 v48, -v37, v53, v48
	v_fma_f32 v49, -v38, v54, v49
	v_fma_f32 v56, -v39, v55, v56
	ds_read_b128 v[52:55], v129 offset:61600
	s_waitcnt lgkmcnt(0)
	v_fma_f32 v48, -v41, v53, v48
	ds_read_b32 v53, v129 offset:61616
	v_fma_f32 v45, -v40, v52, v45
	v_fma_f32 v49, -v42, v54, v49
	v_fma_f32 v52, -v43, v55, v56
	s_waitcnt lgkmcnt(0)
	v_fma_f32 v45, -v44, v53, v45
	v_add_f32_e32 v45, v48, v45
	v_add_f32_e32 v48, v49, v52
	ds_read_b128 v[52:55], v129 offset:61696
	v_add_f32_e32 v45, v48, v45
	s_waitcnt lgkmcnt(0)
	v_mul_f32_e32 v48, v0, v52
	v_fma_f32 v46, v57, v46, -v48
	v_fma_f32 v48, -v1, v53, 0
	v_fma_f32 v49, -v2, v54, 0
	v_fma_f32 v50, -v3, v55, 0
	ds_read_b128 v[52:55], v129 offset:61712
	ds_read_b128 v[56:59], v129 offset:62208
	s_waitcnt lgkmcnt(1)
	v_fma_f32 v46, -v4, v52, v46
	v_fma_f32 v48, -v5, v53, v48
	v_fma_f32 v49, -v6, v54, v49
	v_fma_f32 v50, -v7, v55, v50
	ds_read_b128 v[108:111], v129 offset:61728
	ds_read_b128 v[104:107], v129 offset:61744
	ds_read_b128 v[100:103], v129 offset:61760
	ds_read_b128 v[52:55], v129 offset:61776
	s_waitcnt lgkmcnt(3)
	v_fma_f32 v46, -v8, v108, v46
	v_fma_f32 v48, -v9, v109, v48
	v_fma_f32 v49, -v10, v110, v49
	v_fma_f32 v50, -v11, v111, v50
	ds_read_b128 v[108:111], v129 offset:61792
	s_waitcnt lgkmcnt(3)
	v_fma_f32 v46, -v12, v104, v46
	v_fma_f32 v48, -v13, v105, v48
	v_fma_f32 v49, -v14, v106, v49
	v_fma_f32 v50, -v15, v107, v50
	ds_read_b128 v[104:107], v129 offset:61808
	s_waitcnt lgkmcnt(3)
	v_fma_f32 v46, -v16, v100, v46
	v_fma_f32 v48, -v17, v101, v48
	v_fma_f32 v49, -v18, v102, v49
	v_fma_f32 v50, -v19, v103, v50
	ds_read_b128 v[100:103], v129 offset:61824
	s_waitcnt lgkmcnt(3)
	v_fma_f32 v46, -v20, v52, v46
	v_fma_f32 v48, -v21, v53, v48
	v_fma_f32 v49, -v22, v54, v49
	v_fma_f32 v50, -v23, v55, v50
	ds_read_b128 v[52:55], v129 offset:61840
	s_waitcnt lgkmcnt(3)
	v_fma_f32 v46, -v24, v108, v46
	v_fma_f32 v48, -v25, v109, v48
	v_fma_f32 v49, -v26, v110, v49
	v_fma_f32 v50, -v27, v111, v50
	s_waitcnt lgkmcnt(2)
	v_fma_f32 v46, -v28, v104, v46
	v_fma_f32 v48, -v29, v105, v48
	v_fma_f32 v49, -v30, v106, v49
	v_fma_f32 v50, -v31, v107, v50
	s_waitcnt lgkmcnt(1)
	v_fma_f32 v46, -v32, v100, v46
	v_fma_f32 v48, -v33, v101, v48
	v_fma_f32 v49, -v34, v102, v49
	v_fma_f32 v50, -v35, v103, v50
	s_waitcnt lgkmcnt(0)
	v_fma_f32 v46, -v36, v52, v46
	v_fma_f32 v48, -v37, v53, v48
	v_fma_f32 v49, -v38, v54, v49
	v_fma_f32 v50, -v39, v55, v50
	ds_read_b128 v[52:55], v129 offset:61856
	s_waitcnt lgkmcnt(0)
	v_fma_f32 v46, -v40, v52, v46
	v_fma_f32 v52, -v41, v53, v48
	v_fma_f32 v53, -v42, v54, v49
	ds_read_b64 v[48:49], v129 offset:61872
	v_fma_f32 v50, -v43, v55, v50
	s_waitcnt lgkmcnt(0)
	v_fma_f32 v46, -v44, v48, v46
	v_fma_f32 v48, -v45, v49, v52
	v_add_f32_e32 v46, v46, v48
	v_add_f32_e32 v48, v53, v50
	v_add_f32_e32 v46, v48, v46
	v_add_u32_e32 v48, 0x2e00, v69
	ds_read2_b32 v[60:61], v48 offset0:111 offset1:176
	ds_read_b128 v[48:51], v129 offset:61952
	s_waitcnt lgkmcnt(0)
	v_mul_f32_e32 v48, v0, v48
	v_fma_f32 v47, v60, v47, -v48
	v_fma_f32 v52, -v1, v49, 0
	v_fma_f32 v53, -v2, v50, 0
	v_fma_f32 v54, -v3, v51, 0
	ds_read_b128 v[48:51], v129 offset:61968
	v_fma_f32 v60, -v2, v58, 0
	s_waitcnt lgkmcnt(0)
	v_fma_f32 v47, -v4, v48, v47
	v_fma_f32 v52, -v5, v49, v52
	v_fma_f32 v53, -v6, v50, v53
	v_fma_f32 v54, -v7, v51, v54
	ds_read_b128 v[108:111], v129 offset:61984
	ds_read_b128 v[104:107], v129 offset:62000
	ds_read_b128 v[100:103], v129 offset:62016
	ds_read_b128 v[48:51], v129 offset:62032
	s_waitcnt lgkmcnt(3)
	v_fma_f32 v47, -v8, v108, v47
	v_fma_f32 v52, -v9, v109, v52
	v_fma_f32 v53, -v10, v110, v53
	v_fma_f32 v54, -v11, v111, v54
	ds_read_b128 v[108:111], v129 offset:62048
	s_waitcnt lgkmcnt(3)
	v_fma_f32 v47, -v12, v104, v47
	v_fma_f32 v52, -v13, v105, v52
	v_fma_f32 v53, -v14, v106, v53
	v_fma_f32 v54, -v15, v107, v54
	ds_read_b128 v[104:107], v129 offset:62064
	s_waitcnt lgkmcnt(3)
	v_fma_f32 v47, -v16, v100, v47
	v_fma_f32 v52, -v17, v101, v52
	v_fma_f32 v53, -v18, v102, v53
	v_fma_f32 v54, -v19, v103, v54
	ds_read_b128 v[100:103], v129 offset:62080
	s_waitcnt lgkmcnt(3)
	v_fma_f32 v47, -v20, v48, v47
	v_fma_f32 v52, -v21, v49, v52
	v_fma_f32 v53, -v22, v50, v53
	v_fma_f32 v54, -v23, v51, v54
	ds_read_b128 v[48:51], v129 offset:62096
	s_waitcnt lgkmcnt(3)
	v_fma_f32 v47, -v24, v108, v47
	v_fma_f32 v52, -v25, v109, v52
	v_fma_f32 v53, -v26, v110, v53
	v_fma_f32 v54, -v27, v111, v54
	s_waitcnt lgkmcnt(2)
	v_fma_f32 v47, -v28, v104, v47
	v_fma_f32 v52, -v29, v105, v52
	v_fma_f32 v53, -v30, v106, v53
	v_fma_f32 v54, -v31, v107, v54
	s_waitcnt lgkmcnt(1)
	v_fma_f32 v47, -v32, v100, v47
	v_fma_f32 v52, -v33, v101, v52
	v_fma_f32 v53, -v34, v102, v53
	v_fma_f32 v54, -v35, v103, v54
	s_waitcnt lgkmcnt(0)
	v_fma_f32 v47, -v36, v48, v47
	v_fma_f32 v52, -v37, v49, v52
	v_fma_f32 v53, -v38, v50, v53
	v_fma_f32 v54, -v39, v51, v54
	ds_read_b128 v[48:51], v129 offset:62112
	s_waitcnt lgkmcnt(0)
	v_fma_f32 v47, -v40, v48, v47
	v_fma_f32 v52, -v41, v49, v52
	v_fma_f32 v53, -v42, v50, v53
	ds_read_b96 v[48:50], v129 offset:62128
	v_fma_f32 v51, -v43, v51, v54
	s_waitcnt lgkmcnt(0)
	v_fma_f32 v47, -v44, v48, v47
	v_fma_f32 v48, -v45, v49, v52
	v_fma_f32 v49, -v46, v50, v53
	v_add_f32_e32 v47, v47, v48
	v_add_f32_e32 v48, v51, v49
	v_add_f32_e32 v47, v47, v48
	v_mov_b32_e32 v48, 0x104c0
	v_mov_b32_e32 v52, 0x106c0
	ds_read_b128 v[48:51], v48
	ds_read_b128 v[52:55], v52
	s_waitcnt lgkmcnt(0)
	v_cndmask_b32_e64 v48, v52, v48, s[44:45]
	v_mul_f32_e32 v52, v0, v56
	v_fma_f32 v48, v61, v48, -v52
	v_fma_f32 v52, -v1, v57, 0
	v_fma_f32 v61, -v3, v59, 0
	ds_read_b128 v[56:59], v129 offset:62224
	v_cndmask_b32_e64 v49, v53, v49, s[44:45]
	v_cndmask_b32_e64 v50, v54, v50, s[44:45]
	v_cndmask_b32_e64 v51, v55, v51, s[44:45]
	s_waitcnt lgkmcnt(0)
	v_fma_f32 v48, -v4, v56, v48
	v_fma_f32 v52, -v5, v57, v52
	v_fma_f32 v60, -v6, v58, v60
	v_fma_f32 v61, -v7, v59, v61
	ds_read_b128 v[56:59], v129 offset:62240
	ds_read_b128 v[108:111], v129 offset:62256
	ds_read_b128 v[104:107], v129 offset:62272
	ds_read_b128 v[100:103], v129 offset:62288
	s_waitcnt lgkmcnt(3)
	v_fma_f32 v48, -v8, v56, v48
	v_fma_f32 v52, -v9, v57, v52
	v_fma_f32 v60, -v10, v58, v60
	v_fma_f32 v61, -v11, v59, v61
	ds_read_b128 v[56:59], v129 offset:62304
	s_waitcnt lgkmcnt(3)
	v_fma_f32 v48, -v12, v108, v48
	v_fma_f32 v52, -v13, v109, v52
	v_fma_f32 v60, -v14, v110, v60
	v_fma_f32 v61, -v15, v111, v61
	ds_read_b128 v[108:111], v129 offset:62320
	s_waitcnt lgkmcnt(3)
	v_fma_f32 v48, -v16, v104, v48
	v_fma_f32 v52, -v17, v105, v52
	v_fma_f32 v60, -v18, v106, v60
	v_fma_f32 v61, -v19, v107, v61
	ds_read_b128 v[104:107], v129 offset:62336
	s_waitcnt lgkmcnt(3)
	v_fma_f32 v48, -v20, v100, v48
	v_fma_f32 v52, -v21, v101, v52
	v_fma_f32 v60, -v22, v102, v60
	v_fma_f32 v61, -v23, v103, v61
	ds_read_b128 v[100:103], v129 offset:62352
	s_waitcnt lgkmcnt(3)
	v_fma_f32 v48, -v24, v56, v48
	v_fma_f32 v52, -v25, v57, v52
	v_fma_f32 v60, -v26, v58, v60
	v_fma_f32 v61, -v27, v59, v61
	ds_read_b128 v[56:59], v129 offset:62368
	s_waitcnt lgkmcnt(3)
	v_fma_f32 v48, -v28, v108, v48
	v_fma_f32 v52, -v29, v109, v52
	v_fma_f32 v60, -v30, v110, v60
	v_fma_f32 v61, -v31, v111, v61
	s_waitcnt lgkmcnt(2)
	v_fma_f32 v48, -v32, v104, v48
	v_fma_f32 v52, -v33, v105, v52
	v_fma_f32 v60, -v34, v106, v60
	v_fma_f32 v61, -v35, v107, v61
	s_waitcnt lgkmcnt(1)
	v_fma_f32 v48, -v36, v100, v48
	v_fma_f32 v52, -v37, v101, v52
	v_fma_f32 v60, -v38, v102, v60
	v_fma_f32 v61, -v39, v103, v61
	s_waitcnt lgkmcnt(0)
	v_fma_f32 v48, -v40, v56, v48
	v_fma_f32 v52, -v41, v57, v52
	v_fma_f32 v60, -v42, v58, v60
	v_fma_f32 v61, -v43, v59, v61
	ds_read_b128 v[56:59], v129 offset:62384
	s_waitcnt lgkmcnt(0)
	v_fma_f32 v48, -v44, v56, v48
	v_fma_f32 v52, -v45, v57, v52
	v_fma_f32 v56, -v46, v58, v60
	v_fma_f32 v57, -v47, v59, v61
	v_add_f32_e32 v48, v48, v52
	v_add_f32_e32 v52, v56, v57
	v_add_f32_e32 v48, v48, v52
	v_add_u32_e32 v52, 0x3000, v69
	ds_read_b128 v[56:59], v129 offset:62464
	ds_read2_b32 v[60:61], v52 offset0:113 offset1:178
	s_waitcnt lgkmcnt(1)
	v_mul_f32_e32 v52, v0, v56
	s_waitcnt lgkmcnt(0)
	v_fma_f32 v49, v60, v49, -v52
	v_fma_f32 v52, -v1, v57, 0
	v_fma_f32 v53, -v2, v58, 0
	v_fma_f32 v60, -v3, v59, 0
	ds_read_b128 v[100:103], v129 offset:62480
	ds_read_b128 v[56:59], v129 offset:62496
	ds_read_b128 v[108:111], v129 offset:62512
	ds_read_b128 v[104:107], v129 offset:62528
	s_waitcnt lgkmcnt(3)
	v_fma_f32 v49, -v4, v100, v49
	v_fma_f32 v52, -v5, v101, v52
	v_fma_f32 v53, -v6, v102, v53
	v_fma_f32 v60, -v7, v103, v60
	ds_read_b128 v[100:103], v129 offset:62544
	s_waitcnt lgkmcnt(3)
	v_fma_f32 v49, -v8, v56, v49
	v_fma_f32 v52, -v9, v57, v52
	v_fma_f32 v53, -v10, v58, v53
	v_fma_f32 v60, -v11, v59, v60
	ds_read_b128 v[56:59], v129 offset:62560
	s_waitcnt lgkmcnt(3)
	v_fma_f32 v49, -v12, v108, v49
	v_fma_f32 v52, -v13, v109, v52
	v_fma_f32 v53, -v14, v110, v53
	v_fma_f32 v60, -v15, v111, v60
	ds_read_b128 v[108:111], v129 offset:62576
	s_waitcnt lgkmcnt(3)
	v_fma_f32 v49, -v16, v104, v49
	v_fma_f32 v52, -v17, v105, v52
	v_fma_f32 v53, -v18, v106, v53
	v_fma_f32 v60, -v19, v107, v60
	ds_read_b128 v[104:107], v129 offset:62592
	s_waitcnt lgkmcnt(3)
	v_fma_f32 v49, -v20, v100, v49
	v_fma_f32 v52, -v21, v101, v52
	v_fma_f32 v53, -v22, v102, v53
	v_fma_f32 v60, -v23, v103, v60
	ds_read_b128 v[100:103], v129 offset:62608
	s_waitcnt lgkmcnt(3)
	v_fma_f32 v49, -v24, v56, v49
	v_fma_f32 v52, -v25, v57, v52
	v_fma_f32 v53, -v26, v58, v53
	v_fma_f32 v60, -v27, v59, v60
	ds_read_b128 v[56:59], v129 offset:62624
	s_waitcnt lgkmcnt(3)
	v_fma_f32 v49, -v28, v108, v49
	v_fma_f32 v52, -v29, v109, v52
	v_fma_f32 v53, -v30, v110, v53
	v_fma_f32 v60, -v31, v111, v60
	s_waitcnt lgkmcnt(2)
	v_fma_f32 v49, -v32, v104, v49
	v_fma_f32 v52, -v33, v105, v52
	v_fma_f32 v53, -v34, v106, v53
	v_fma_f32 v60, -v35, v107, v60
	s_waitcnt lgkmcnt(1)
	v_fma_f32 v49, -v36, v100, v49
	v_fma_f32 v52, -v37, v101, v52
	v_fma_f32 v53, -v38, v102, v53
	v_fma_f32 v60, -v39, v103, v60
	s_waitcnt lgkmcnt(0)
	v_fma_f32 v49, -v40, v56, v49
	v_fma_f32 v52, -v41, v57, v52
	v_fma_f32 v53, -v42, v58, v53
	v_fma_f32 v60, -v43, v59, v60
	ds_read_b128 v[56:59], v129 offset:62640
	s_waitcnt lgkmcnt(0)
	v_fma_f32 v52, -v45, v57, v52
	ds_read_b32 v57, v129 offset:62656
	v_fma_f32 v49, -v44, v56, v49
	v_fma_f32 v53, -v46, v58, v53
	v_fma_f32 v56, -v47, v59, v60
	s_waitcnt lgkmcnt(0)
	v_fma_f32 v49, -v48, v57, v49
	v_add_f32_e32 v49, v52, v49
	v_add_f32_e32 v52, v53, v56
	ds_read_b128 v[56:59], v129 offset:62720
	v_add_f32_e32 v49, v52, v49
	s_waitcnt lgkmcnt(0)
	v_mul_f32_e32 v52, v0, v56
	v_fma_f32 v50, v61, v50, -v52
	v_fma_f32 v52, -v1, v57, 0
	v_fma_f32 v53, -v2, v58, 0
	v_fma_f32 v54, -v3, v59, 0
	ds_read_b128 v[56:59], v129 offset:62736
	ds_read_b128 v[60:63], v129 offset:63232
	s_waitcnt lgkmcnt(1)
	v_fma_f32 v50, -v4, v56, v50
	v_fma_f32 v52, -v5, v57, v52
	v_fma_f32 v53, -v6, v58, v53
	v_fma_f32 v54, -v7, v59, v54
	ds_read_b128 v[56:59], v129 offset:62752
	ds_read_b128 v[108:111], v129 offset:62768
	ds_read_b128 v[104:107], v129 offset:62784
	ds_read_b128 v[100:103], v129 offset:62800
	s_waitcnt lgkmcnt(3)
	v_fma_f32 v50, -v8, v56, v50
	v_fma_f32 v52, -v9, v57, v52
	v_fma_f32 v53, -v10, v58, v53
	v_fma_f32 v54, -v11, v59, v54
	ds_read_b128 v[56:59], v129 offset:62816
	s_waitcnt lgkmcnt(3)
	v_fma_f32 v50, -v12, v108, v50
	v_fma_f32 v52, -v13, v109, v52
	v_fma_f32 v53, -v14, v110, v53
	v_fma_f32 v54, -v15, v111, v54
	ds_read_b128 v[108:111], v129 offset:62832
	s_waitcnt lgkmcnt(3)
	v_fma_f32 v50, -v16, v104, v50
	v_fma_f32 v52, -v17, v105, v52
	v_fma_f32 v53, -v18, v106, v53
	v_fma_f32 v54, -v19, v107, v54
	ds_read_b128 v[104:107], v129 offset:62848
	s_waitcnt lgkmcnt(3)
	v_fma_f32 v50, -v20, v100, v50
	v_fma_f32 v52, -v21, v101, v52
	v_fma_f32 v53, -v22, v102, v53
	v_fma_f32 v54, -v23, v103, v54
	ds_read_b128 v[100:103], v129 offset:62864
	s_waitcnt lgkmcnt(3)
	v_fma_f32 v50, -v24, v56, v50
	v_fma_f32 v52, -v25, v57, v52
	v_fma_f32 v53, -v26, v58, v53
	v_fma_f32 v54, -v27, v59, v54
	ds_read_b128 v[56:59], v129 offset:62880
	s_waitcnt lgkmcnt(3)
	v_fma_f32 v50, -v28, v108, v50
	v_fma_f32 v52, -v29, v109, v52
	v_fma_f32 v53, -v30, v110, v53
	v_fma_f32 v54, -v31, v111, v54
	s_waitcnt lgkmcnt(2)
	v_fma_f32 v50, -v32, v104, v50
	v_fma_f32 v52, -v33, v105, v52
	v_fma_f32 v53, -v34, v106, v53
	v_fma_f32 v54, -v35, v107, v54
	s_waitcnt lgkmcnt(1)
	v_fma_f32 v50, -v36, v100, v50
	v_fma_f32 v52, -v37, v101, v52
	v_fma_f32 v53, -v38, v102, v53
	v_fma_f32 v54, -v39, v103, v54
	s_waitcnt lgkmcnt(0)
	v_fma_f32 v50, -v40, v56, v50
	v_fma_f32 v52, -v41, v57, v52
	v_fma_f32 v53, -v42, v58, v53
	v_fma_f32 v54, -v43, v59, v54
	ds_read_b128 v[56:59], v129 offset:62896
	s_waitcnt lgkmcnt(0)
	v_fma_f32 v50, -v44, v56, v50
	v_fma_f32 v56, -v45, v57, v52
	v_fma_f32 v57, -v46, v58, v53
	ds_read_b64 v[52:53], v129 offset:62912
	v_fma_f32 v54, -v47, v59, v54
	s_waitcnt lgkmcnt(0)
	v_fma_f32 v50, -v48, v52, v50
	v_fma_f32 v52, -v49, v53, v56
	v_add_f32_e32 v50, v50, v52
	v_add_f32_e32 v52, v57, v54
	v_add_f32_e32 v50, v52, v50
	v_add_u32_e32 v52, 0x3200, v69
	ds_read2_b32 v[64:65], v52 offset0:115 offset1:180
	ds_read_b128 v[52:55], v129 offset:62976
	s_waitcnt lgkmcnt(0)
	v_mul_f32_e32 v52, v0, v52
	v_fma_f32 v51, v64, v51, -v52
	v_fma_f32 v56, -v1, v53, 0
	v_fma_f32 v57, -v2, v54, 0
	v_fma_f32 v58, -v3, v55, 0
	ds_read_b128 v[52:55], v129 offset:62992
	v_fma_f32 v64, -v2, v62, 0
	s_waitcnt lgkmcnt(0)
	v_fma_f32 v51, -v4, v52, v51
	v_fma_f32 v56, -v5, v53, v56
	v_fma_f32 v57, -v6, v54, v57
	v_fma_f32 v58, -v7, v55, v58
	ds_read_b128 v[52:55], v129 offset:63008
	ds_read_b128 v[108:111], v129 offset:63024
	ds_read_b128 v[104:107], v129 offset:63040
	ds_read_b128 v[100:103], v129 offset:63056
	s_waitcnt lgkmcnt(3)
	v_fma_f32 v51, -v8, v52, v51
	v_fma_f32 v56, -v9, v53, v56
	v_fma_f32 v57, -v10, v54, v57
	v_fma_f32 v58, -v11, v55, v58
	ds_read_b128 v[52:55], v129 offset:63072
	s_waitcnt lgkmcnt(3)
	v_fma_f32 v51, -v12, v108, v51
	v_fma_f32 v56, -v13, v109, v56
	v_fma_f32 v57, -v14, v110, v57
	v_fma_f32 v58, -v15, v111, v58
	ds_read_b128 v[108:111], v129 offset:63088
	s_waitcnt lgkmcnt(3)
	v_fma_f32 v51, -v16, v104, v51
	v_fma_f32 v56, -v17, v105, v56
	v_fma_f32 v57, -v18, v106, v57
	v_fma_f32 v58, -v19, v107, v58
	ds_read_b128 v[104:107], v129 offset:63104
	s_waitcnt lgkmcnt(3)
	v_fma_f32 v51, -v20, v100, v51
	v_fma_f32 v56, -v21, v101, v56
	v_fma_f32 v57, -v22, v102, v57
	v_fma_f32 v58, -v23, v103, v58
	ds_read_b128 v[100:103], v129 offset:63120
	s_waitcnt lgkmcnt(3)
	v_fma_f32 v51, -v24, v52, v51
	v_fma_f32 v56, -v25, v53, v56
	v_fma_f32 v57, -v26, v54, v57
	v_fma_f32 v58, -v27, v55, v58
	ds_read_b128 v[52:55], v129 offset:63136
	s_waitcnt lgkmcnt(3)
	v_fma_f32 v51, -v28, v108, v51
	v_fma_f32 v56, -v29, v109, v56
	v_fma_f32 v57, -v30, v110, v57
	v_fma_f32 v58, -v31, v111, v58
	s_waitcnt lgkmcnt(2)
	v_fma_f32 v51, -v32, v104, v51
	v_fma_f32 v56, -v33, v105, v56
	v_fma_f32 v57, -v34, v106, v57
	v_fma_f32 v58, -v35, v107, v58
	s_waitcnt lgkmcnt(1)
	v_fma_f32 v51, -v36, v100, v51
	v_fma_f32 v56, -v37, v101, v56
	v_fma_f32 v57, -v38, v102, v57
	v_fma_f32 v58, -v39, v103, v58
	s_waitcnt lgkmcnt(0)
	v_fma_f32 v51, -v40, v52, v51
	v_fma_f32 v56, -v41, v53, v56
	v_fma_f32 v57, -v42, v54, v57
	v_fma_f32 v58, -v43, v55, v58
	ds_read_b128 v[52:55], v129 offset:63152
	s_waitcnt lgkmcnt(0)
	v_fma_f32 v51, -v44, v52, v51
	v_fma_f32 v56, -v45, v53, v56
	v_fma_f32 v57, -v46, v54, v57
	ds_read_b96 v[52:54], v129 offset:63168
	v_fma_f32 v55, -v47, v55, v58
	s_waitcnt lgkmcnt(0)
	v_fma_f32 v51, -v48, v52, v51
	v_fma_f32 v52, -v49, v53, v56
	v_fma_f32 v53, -v50, v54, v57
	v_add_f32_e32 v51, v51, v52
	v_add_f32_e32 v52, v55, v53
	v_add_f32_e32 v51, v51, v52
	v_mov_b32_e32 v52, 0x104d0
	v_mov_b32_e32 v56, 0x106d0
	ds_read_b128 v[52:55], v52
	ds_read_b128 v[56:59], v56
	s_waitcnt lgkmcnt(0)
	v_cndmask_b32_e64 v52, v56, v52, s[44:45]
	v_mul_f32_e32 v56, v0, v60
	v_fma_f32 v52, v65, v52, -v56
	v_fma_f32 v56, -v1, v61, 0
	v_fma_f32 v65, -v3, v63, 0
	ds_read_b128 v[60:63], v129 offset:63248
	v_cndmask_b32_e64 v53, v57, v53, s[44:45]
	v_cndmask_b32_e64 v54, v58, v54, s[44:45]
	v_cndmask_b32_e64 v55, v59, v55, s[44:45]
	s_waitcnt lgkmcnt(0)
	v_fma_f32 v52, -v4, v60, v52
	v_fma_f32 v56, -v5, v61, v56
	v_fma_f32 v64, -v6, v62, v64
	v_fma_f32 v65, -v7, v63, v65
	ds_read_b128 v[100:103], v129 offset:63264
	ds_read_b128 v[60:63], v129 offset:63280
	ds_read_b128 v[108:111], v129 offset:63296
	ds_read_b128 v[104:107], v129 offset:63312
	s_waitcnt lgkmcnt(3)
	v_fma_f32 v52, -v8, v100, v52
	v_fma_f32 v56, -v9, v101, v56
	v_fma_f32 v64, -v10, v102, v64
	v_fma_f32 v65, -v11, v103, v65
	ds_read_b128 v[100:103], v129 offset:63328
	s_waitcnt lgkmcnt(3)
	v_fma_f32 v52, -v12, v60, v52
	v_fma_f32 v56, -v13, v61, v56
	v_fma_f32 v64, -v14, v62, v64
	v_fma_f32 v65, -v15, v63, v65
	ds_read_b128 v[60:63], v129 offset:63344
	s_waitcnt lgkmcnt(3)
	v_fma_f32 v52, -v16, v108, v52
	v_fma_f32 v56, -v17, v109, v56
	v_fma_f32 v64, -v18, v110, v64
	v_fma_f32 v65, -v19, v111, v65
	ds_read_b128 v[108:111], v129 offset:63360
	s_waitcnt lgkmcnt(3)
	v_fma_f32 v52, -v20, v104, v52
	v_fma_f32 v56, -v21, v105, v56
	v_fma_f32 v64, -v22, v106, v64
	v_fma_f32 v65, -v23, v107, v65
	ds_read_b128 v[104:107], v129 offset:63376
	s_waitcnt lgkmcnt(3)
	v_fma_f32 v52, -v24, v100, v52
	v_fma_f32 v56, -v25, v101, v56
	v_fma_f32 v64, -v26, v102, v64
	v_fma_f32 v65, -v27, v103, v65
	ds_read_b128 v[100:103], v129 offset:63392
	s_waitcnt lgkmcnt(3)
	v_fma_f32 v52, -v28, v60, v52
	v_fma_f32 v56, -v29, v61, v56
	v_fma_f32 v64, -v30, v62, v64
	v_fma_f32 v65, -v31, v63, v65
	ds_read_b128 v[60:63], v129 offset:63408
	s_waitcnt lgkmcnt(3)
	v_fma_f32 v52, -v32, v108, v52
	v_fma_f32 v56, -v33, v109, v56
	v_fma_f32 v64, -v34, v110, v64
	v_fma_f32 v65, -v35, v111, v65
	s_waitcnt lgkmcnt(2)
	v_fma_f32 v52, -v36, v104, v52
	v_fma_f32 v56, -v37, v105, v56
	v_fma_f32 v64, -v38, v106, v64
	v_fma_f32 v65, -v39, v107, v65
	s_waitcnt lgkmcnt(1)
	v_fma_f32 v52, -v40, v100, v52
	v_fma_f32 v56, -v41, v101, v56
	v_fma_f32 v64, -v42, v102, v64
	v_fma_f32 v65, -v43, v103, v65
	s_waitcnt lgkmcnt(0)
	v_fma_f32 v52, -v44, v60, v52
	v_fma_f32 v56, -v45, v61, v56
	v_fma_f32 v64, -v46, v62, v64
	v_fma_f32 v65, -v47, v63, v65
	ds_read_b128 v[60:63], v129 offset:63424
	s_waitcnt lgkmcnt(0)
	v_fma_f32 v52, -v48, v60, v52
	v_fma_f32 v56, -v49, v61, v56
	v_fma_f32 v60, -v50, v62, v64
	v_fma_f32 v61, -v51, v63, v65
	v_add_f32_e32 v52, v52, v56
	v_add_f32_e32 v56, v60, v61
	v_add_f32_e32 v52, v52, v56
	v_add_u32_e32 v56, 0x3400, v69
	ds_read_b128 v[60:63], v129 offset:63488
	ds_read2_b32 v[64:65], v56 offset0:117 offset1:182
	s_waitcnt lgkmcnt(1)
	v_mul_f32_e32 v56, v0, v60
	s_waitcnt lgkmcnt(0)
	v_fma_f32 v53, v64, v53, -v56
	v_fma_f32 v56, -v1, v61, 0
	v_fma_f32 v57, -v2, v62, 0
	v_fma_f32 v64, -v3, v63, 0
	ds_read_b128 v[104:107], v129 offset:63504
	ds_read_b128 v[100:103], v129 offset:63520
	ds_read_b128 v[60:63], v129 offset:63536
	ds_read_b128 v[108:111], v129 offset:63552
	s_waitcnt lgkmcnt(3)
	v_fma_f32 v53, -v4, v104, v53
	v_fma_f32 v56, -v5, v105, v56
	v_fma_f32 v57, -v6, v106, v57
	v_fma_f32 v64, -v7, v107, v64
	ds_read_b128 v[104:107], v129 offset:63568
	s_waitcnt lgkmcnt(3)
	v_fma_f32 v53, -v8, v100, v53
	v_fma_f32 v56, -v9, v101, v56
	v_fma_f32 v57, -v10, v102, v57
	v_fma_f32 v64, -v11, v103, v64
	ds_read_b128 v[100:103], v129 offset:63584
	s_waitcnt lgkmcnt(3)
	v_fma_f32 v53, -v12, v60, v53
	v_fma_f32 v56, -v13, v61, v56
	v_fma_f32 v57, -v14, v62, v57
	v_fma_f32 v64, -v15, v63, v64
	ds_read_b128 v[60:63], v129 offset:63600
	s_waitcnt lgkmcnt(3)
	v_fma_f32 v53, -v16, v108, v53
	v_fma_f32 v56, -v17, v109, v56
	v_fma_f32 v57, -v18, v110, v57
	v_fma_f32 v64, -v19, v111, v64
	ds_read_b128 v[108:111], v129 offset:63616
	s_waitcnt lgkmcnt(3)
	v_fma_f32 v53, -v20, v104, v53
	v_fma_f32 v56, -v21, v105, v56
	v_fma_f32 v57, -v22, v106, v57
	v_fma_f32 v64, -v23, v107, v64
	ds_read_b128 v[104:107], v129 offset:63632
	s_waitcnt lgkmcnt(3)
	v_fma_f32 v53, -v24, v100, v53
	v_fma_f32 v56, -v25, v101, v56
	v_fma_f32 v57, -v26, v102, v57
	v_fma_f32 v64, -v27, v103, v64
	ds_read_b128 v[100:103], v129 offset:63648
	s_waitcnt lgkmcnt(3)
	v_fma_f32 v53, -v28, v60, v53
	v_fma_f32 v56, -v29, v61, v56
	v_fma_f32 v57, -v30, v62, v57
	v_fma_f32 v64, -v31, v63, v64
	ds_read_b128 v[60:63], v129 offset:63664
	s_waitcnt lgkmcnt(3)
	v_fma_f32 v53, -v32, v108, v53
	v_fma_f32 v56, -v33, v109, v56
	v_fma_f32 v57, -v34, v110, v57
	v_fma_f32 v64, -v35, v111, v64
	s_waitcnt lgkmcnt(2)
	v_fma_f32 v53, -v36, v104, v53
	v_fma_f32 v56, -v37, v105, v56
	v_fma_f32 v57, -v38, v106, v57
	v_fma_f32 v64, -v39, v107, v64
	s_waitcnt lgkmcnt(1)
	v_fma_f32 v53, -v40, v100, v53
	v_fma_f32 v56, -v41, v101, v56
	v_fma_f32 v57, -v42, v102, v57
	v_fma_f32 v64, -v43, v103, v64
	s_waitcnt lgkmcnt(0)
	v_fma_f32 v53, -v44, v60, v53
	v_fma_f32 v56, -v45, v61, v56
	v_fma_f32 v57, -v46, v62, v57
	v_fma_f32 v64, -v47, v63, v64
	ds_read_b128 v[60:63], v129 offset:63680
	s_waitcnt lgkmcnt(0)
	v_fma_f32 v56, -v49, v61, v56
	ds_read_b32 v61, v129 offset:63696
	v_fma_f32 v53, -v48, v60, v53
	v_fma_f32 v57, -v50, v62, v57
	v_fma_f32 v60, -v51, v63, v64
	s_waitcnt lgkmcnt(0)
	v_fma_f32 v53, -v52, v61, v53
	v_add_f32_e32 v53, v56, v53
	v_add_f32_e32 v56, v57, v60
	ds_read_b128 v[60:63], v129 offset:63744
	v_add_f32_e32 v53, v56, v53
	s_waitcnt lgkmcnt(0)
	v_mul_f32_e32 v56, v0, v60
	v_fma_f32 v54, v65, v54, -v56
	v_fma_f32 v56, -v1, v61, 0
	v_fma_f32 v57, -v2, v62, 0
	v_fma_f32 v58, -v3, v63, 0
	ds_read_b128 v[60:63], v129 offset:63760
	ds_read_b128 v[64:67], v129 offset:64256
	s_waitcnt lgkmcnt(1)
	v_fma_f32 v54, -v4, v60, v54
	v_fma_f32 v56, -v5, v61, v56
	v_fma_f32 v57, -v6, v62, v57
	v_fma_f32 v58, -v7, v63, v58
	ds_read_b128 v[100:103], v129 offset:63776
	ds_read_b128 v[60:63], v129 offset:63792
	ds_read_b128 v[108:111], v129 offset:63808
	ds_read_b128 v[104:107], v129 offset:63824
	s_waitcnt lgkmcnt(3)
	v_fma_f32 v54, -v8, v100, v54
	v_fma_f32 v56, -v9, v101, v56
	v_fma_f32 v57, -v10, v102, v57
	v_fma_f32 v58, -v11, v103, v58
	ds_read_b128 v[100:103], v129 offset:63840
	s_waitcnt lgkmcnt(3)
	v_fma_f32 v54, -v12, v60, v54
	v_fma_f32 v56, -v13, v61, v56
	v_fma_f32 v57, -v14, v62, v57
	v_fma_f32 v58, -v15, v63, v58
	ds_read_b128 v[60:63], v129 offset:63856
	s_waitcnt lgkmcnt(3)
	v_fma_f32 v54, -v16, v108, v54
	v_fma_f32 v56, -v17, v109, v56
	v_fma_f32 v57, -v18, v110, v57
	v_fma_f32 v58, -v19, v111, v58
	ds_read_b128 v[108:111], v129 offset:63872
	s_waitcnt lgkmcnt(3)
	v_fma_f32 v54, -v20, v104, v54
	v_fma_f32 v56, -v21, v105, v56
	v_fma_f32 v57, -v22, v106, v57
	v_fma_f32 v58, -v23, v107, v58
	ds_read_b128 v[104:107], v129 offset:63888
	s_waitcnt lgkmcnt(3)
	v_fma_f32 v54, -v24, v100, v54
	v_fma_f32 v56, -v25, v101, v56
	v_fma_f32 v57, -v26, v102, v57
	v_fma_f32 v58, -v27, v103, v58
	ds_read_b128 v[100:103], v129 offset:63904
	s_waitcnt lgkmcnt(3)
	v_fma_f32 v54, -v28, v60, v54
	v_fma_f32 v56, -v29, v61, v56
	v_fma_f32 v57, -v30, v62, v57
	v_fma_f32 v58, -v31, v63, v58
	ds_read_b128 v[60:63], v129 offset:63920
	s_waitcnt lgkmcnt(3)
	v_fma_f32 v54, -v32, v108, v54
	v_fma_f32 v56, -v33, v109, v56
	v_fma_f32 v57, -v34, v110, v57
	v_fma_f32 v58, -v35, v111, v58
	s_waitcnt lgkmcnt(2)
	v_fma_f32 v54, -v36, v104, v54
	v_fma_f32 v56, -v37, v105, v56
	v_fma_f32 v57, -v38, v106, v57
	v_fma_f32 v58, -v39, v107, v58
	s_waitcnt lgkmcnt(1)
	v_fma_f32 v54, -v40, v100, v54
	v_fma_f32 v56, -v41, v101, v56
	v_fma_f32 v57, -v42, v102, v57
	v_fma_f32 v58, -v43, v103, v58
	s_waitcnt lgkmcnt(0)
	v_fma_f32 v54, -v44, v60, v54
	v_fma_f32 v56, -v45, v61, v56
	v_fma_f32 v57, -v46, v62, v57
	v_fma_f32 v58, -v47, v63, v58
	ds_read_b128 v[60:63], v129 offset:63936
	s_waitcnt lgkmcnt(0)
	v_fma_f32 v54, -v48, v60, v54
	v_fma_f32 v60, -v49, v61, v56
	v_fma_f32 v61, -v50, v62, v57
	ds_read_b64 v[56:57], v129 offset:63952
	v_fma_f32 v58, -v51, v63, v58
	s_waitcnt lgkmcnt(0)
	v_fma_f32 v54, -v52, v56, v54
	v_fma_f32 v56, -v53, v57, v60
	v_add_f32_e32 v54, v54, v56
	v_add_f32_e32 v56, v61, v58
	v_add_f32_e32 v54, v56, v54
	v_add_u32_e32 v56, 0x3600, v69
	ds_read2_b32 v[70:71], v56 offset0:119 offset1:184
	ds_read_b128 v[56:59], v129 offset:64000
	s_waitcnt lgkmcnt(0)
	v_mul_f32_e32 v56, v0, v56
	v_fma_f32 v55, v70, v55, -v56
	v_fma_f32 v60, -v1, v57, 0
	v_fma_f32 v61, -v2, v58, 0
	v_fma_f32 v62, -v3, v59, 0
	ds_read_b128 v[56:59], v129 offset:64016
	v_fma_f32 v70, -v2, v66, 0
	s_waitcnt lgkmcnt(0)
	v_fma_f32 v55, -v4, v56, v55
	v_fma_f32 v60, -v5, v57, v60
	v_fma_f32 v61, -v6, v58, v61
	v_fma_f32 v62, -v7, v59, v62
	ds_read_b128 v[100:103], v129 offset:64032
	ds_read_b128 v[56:59], v129 offset:64048
	ds_read_b128 v[108:111], v129 offset:64064
	ds_read_b128 v[104:107], v129 offset:64080
	s_waitcnt lgkmcnt(3)
	v_fma_f32 v55, -v8, v100, v55
	v_fma_f32 v60, -v9, v101, v60
	v_fma_f32 v61, -v10, v102, v61
	v_fma_f32 v62, -v11, v103, v62
	ds_read_b128 v[100:103], v129 offset:64096
	s_waitcnt lgkmcnt(3)
	v_fma_f32 v55, -v12, v56, v55
	v_fma_f32 v60, -v13, v57, v60
	v_fma_f32 v61, -v14, v58, v61
	v_fma_f32 v62, -v15, v59, v62
	ds_read_b128 v[56:59], v129 offset:64112
	s_waitcnt lgkmcnt(3)
	v_fma_f32 v55, -v16, v108, v55
	v_fma_f32 v60, -v17, v109, v60
	v_fma_f32 v61, -v18, v110, v61
	v_fma_f32 v62, -v19, v111, v62
	ds_read_b128 v[108:111], v129 offset:64128
	s_waitcnt lgkmcnt(3)
	v_fma_f32 v55, -v20, v104, v55
	v_fma_f32 v60, -v21, v105, v60
	v_fma_f32 v61, -v22, v106, v61
	v_fma_f32 v62, -v23, v107, v62
	ds_read_b128 v[104:107], v129 offset:64144
	s_waitcnt lgkmcnt(3)
	v_fma_f32 v55, -v24, v100, v55
	v_fma_f32 v60, -v25, v101, v60
	v_fma_f32 v61, -v26, v102, v61
	v_fma_f32 v62, -v27, v103, v62
	ds_read_b128 v[100:103], v129 offset:64160
	s_waitcnt lgkmcnt(3)
	v_fma_f32 v55, -v28, v56, v55
	v_fma_f32 v60, -v29, v57, v60
	v_fma_f32 v61, -v30, v58, v61
	v_fma_f32 v62, -v31, v59, v62
	ds_read_b128 v[56:59], v129 offset:64176
	s_waitcnt lgkmcnt(3)
	v_fma_f32 v55, -v32, v108, v55
	v_fma_f32 v60, -v33, v109, v60
	v_fma_f32 v61, -v34, v110, v61
	v_fma_f32 v62, -v35, v111, v62
	s_waitcnt lgkmcnt(2)
	v_fma_f32 v55, -v36, v104, v55
	v_fma_f32 v60, -v37, v105, v60
	v_fma_f32 v61, -v38, v106, v61
	v_fma_f32 v62, -v39, v107, v62
	s_waitcnt lgkmcnt(1)
	v_fma_f32 v55, -v40, v100, v55
	v_fma_f32 v60, -v41, v101, v60
	v_fma_f32 v61, -v42, v102, v61
	v_fma_f32 v62, -v43, v103, v62
	s_waitcnt lgkmcnt(0)
	v_fma_f32 v55, -v44, v56, v55
	v_fma_f32 v60, -v45, v57, v60
	v_fma_f32 v61, -v46, v58, v61
	v_fma_f32 v62, -v47, v59, v62
	ds_read_b128 v[56:59], v129 offset:64192
	s_waitcnt lgkmcnt(0)
	v_fma_f32 v55, -v48, v56, v55
	v_fma_f32 v60, -v49, v57, v60
	v_fma_f32 v61, -v50, v58, v61
	ds_read_b96 v[56:58], v129 offset:64208
	v_fma_f32 v59, -v51, v59, v62
	s_waitcnt lgkmcnt(0)
	v_fma_f32 v55, -v52, v56, v55
	v_fma_f32 v56, -v53, v57, v60
	v_fma_f32 v57, -v54, v58, v61
	v_add_f32_e32 v55, v55, v56
	v_add_f32_e32 v56, v59, v57
	v_add_f32_e32 v55, v55, v56
	v_mov_b32_e32 v56, 0x104e0
	v_mov_b32_e32 v60, 0x106e0
	ds_read_b128 v[56:59], v56
	ds_read_b128 v[60:63], v60
	s_waitcnt lgkmcnt(0)
	v_cndmask_b32_e64 v56, v60, v56, s[44:45]
	v_mul_f32_e32 v60, v0, v64
	v_fma_f32 v56, v71, v56, -v60
	v_fma_f32 v60, -v1, v65, 0
	v_fma_f32 v71, -v3, v67, 0
	ds_read_b128 v[64:67], v129 offset:64272
	v_cndmask_b32_e64 v57, v61, v57, s[44:45]
	v_cndmask_b32_e64 v58, v62, v58, s[44:45]
	v_cndmask_b32_e64 v59, v63, v59, s[44:45]
	s_waitcnt lgkmcnt(0)
	v_fma_f32 v56, -v4, v64, v56
	v_fma_f32 v60, -v5, v65, v60
	v_fma_f32 v70, -v6, v66, v70
	v_fma_f32 v71, -v7, v67, v71
	ds_read_b128 v[104:107], v129 offset:64288
	ds_read_b128 v[100:103], v129 offset:64304
	ds_read_b128 v[64:67], v129 offset:64320
	ds_read_b128 v[108:111], v129 offset:64336
	s_waitcnt lgkmcnt(3)
	v_fma_f32 v56, -v8, v104, v56
	v_fma_f32 v60, -v9, v105, v60
	v_fma_f32 v70, -v10, v106, v70
	v_fma_f32 v71, -v11, v107, v71
	ds_read_b128 v[104:107], v129 offset:64352
	s_waitcnt lgkmcnt(3)
	v_fma_f32 v56, -v12, v100, v56
	v_fma_f32 v60, -v13, v101, v60
	v_fma_f32 v70, -v14, v102, v70
	v_fma_f32 v71, -v15, v103, v71
	ds_read_b128 v[100:103], v129 offset:64368
	s_waitcnt lgkmcnt(3)
	v_fma_f32 v56, -v16, v64, v56
	v_fma_f32 v60, -v17, v65, v60
	v_fma_f32 v70, -v18, v66, v70
	v_fma_f32 v71, -v19, v67, v71
	ds_read_b128 v[64:67], v129 offset:64384
	s_waitcnt lgkmcnt(3)
	v_fma_f32 v56, -v20, v108, v56
	v_fma_f32 v60, -v21, v109, v60
	v_fma_f32 v70, -v22, v110, v70
	v_fma_f32 v71, -v23, v111, v71
	ds_read_b128 v[108:111], v129 offset:64400
	s_waitcnt lgkmcnt(3)
	v_fma_f32 v56, -v24, v104, v56
	v_fma_f32 v60, -v25, v105, v60
	v_fma_f32 v70, -v26, v106, v70
	v_fma_f32 v71, -v27, v107, v71
	ds_read_b128 v[104:107], v129 offset:64416
	s_waitcnt lgkmcnt(3)
	v_fma_f32 v56, -v28, v100, v56
	v_fma_f32 v60, -v29, v101, v60
	v_fma_f32 v70, -v30, v102, v70
	v_fma_f32 v71, -v31, v103, v71
	ds_read_b128 v[100:103], v129 offset:64432
	s_waitcnt lgkmcnt(3)
	v_fma_f32 v56, -v32, v64, v56
	v_fma_f32 v60, -v33, v65, v60
	v_fma_f32 v70, -v34, v66, v70
	v_fma_f32 v71, -v35, v67, v71
	ds_read_b128 v[64:67], v129 offset:64448
	s_waitcnt lgkmcnt(3)
	v_fma_f32 v56, -v36, v108, v56
	v_fma_f32 v60, -v37, v109, v60
	v_fma_f32 v70, -v38, v110, v70
	v_fma_f32 v71, -v39, v111, v71
	s_waitcnt lgkmcnt(2)
	v_fma_f32 v56, -v40, v104, v56
	v_fma_f32 v60, -v41, v105, v60
	v_fma_f32 v70, -v42, v106, v70
	v_fma_f32 v71, -v43, v107, v71
	s_waitcnt lgkmcnt(1)
	v_fma_f32 v56, -v44, v100, v56
	v_fma_f32 v60, -v45, v101, v60
	v_fma_f32 v70, -v46, v102, v70
	v_fma_f32 v71, -v47, v103, v71
	s_waitcnt lgkmcnt(0)
	v_fma_f32 v56, -v48, v64, v56
	v_fma_f32 v60, -v49, v65, v60
	v_fma_f32 v70, -v50, v66, v70
	v_fma_f32 v71, -v51, v67, v71
	ds_read_b128 v[64:67], v129 offset:64464
	s_waitcnt lgkmcnt(0)
	v_fma_f32 v56, -v52, v64, v56
	v_fma_f32 v60, -v53, v65, v60
	v_fma_f32 v64, -v54, v66, v70
	v_fma_f32 v65, -v55, v67, v71
	v_add_f32_e32 v56, v56, v60
	v_add_f32_e32 v60, v64, v65
	v_add_f32_e32 v56, v56, v60
	v_add_u32_e32 v60, 0x3800, v69
	ds_read_b128 v[64:67], v129 offset:64512
	ds_read2_b32 v[70:71], v60 offset0:121 offset1:186
	s_waitcnt lgkmcnt(1)
	v_mul_f32_e32 v60, v0, v64
	s_waitcnt lgkmcnt(0)
	v_fma_f32 v57, v70, v57, -v60
	v_fma_f32 v60, -v1, v65, 0
	v_fma_f32 v61, -v2, v66, 0
	v_fma_f32 v70, -v3, v67, 0
	ds_read_b128 v[108:111], v129 offset:64528
	ds_read_b128 v[104:107], v129 offset:64544
	ds_read_b128 v[100:103], v129 offset:64560
	ds_read_b128 v[64:67], v129 offset:64576
	s_waitcnt lgkmcnt(3)
	v_fma_f32 v57, -v4, v108, v57
	v_fma_f32 v60, -v5, v109, v60
	v_fma_f32 v61, -v6, v110, v61
	v_fma_f32 v70, -v7, v111, v70
	ds_read_b128 v[108:111], v129 offset:64592
	s_waitcnt lgkmcnt(3)
	v_fma_f32 v57, -v8, v104, v57
	v_fma_f32 v60, -v9, v105, v60
	v_fma_f32 v61, -v10, v106, v61
	v_fma_f32 v70, -v11, v107, v70
	ds_read_b128 v[104:107], v129 offset:64608
	s_waitcnt lgkmcnt(3)
	v_fma_f32 v57, -v12, v100, v57
	v_fma_f32 v60, -v13, v101, v60
	v_fma_f32 v61, -v14, v102, v61
	v_fma_f32 v70, -v15, v103, v70
	ds_read_b128 v[100:103], v129 offset:64624
	s_waitcnt lgkmcnt(3)
	v_fma_f32 v57, -v16, v64, v57
	v_fma_f32 v60, -v17, v65, v60
	v_fma_f32 v61, -v18, v66, v61
	v_fma_f32 v70, -v19, v67, v70
	ds_read_b128 v[64:67], v129 offset:64640
	s_waitcnt lgkmcnt(3)
	v_fma_f32 v57, -v20, v108, v57
	v_fma_f32 v60, -v21, v109, v60
	v_fma_f32 v61, -v22, v110, v61
	v_fma_f32 v70, -v23, v111, v70
	ds_read_b128 v[108:111], v129 offset:64656
	s_waitcnt lgkmcnt(3)
	v_fma_f32 v57, -v24, v104, v57
	v_fma_f32 v60, -v25, v105, v60
	v_fma_f32 v61, -v26, v106, v61
	v_fma_f32 v70, -v27, v107, v70
	ds_read_b128 v[104:107], v129 offset:64672
	s_waitcnt lgkmcnt(3)
	v_fma_f32 v57, -v28, v100, v57
	v_fma_f32 v60, -v29, v101, v60
	v_fma_f32 v61, -v30, v102, v61
	v_fma_f32 v70, -v31, v103, v70
	ds_read_b128 v[100:103], v129 offset:64688
	s_waitcnt lgkmcnt(3)
	v_fma_f32 v57, -v32, v64, v57
	v_fma_f32 v60, -v33, v65, v60
	v_fma_f32 v61, -v34, v66, v61
	v_fma_f32 v70, -v35, v67, v70
	ds_read_b128 v[64:67], v129 offset:64704
	s_waitcnt lgkmcnt(3)
	v_fma_f32 v57, -v36, v108, v57
	v_fma_f32 v60, -v37, v109, v60
	v_fma_f32 v61, -v38, v110, v61
	v_fma_f32 v70, -v39, v111, v70
	s_waitcnt lgkmcnt(2)
	v_fma_f32 v57, -v40, v104, v57
	v_fma_f32 v60, -v41, v105, v60
	v_fma_f32 v61, -v42, v106, v61
	v_fma_f32 v70, -v43, v107, v70
	s_waitcnt lgkmcnt(1)
	v_fma_f32 v57, -v44, v100, v57
	v_fma_f32 v60, -v45, v101, v60
	v_fma_f32 v61, -v46, v102, v61
	v_fma_f32 v70, -v47, v103, v70
	s_waitcnt lgkmcnt(0)
	v_fma_f32 v57, -v48, v64, v57
	v_fma_f32 v60, -v49, v65, v60
	v_fma_f32 v61, -v50, v66, v61
	v_fma_f32 v70, -v51, v67, v70
	ds_read_b128 v[64:67], v129 offset:64720
	s_waitcnt lgkmcnt(0)
	v_fma_f32 v60, -v53, v65, v60
	ds_read_b32 v65, v129 offset:64736
	v_fma_f32 v57, -v52, v64, v57
	v_fma_f32 v61, -v54, v66, v61
	v_fma_f32 v64, -v55, v67, v70
	s_waitcnt lgkmcnt(0)
	v_fma_f32 v57, -v56, v65, v57
	v_add_f32_e32 v57, v60, v57
	v_add_f32_e32 v60, v61, v64
	ds_read_b128 v[64:67], v129 offset:64768
	v_add_f32_e32 v57, v60, v57
	s_waitcnt lgkmcnt(0)
	v_mul_f32_e32 v60, v0, v64
	v_fma_f32 v58, v71, v58, -v60
	v_fma_f32 v60, -v1, v65, 0
	v_fma_f32 v61, -v2, v66, 0
	v_fma_f32 v62, -v3, v67, 0
	ds_read_b128 v[64:67], v129 offset:64784
	ds_read_b128 v[70:73], v129 offset:65280
	s_waitcnt lgkmcnt(1)
	v_fma_f32 v58, -v4, v64, v58
	v_fma_f32 v60, -v5, v65, v60
	v_fma_f32 v61, -v6, v66, v61
	v_fma_f32 v62, -v7, v67, v62
	ds_read_b128 v[104:107], v129 offset:64800
	ds_read_b128 v[100:103], v129 offset:64816
	ds_read_b128 v[64:67], v129 offset:64832
	ds_read_b128 v[108:111], v129 offset:64848
	s_waitcnt lgkmcnt(3)
	v_fma_f32 v58, -v8, v104, v58
	v_fma_f32 v60, -v9, v105, v60
	v_fma_f32 v61, -v10, v106, v61
	v_fma_f32 v62, -v11, v107, v62
	ds_read_b128 v[104:107], v129 offset:64864
	s_waitcnt lgkmcnt(3)
	v_fma_f32 v58, -v12, v100, v58
	v_fma_f32 v60, -v13, v101, v60
	v_fma_f32 v61, -v14, v102, v61
	v_fma_f32 v62, -v15, v103, v62
	ds_read_b128 v[100:103], v129 offset:64880
	s_waitcnt lgkmcnt(3)
	v_fma_f32 v58, -v16, v64, v58
	v_fma_f32 v60, -v17, v65, v60
	v_fma_f32 v61, -v18, v66, v61
	v_fma_f32 v62, -v19, v67, v62
	ds_read_b128 v[64:67], v129 offset:64896
	s_waitcnt lgkmcnt(3)
	v_fma_f32 v58, -v20, v108, v58
	v_fma_f32 v60, -v21, v109, v60
	v_fma_f32 v61, -v22, v110, v61
	v_fma_f32 v62, -v23, v111, v62
	ds_read_b128 v[108:111], v129 offset:64912
	s_waitcnt lgkmcnt(3)
	v_fma_f32 v58, -v24, v104, v58
	v_fma_f32 v60, -v25, v105, v60
	v_fma_f32 v61, -v26, v106, v61
	v_fma_f32 v62, -v27, v107, v62
	ds_read_b128 v[104:107], v129 offset:64928
	s_waitcnt lgkmcnt(3)
	v_fma_f32 v58, -v28, v100, v58
	v_fma_f32 v60, -v29, v101, v60
	v_fma_f32 v61, -v30, v102, v61
	v_fma_f32 v62, -v31, v103, v62
	ds_read_b128 v[100:103], v129 offset:64944
	s_waitcnt lgkmcnt(3)
	v_fma_f32 v58, -v32, v64, v58
	v_fma_f32 v60, -v33, v65, v60
	v_fma_f32 v61, -v34, v66, v61
	v_fma_f32 v62, -v35, v67, v62
	ds_read_b128 v[64:67], v129 offset:64960
	s_waitcnt lgkmcnt(3)
	v_fma_f32 v58, -v36, v108, v58
	v_fma_f32 v60, -v37, v109, v60
	v_fma_f32 v61, -v38, v110, v61
	v_fma_f32 v62, -v39, v111, v62
	s_waitcnt lgkmcnt(2)
	v_fma_f32 v58, -v40, v104, v58
	v_fma_f32 v60, -v41, v105, v60
	v_fma_f32 v61, -v42, v106, v61
	v_fma_f32 v62, -v43, v107, v62
	s_waitcnt lgkmcnt(1)
	v_fma_f32 v58, -v44, v100, v58
	v_fma_f32 v60, -v45, v101, v60
	v_fma_f32 v61, -v46, v102, v61
	v_fma_f32 v62, -v47, v103, v62
	s_waitcnt lgkmcnt(0)
	v_fma_f32 v58, -v48, v64, v58
	v_fma_f32 v60, -v49, v65, v60
	v_fma_f32 v61, -v50, v66, v61
	v_fma_f32 v62, -v51, v67, v62
	ds_read_b128 v[64:67], v129 offset:64976
	s_waitcnt lgkmcnt(0)
	v_fma_f32 v58, -v52, v64, v58
	v_fma_f32 v64, -v53, v65, v60
	v_fma_f32 v65, -v54, v66, v61
	ds_read_b64 v[60:61], v129 offset:64992
	v_fma_f32 v62, -v55, v67, v62
	s_waitcnt lgkmcnt(0)
	v_fma_f32 v58, -v56, v60, v58
	v_fma_f32 v60, -v57, v61, v64
	v_add_f32_e32 v58, v58, v60
	v_add_f32_e32 v60, v65, v62
	v_add_f32_e32 v58, v60, v58
	v_add_u32_e32 v60, 0x3a00, v69
	ds_read2_b32 v[74:75], v60 offset0:123 offset1:188
	ds_read_b128 v[60:63], v129 offset:65024
	s_waitcnt lgkmcnt(0)
	v_mul_f32_e32 v60, v0, v60
	v_fma_f32 v59, v74, v59, -v60
	v_fma_f32 v64, -v1, v61, 0
	v_fma_f32 v65, -v2, v62, 0
	v_fma_f32 v66, -v3, v63, 0
	ds_read_b128 v[60:63], v129 offset:65040
	v_fma_f32 v74, -v2, v72, 0
	s_waitcnt lgkmcnt(0)
	v_fma_f32 v59, -v4, v60, v59
	v_fma_f32 v64, -v5, v61, v64
	v_fma_f32 v65, -v6, v62, v65
	v_fma_f32 v66, -v7, v63, v66
	ds_read_b128 v[104:107], v129 offset:65056
	ds_read_b128 v[100:103], v129 offset:65072
	ds_read_b128 v[60:63], v129 offset:65088
	ds_read_b128 v[108:111], v129 offset:65104
	s_waitcnt lgkmcnt(3)
	v_fma_f32 v59, -v8, v104, v59
	v_fma_f32 v64, -v9, v105, v64
	v_fma_f32 v65, -v10, v106, v65
	v_fma_f32 v66, -v11, v107, v66
	ds_read_b128 v[104:107], v129 offset:65120
	s_waitcnt lgkmcnt(3)
	v_fma_f32 v59, -v12, v100, v59
	v_fma_f32 v64, -v13, v101, v64
	v_fma_f32 v65, -v14, v102, v65
	v_fma_f32 v66, -v15, v103, v66
	ds_read_b128 v[100:103], v129 offset:65136
	s_waitcnt lgkmcnt(3)
	v_fma_f32 v59, -v16, v60, v59
	v_fma_f32 v64, -v17, v61, v64
	v_fma_f32 v65, -v18, v62, v65
	v_fma_f32 v66, -v19, v63, v66
	ds_read_b128 v[60:63], v129 offset:65152
	s_waitcnt lgkmcnt(3)
	v_fma_f32 v59, -v20, v108, v59
	v_fma_f32 v64, -v21, v109, v64
	v_fma_f32 v65, -v22, v110, v65
	v_fma_f32 v66, -v23, v111, v66
	ds_read_b128 v[108:111], v129 offset:65168
	s_waitcnt lgkmcnt(3)
	v_fma_f32 v59, -v24, v104, v59
	v_fma_f32 v64, -v25, v105, v64
	v_fma_f32 v65, -v26, v106, v65
	v_fma_f32 v66, -v27, v107, v66
	ds_read_b128 v[104:107], v129 offset:65184
	s_waitcnt lgkmcnt(3)
	v_fma_f32 v59, -v28, v100, v59
	v_fma_f32 v64, -v29, v101, v64
	v_fma_f32 v65, -v30, v102, v65
	v_fma_f32 v66, -v31, v103, v66
	ds_read_b128 v[100:103], v129 offset:65200
	s_waitcnt lgkmcnt(3)
	v_fma_f32 v59, -v32, v60, v59
	v_fma_f32 v64, -v33, v61, v64
	v_fma_f32 v65, -v34, v62, v65
	v_fma_f32 v66, -v35, v63, v66
	ds_read_b128 v[60:63], v129 offset:65216
	s_waitcnt lgkmcnt(3)
	v_fma_f32 v59, -v36, v108, v59
	v_fma_f32 v64, -v37, v109, v64
	v_fma_f32 v65, -v38, v110, v65
	v_fma_f32 v66, -v39, v111, v66
	s_waitcnt lgkmcnt(2)
	v_fma_f32 v59, -v40, v104, v59
	v_fma_f32 v64, -v41, v105, v64
	v_fma_f32 v65, -v42, v106, v65
	v_fma_f32 v66, -v43, v107, v66
	s_waitcnt lgkmcnt(1)
	v_fma_f32 v59, -v44, v100, v59
	v_fma_f32 v64, -v45, v101, v64
	v_fma_f32 v65, -v46, v102, v65
	v_fma_f32 v66, -v47, v103, v66
	s_waitcnt lgkmcnt(0)
	v_fma_f32 v59, -v48, v60, v59
	v_fma_f32 v64, -v49, v61, v64
	v_fma_f32 v65, -v50, v62, v65
	v_fma_f32 v66, -v51, v63, v66
	ds_read_b128 v[60:63], v129 offset:65232
	s_waitcnt lgkmcnt(0)
	v_fma_f32 v59, -v52, v60, v59
	v_fma_f32 v64, -v53, v61, v64
	v_fma_f32 v65, -v54, v62, v65
	ds_read_b96 v[60:62], v129 offset:65248
	v_fma_f32 v63, -v55, v63, v66
	s_waitcnt lgkmcnt(0)
	v_fma_f32 v59, -v56, v60, v59
	v_fma_f32 v60, -v57, v61, v64
	v_fma_f32 v61, -v58, v62, v65
	v_add_f32_e32 v59, v59, v60
	v_add_f32_e32 v60, v63, v61
	v_add_f32_e32 v59, v59, v60
	v_mov_b32_e32 v60, 0x104f0
	v_mov_b32_e32 v64, 0x106f0
	ds_read_b128 v[60:63], v60
	ds_read_b128 v[64:67], v64
	s_waitcnt lgkmcnt(0)
	v_cndmask_b32_e64 v60, v64, v60, s[44:45]
	v_mul_f32_e32 v64, v0, v70
	v_fma_f32 v60, v75, v60, -v64
	v_fma_f32 v64, -v1, v71, 0
	v_fma_f32 v75, -v3, v73, 0
	ds_read_b128 v[70:73], v129 offset:65296
	v_cndmask_b32_e64 v61, v65, v61, s[44:45]
	v_cndmask_b32_e64 v62, v66, v62, s[44:45]
	v_cndmask_b32_e64 v63, v67, v63, s[44:45]
	s_waitcnt lgkmcnt(0)
	v_fma_f32 v60, -v4, v70, v60
	v_fma_f32 v64, -v5, v71, v64
	v_fma_f32 v74, -v6, v72, v74
	v_fma_f32 v75, -v7, v73, v75
	ds_read_b128 v[108:111], v129 offset:65312
	ds_read_b128 v[104:107], v129 offset:65328
	ds_read_b128 v[100:103], v129 offset:65344
	ds_read_b128 v[70:73], v129 offset:65360
	s_waitcnt lgkmcnt(3)
	v_fma_f32 v60, -v8, v108, v60
	v_fma_f32 v64, -v9, v109, v64
	v_fma_f32 v74, -v10, v110, v74
	v_fma_f32 v75, -v11, v111, v75
	ds_read_b128 v[108:111], v129 offset:65376
	s_waitcnt lgkmcnt(3)
	v_fma_f32 v60, -v12, v104, v60
	v_fma_f32 v64, -v13, v105, v64
	v_fma_f32 v74, -v14, v106, v74
	v_fma_f32 v75, -v15, v107, v75
	ds_read_b128 v[104:107], v129 offset:65392
	s_waitcnt lgkmcnt(3)
	v_fma_f32 v60, -v16, v100, v60
	v_fma_f32 v64, -v17, v101, v64
	v_fma_f32 v74, -v18, v102, v74
	v_fma_f32 v75, -v19, v103, v75
	ds_read_b128 v[100:103], v129 offset:65408
	s_waitcnt lgkmcnt(3)
	v_fma_f32 v60, -v20, v70, v60
	v_fma_f32 v64, -v21, v71, v64
	v_fma_f32 v74, -v22, v72, v74
	v_fma_f32 v75, -v23, v73, v75
	ds_read_b128 v[70:73], v129 offset:65424
	s_waitcnt lgkmcnt(3)
	v_fma_f32 v60, -v24, v108, v60
	v_fma_f32 v64, -v25, v109, v64
	v_fma_f32 v74, -v26, v110, v74
	v_fma_f32 v75, -v27, v111, v75
	ds_read_b128 v[108:111], v129 offset:65440
	s_waitcnt lgkmcnt(3)
	v_fma_f32 v60, -v28, v104, v60
	v_fma_f32 v64, -v29, v105, v64
	v_fma_f32 v74, -v30, v106, v74
	v_fma_f32 v75, -v31, v107, v75
	ds_read_b128 v[104:107], v129 offset:65456
	s_waitcnt lgkmcnt(3)
	v_fma_f32 v60, -v32, v100, v60
	v_fma_f32 v64, -v33, v101, v64
	v_fma_f32 v74, -v34, v102, v74
	v_fma_f32 v75, -v35, v103, v75
	ds_read_b128 v[100:103], v129 offset:65472
	s_waitcnt lgkmcnt(3)
	v_fma_f32 v60, -v36, v70, v60
	v_fma_f32 v64, -v37, v71, v64
	v_fma_f32 v74, -v38, v72, v74
	v_fma_f32 v75, -v39, v73, v75
	ds_read_b128 v[70:73], v129 offset:65488
	s_waitcnt lgkmcnt(3)
	v_fma_f32 v60, -v40, v108, v60
	v_fma_f32 v64, -v41, v109, v64
	v_fma_f32 v74, -v42, v110, v74
	v_fma_f32 v75, -v43, v111, v75
	s_waitcnt lgkmcnt(2)
	v_fma_f32 v60, -v44, v104, v60
	v_fma_f32 v64, -v45, v105, v64
	v_fma_f32 v74, -v46, v106, v74
	v_fma_f32 v75, -v47, v107, v75
	s_waitcnt lgkmcnt(1)
	v_fma_f32 v60, -v48, v100, v60
	v_fma_f32 v64, -v49, v101, v64
	v_fma_f32 v74, -v50, v102, v74
	v_fma_f32 v75, -v51, v103, v75
	s_waitcnt lgkmcnt(0)
	v_fma_f32 v60, -v52, v70, v60
	v_fma_f32 v64, -v53, v71, v64
	v_fma_f32 v74, -v54, v72, v74
	v_fma_f32 v75, -v55, v73, v75
	ds_read_b128 v[70:73], v129 offset:65504
	s_waitcnt lgkmcnt(0)
	v_fma_f32 v60, -v56, v70, v60
	v_fma_f32 v64, -v57, v71, v64
	v_fma_f32 v70, -v58, v72, v74
	v_fma_f32 v71, -v59, v73, v75
	v_add_f32_e32 v60, v60, v64
	v_add_f32_e32 v64, v70, v71
	v_add_f32_e32 v60, v60, v64
	v_add_u32_e32 v64, 0x3c00, v69
	ds_read2_b32 v[74:75], v64 offset0:125 offset1:190
	v_mov_b32_e32 v64, 0x10000
	ds_read_b128 v[70:73], v64
	ds_read_b32 v69, v69 offset:16380
	s_waitcnt lgkmcnt(1)
	v_mul_f32_e32 v64, v0, v70
	v_mov_b32_e32 v70, 0x10010
	v_fma_f32 v61, v74, v61, -v64
	v_fma_f32 v64, -v1, v71, 0
	v_fma_f32 v65, -v2, v72, 0
	v_fma_f32 v74, -v3, v73, 0
	ds_read_b128 v[70:73], v70
	s_waitcnt lgkmcnt(0)
	v_fma_f32 v61, -v4, v70, v61
	v_mov_b32_e32 v70, 0x10020
	v_fma_f32 v64, -v5, v71, v64
	v_fma_f32 v65, -v6, v72, v65
	v_fma_f32 v74, -v7, v73, v74
	ds_read_b128 v[70:73], v70
	s_waitcnt lgkmcnt(0)
	v_fma_f32 v61, -v8, v70, v61
	v_mov_b32_e32 v70, 0x10030
	v_fma_f32 v64, -v9, v71, v64
	v_fma_f32 v65, -v10, v72, v65
	v_fma_f32 v74, -v11, v73, v74
	ds_read_b128 v[70:73], v70
	s_waitcnt lgkmcnt(0)
	v_fma_f32 v61, -v12, v70, v61
	v_mov_b32_e32 v70, 0x10040
	v_fma_f32 v64, -v13, v71, v64
	v_fma_f32 v65, -v14, v72, v65
	v_fma_f32 v74, -v15, v73, v74
	ds_read_b128 v[70:73], v70
	s_waitcnt lgkmcnt(0)
	v_fma_f32 v61, -v16, v70, v61
	v_mov_b32_e32 v70, 0x10050
	v_fma_f32 v64, -v17, v71, v64
	v_fma_f32 v65, -v18, v72, v65
	v_fma_f32 v74, -v19, v73, v74
	ds_read_b128 v[70:73], v70
	s_waitcnt lgkmcnt(0)
	v_fma_f32 v61, -v20, v70, v61
	v_mov_b32_e32 v70, 0x10060
	v_fma_f32 v64, -v21, v71, v64
	v_fma_f32 v65, -v22, v72, v65
	v_fma_f32 v74, -v23, v73, v74
	ds_read_b128 v[70:73], v70
	s_waitcnt lgkmcnt(0)
	v_fma_f32 v61, -v24, v70, v61
	v_mov_b32_e32 v70, 0x10070
	v_fma_f32 v64, -v25, v71, v64
	v_fma_f32 v65, -v26, v72, v65
	v_fma_f32 v74, -v27, v73, v74
	ds_read_b128 v[70:73], v70
	s_waitcnt lgkmcnt(0)
	v_fma_f32 v61, -v28, v70, v61
	v_mov_b32_e32 v70, 0x10080
	v_fma_f32 v64, -v29, v71, v64
	v_fma_f32 v65, -v30, v72, v65
	v_fma_f32 v74, -v31, v73, v74
	ds_read_b128 v[70:73], v70
	s_waitcnt lgkmcnt(0)
	v_fma_f32 v61, -v32, v70, v61
	v_mov_b32_e32 v70, 0x10090
	v_fma_f32 v64, -v33, v71, v64
	v_fma_f32 v65, -v34, v72, v65
	v_fma_f32 v74, -v35, v73, v74
	ds_read_b128 v[70:73], v70
	s_waitcnt lgkmcnt(0)
	v_fma_f32 v61, -v36, v70, v61
	v_mov_b32_e32 v70, 0x100a0
	v_fma_f32 v64, -v37, v71, v64
	v_fma_f32 v65, -v38, v72, v65
	v_fma_f32 v74, -v39, v73, v74
	ds_read_b128 v[70:73], v70
	s_waitcnt lgkmcnt(0)
	v_fma_f32 v61, -v40, v70, v61
	v_mov_b32_e32 v70, 0x100b0
	v_fma_f32 v64, -v41, v71, v64
	v_fma_f32 v65, -v42, v72, v65
	v_fma_f32 v74, -v43, v73, v74
	ds_read_b128 v[70:73], v70
	s_waitcnt lgkmcnt(0)
	v_fma_f32 v61, -v44, v70, v61
	v_mov_b32_e32 v70, 0x100c0
	v_fma_f32 v64, -v45, v71, v64
	v_fma_f32 v65, -v46, v72, v65
	v_fma_f32 v74, -v47, v73, v74
	ds_read_b128 v[70:73], v70
	s_waitcnt lgkmcnt(0)
	v_fma_f32 v61, -v48, v70, v61
	v_mov_b32_e32 v70, 0x100d0
	v_fma_f32 v64, -v49, v71, v64
	v_fma_f32 v65, -v50, v72, v65
	v_fma_f32 v74, -v51, v73, v74
	ds_read_b128 v[70:73], v70
	s_waitcnt lgkmcnt(0)
	v_fma_f32 v61, -v52, v70, v61
	v_mov_b32_e32 v70, 0x100e0
	v_fma_f32 v64, -v53, v71, v64
	v_fma_f32 v65, -v54, v72, v65
	v_fma_f32 v74, -v55, v73, v74
	ds_read_b128 v[70:73], v70
	s_waitcnt lgkmcnt(0)
	v_fma_f32 v64, -v57, v71, v64
	v_mov_b32_e32 v71, 0x100f0
	ds_read_b32 v71, v71
	v_fma_f32 v61, -v56, v70, v61
	v_fma_f32 v65, -v58, v72, v65
	v_fma_f32 v70, -v59, v73, v74
	s_waitcnt lgkmcnt(0)
	v_fma_f32 v61, -v60, v71, v61
	v_add_f32_e32 v61, v64, v61
	v_add_f32_e32 v64, v65, v70
	v_add_f32_e32 v61, v64, v61
	v_mov_b32_e32 v64, 0x10100
	ds_read_b128 v[70:73], v64
	s_waitcnt lgkmcnt(0)
	v_mul_f32_e32 v64, v0, v70
	v_mov_b32_e32 v70, 0x10110
	v_fma_f32 v62, v75, v62, -v64
	v_fma_f32 v64, -v1, v71, 0
	v_fma_f32 v65, -v2, v72, 0
	v_fma_f32 v66, -v3, v73, 0
	ds_read_b128 v[70:73], v70
	s_waitcnt lgkmcnt(0)
	v_fma_f32 v62, -v4, v70, v62
	v_mov_b32_e32 v70, 0x10120
	v_fma_f32 v64, -v5, v71, v64
	v_fma_f32 v65, -v6, v72, v65
	v_fma_f32 v66, -v7, v73, v66
	ds_read_b128 v[70:73], v70
	s_waitcnt lgkmcnt(0)
	v_fma_f32 v62, -v8, v70, v62
	v_mov_b32_e32 v70, 0x10130
	v_fma_f32 v64, -v9, v71, v64
	v_fma_f32 v65, -v10, v72, v65
	v_fma_f32 v66, -v11, v73, v66
	ds_read_b128 v[70:73], v70
	s_waitcnt lgkmcnt(0)
	v_fma_f32 v62, -v12, v70, v62
	v_mov_b32_e32 v70, 0x10140
	v_fma_f32 v64, -v13, v71, v64
	v_fma_f32 v65, -v14, v72, v65
	v_fma_f32 v66, -v15, v73, v66
	ds_read_b128 v[70:73], v70
	s_waitcnt lgkmcnt(0)
	v_fma_f32 v62, -v16, v70, v62
	v_mov_b32_e32 v70, 0x10150
	v_fma_f32 v64, -v17, v71, v64
	v_fma_f32 v65, -v18, v72, v65
	v_fma_f32 v66, -v19, v73, v66
	ds_read_b128 v[70:73], v70
	s_waitcnt lgkmcnt(0)
	v_fma_f32 v62, -v20, v70, v62
	v_mov_b32_e32 v70, 0x10160
	v_fma_f32 v64, -v21, v71, v64
	v_fma_f32 v65, -v22, v72, v65
	v_fma_f32 v66, -v23, v73, v66
	ds_read_b128 v[70:73], v70
	s_waitcnt lgkmcnt(0)
	v_fma_f32 v62, -v24, v70, v62
	v_mov_b32_e32 v70, 0x10170
	v_fma_f32 v64, -v25, v71, v64
	v_fma_f32 v65, -v26, v72, v65
	v_fma_f32 v66, -v27, v73, v66
	ds_read_b128 v[70:73], v70
	s_waitcnt lgkmcnt(0)
	v_fma_f32 v62, -v28, v70, v62
	v_mov_b32_e32 v70, 0x10180
	v_fma_f32 v64, -v29, v71, v64
	v_fma_f32 v65, -v30, v72, v65
	v_fma_f32 v66, -v31, v73, v66
	ds_read_b128 v[70:73], v70
	s_waitcnt lgkmcnt(0)
	v_fma_f32 v62, -v32, v70, v62
	v_mov_b32_e32 v70, 0x10190
	v_fma_f32 v64, -v33, v71, v64
	v_fma_f32 v65, -v34, v72, v65
	v_fma_f32 v66, -v35, v73, v66
	ds_read_b128 v[70:73], v70
	s_waitcnt lgkmcnt(0)
	v_fma_f32 v62, -v36, v70, v62
	v_mov_b32_e32 v70, 0x101a0
	v_fma_f32 v64, -v37, v71, v64
	v_fma_f32 v65, -v38, v72, v65
	v_fma_f32 v66, -v39, v73, v66
	ds_read_b128 v[70:73], v70
	s_waitcnt lgkmcnt(0)
	v_fma_f32 v62, -v40, v70, v62
	v_mov_b32_e32 v70, 0x101b0
	v_fma_f32 v64, -v41, v71, v64
	v_fma_f32 v65, -v42, v72, v65
	v_fma_f32 v66, -v43, v73, v66
	ds_read_b128 v[70:73], v70
	s_waitcnt lgkmcnt(0)
	v_fma_f32 v62, -v44, v70, v62
	v_mov_b32_e32 v70, 0x101c0
	v_fma_f32 v64, -v45, v71, v64
	v_fma_f32 v65, -v46, v72, v65
	v_fma_f32 v66, -v47, v73, v66
	ds_read_b128 v[70:73], v70
	s_waitcnt lgkmcnt(0)
	v_fma_f32 v62, -v48, v70, v62
	v_mov_b32_e32 v70, 0x101d0
	v_fma_f32 v64, -v49, v71, v64
	v_fma_f32 v65, -v50, v72, v65
	v_fma_f32 v66, -v51, v73, v66
	ds_read_b128 v[70:73], v70
	s_waitcnt lgkmcnt(0)
	v_fma_f32 v62, -v52, v70, v62
	v_mov_b32_e32 v70, 0x101e0
	v_fma_f32 v64, -v53, v71, v64
	v_fma_f32 v65, -v54, v72, v65
	v_fma_f32 v66, -v55, v73, v66
	ds_read_b128 v[70:73], v70
	s_waitcnt lgkmcnt(0)
	v_fma_f32 v62, -v56, v70, v62
	v_fma_f32 v70, -v57, v71, v64
	v_mov_b32_e32 v64, 0x101f0
	v_fma_f32 v71, -v58, v72, v65
	ds_read_b64 v[64:65], v64
	v_fma_f32 v66, -v59, v73, v66
	s_waitcnt lgkmcnt(0)
	v_fma_f32 v62, -v60, v64, v62
	v_fma_f32 v64, -v61, v65, v70
	v_add_f32_e32 v62, v62, v64
	v_add_f32_e32 v64, v71, v66
	v_add_f32_e32 v62, v64, v62
	v_mov_b32_e32 v64, 0x10200
	ds_read_b128 v[64:67], v64
	s_waitcnt lgkmcnt(0)
	v_mul_f32_e32 v64, v0, v64
	v_fma_f32 v63, v69, v63, -v64
	v_mov_b32_e32 v64, 0x10210
	v_fma_f32 v69, -v1, v65, 0
	v_fma_f32 v70, -v2, v66, 0
	v_fma_f32 v71, -v3, v67, 0
	ds_read_b128 v[64:67], v64
	s_waitcnt lgkmcnt(0)
	v_fma_f32 v63, -v4, v64, v63
	v_mov_b32_e32 v64, 0x10220
	v_fma_f32 v69, -v5, v65, v69
	v_fma_f32 v70, -v6, v66, v70
	v_fma_f32 v71, -v7, v67, v71
	ds_read_b128 v[64:67], v64
	s_waitcnt lgkmcnt(0)
	v_fma_f32 v63, -v8, v64, v63
	v_mov_b32_e32 v64, 0x10230
	v_fma_f32 v69, -v9, v65, v69
	v_fma_f32 v70, -v10, v66, v70
	v_fma_f32 v71, -v11, v67, v71
	ds_read_b128 v[64:67], v64
	s_waitcnt lgkmcnt(0)
	v_fma_f32 v63, -v12, v64, v63
	v_mov_b32_e32 v64, 0x10240
	v_fma_f32 v69, -v13, v65, v69
	v_fma_f32 v70, -v14, v66, v70
	v_fma_f32 v71, -v15, v67, v71
	ds_read_b128 v[64:67], v64
	s_waitcnt lgkmcnt(0)
	v_fma_f32 v63, -v16, v64, v63
	v_mov_b32_e32 v64, 0x10250
	v_fma_f32 v69, -v17, v65, v69
	v_fma_f32 v70, -v18, v66, v70
	v_fma_f32 v71, -v19, v67, v71
	ds_read_b128 v[64:67], v64
	s_waitcnt lgkmcnt(0)
	v_fma_f32 v63, -v20, v64, v63
	v_mov_b32_e32 v64, 0x10260
	v_fma_f32 v69, -v21, v65, v69
	v_fma_f32 v70, -v22, v66, v70
	v_fma_f32 v71, -v23, v67, v71
	ds_read_b128 v[64:67], v64
	s_waitcnt lgkmcnt(0)
	v_fma_f32 v63, -v24, v64, v63
	v_mov_b32_e32 v64, 0x10270
	v_fma_f32 v69, -v25, v65, v69
	v_fma_f32 v70, -v26, v66, v70
	v_fma_f32 v71, -v27, v67, v71
	ds_read_b128 v[64:67], v64
	s_waitcnt lgkmcnt(0)
	v_fma_f32 v63, -v28, v64, v63
	v_mov_b32_e32 v64, 0x10280
	v_fma_f32 v69, -v29, v65, v69
	v_fma_f32 v70, -v30, v66, v70
	v_fma_f32 v71, -v31, v67, v71
	ds_read_b128 v[64:67], v64
	s_waitcnt lgkmcnt(0)
	v_fma_f32 v63, -v32, v64, v63
	v_mov_b32_e32 v64, 0x10290
	v_fma_f32 v69, -v33, v65, v69
	v_fma_f32 v70, -v34, v66, v70
	v_fma_f32 v71, -v35, v67, v71
	ds_read_b128 v[64:67], v64
	s_waitcnt lgkmcnt(0)
	v_fma_f32 v63, -v36, v64, v63
	v_mov_b32_e32 v64, 0x102a0
	v_fma_f32 v69, -v37, v65, v69
	v_fma_f32 v70, -v38, v66, v70
	v_fma_f32 v71, -v39, v67, v71
	ds_read_b128 v[64:67], v64
	s_waitcnt lgkmcnt(0)
	v_fma_f32 v63, -v40, v64, v63
	v_mov_b32_e32 v64, 0x102b0
	v_fma_f32 v69, -v41, v65, v69
	v_fma_f32 v70, -v42, v66, v70
	v_fma_f32 v71, -v43, v67, v71
	ds_read_b128 v[64:67], v64
	s_waitcnt lgkmcnt(0)
	v_fma_f32 v63, -v44, v64, v63
	v_mov_b32_e32 v64, 0x102c0
	v_fma_f32 v69, -v45, v65, v69
	v_fma_f32 v70, -v46, v66, v70
	v_fma_f32 v71, -v47, v67, v71
	ds_read_b128 v[64:67], v64
	s_waitcnt lgkmcnt(0)
	v_fma_f32 v63, -v48, v64, v63
	v_mov_b32_e32 v64, 0x102d0
	v_fma_f32 v69, -v49, v65, v69
	v_fma_f32 v70, -v50, v66, v70
	v_fma_f32 v71, -v51, v67, v71
	ds_read_b128 v[64:67], v64
	s_waitcnt lgkmcnt(0)
	v_fma_f32 v63, -v52, v64, v63
	v_fma_f32 v64, -v53, v65, v69
	v_fma_f32 v65, -v54, v66, v70
	v_fma_f32 v66, -v55, v67, v71
	v_mov_b32_e32 v67, 0x102e0
	ds_read_b128 v[70:73], v67
	s_waitcnt lgkmcnt(0)
	v_fma_f32 v69, -v57, v71, v64
	v_mov_b32_e32 v64, 0x102f0
	v_fma_f32 v67, -v56, v70, v63
	v_fma_f32 v70, -v58, v72, v65
	v_fma_f32 v63, -v59, v73, v66
	ds_read_b96 v[64:66], v64
	s_waitcnt lgkmcnt(0)
	v_fma_f32 v64, -v60, v64, v67
	v_fma_f32 v65, -v61, v65, v69
	v_fma_f32 v66, -v62, v66, v70
	v_add_f32_e32 v64, v64, v65
	v_add_f32_e32 v63, v63, v66
	v_add_f32_e32 v63, v64, v63
	s_and_saveexec_b64 s[2:3], s[42:43]
	s_xor_b64 s[40:41], exec, s[2:3]
	s_cbranch_execz .LBB0_419
	v_mov_b32_e32 v69, v129
	v_lshl_add_u64 v[64:65], v[68:69], 1, s[56:57]
	v_cvt_pk_bf16_f32 v0, -v0, s0
	v_lshl_add_u64 v[66:67], v[64:65], 0, s[0:1]
	global_store_short v[66:67], v0, off offset:-128
	v_add_co_u32_e32 v0, vcc, 0x4000, v64
	v_cvt_pk_bf16_f32 v68, -v1, s0
	s_nop 0
	v_addc_co_u32_e32 v1, vcc, 0, v65, vcc
	global_store_short v[0:1], v68, off
	v_cvt_pk_bf16_f32 v0, -v2, s0
	global_store_short v[66:67], v0, off offset:128
	v_cvt_pk_bf16_f32 v0, -v3, s0
	global_store_short v[66:67], v0, off offset:256
	v_cvt_pk_bf16_f32 v0, -v4, s0
	global_store_short v[66:67], v0, off offset:384
	v_cvt_pk_bf16_f32 v0, -v5, s0
	global_store_short v[66:67], v0, off offset:512
	v_cvt_pk_bf16_f32 v0, -v6, s0
	global_store_short v[66:67], v0, off offset:640
	v_cvt_pk_bf16_f32 v0, -v7, s0
	global_store_short v[66:67], v0, off offset:768
	v_cvt_pk_bf16_f32 v0, -v8, s0
	global_store_short v[66:67], v0, off offset:896
	v_cvt_pk_bf16_f32 v0, -v9, s0
	global_store_short v[66:67], v0, off offset:1024
	v_cvt_pk_bf16_f32 v0, -v10, s0
	global_store_short v[66:67], v0, off offset:1152
	v_cvt_pk_bf16_f32 v0, -v11, s0
	global_store_short v[66:67], v0, off offset:1280
	v_cvt_pk_bf16_f32 v0, -v12, s0
	global_store_short v[66:67], v0, off offset:1408
	v_cvt_pk_bf16_f32 v0, -v13, s0
	global_store_short v[66:67], v0, off offset:1536
	v_cvt_pk_bf16_f32 v0, -v14, s0
	global_store_short v[66:67], v0, off offset:1664
	v_cvt_pk_bf16_f32 v0, -v15, s0
	global_store_short v[66:67], v0, off offset:1792
	v_cvt_pk_bf16_f32 v0, -v16, s0
	global_store_short v[66:67], v0, off offset:1920
	v_cvt_pk_bf16_f32 v0, -v17, s0
	global_store_short v[66:67], v0, off offset:2048
	v_cvt_pk_bf16_f32 v0, -v18, s0
	global_store_short v[66:67], v0, off offset:2176
	v_cvt_pk_bf16_f32 v0, -v19, s0
	global_store_short v[66:67], v0, off offset:2304
	v_cvt_pk_bf16_f32 v0, -v20, s0
	global_store_short v[66:67], v0, off offset:2432
	v_cvt_pk_bf16_f32 v0, -v21, s0
	global_store_short v[66:67], v0, off offset:2560
	v_cvt_pk_bf16_f32 v0, -v22, s0
	global_store_short v[66:67], v0, off offset:2688
	v_cvt_pk_bf16_f32 v0, -v23, s0
	global_store_short v[66:67], v0, off offset:2816
	v_cvt_pk_bf16_f32 v0, -v24, s0
	global_store_short v[66:67], v0, off offset:2944
	v_cvt_pk_bf16_f32 v0, -v25, s0
	global_store_short v[66:67], v0, off offset:3072
	v_cvt_pk_bf16_f32 v0, -v26, s0
	global_store_short v[66:67], v0, off offset:3200
	v_cvt_pk_bf16_f32 v0, -v27, s0
	global_store_short v[66:67], v0, off offset:3328
	v_cvt_pk_bf16_f32 v0, -v28, s0
	global_store_short v[66:67], v0, off offset:3456
	v_cvt_pk_bf16_f32 v0, -v29, s0
	global_store_short v[66:67], v0, off offset:3584
	v_cvt_pk_bf16_f32 v0, -v30, s0
	global_store_short v[66:67], v0, off offset:3712
	v_cvt_pk_bf16_f32 v0, -v31, s0
	global_store_short v[66:67], v0, off offset:3840
	v_cvt_pk_bf16_f32 v0, -v32, s0
	s_movk_i32 s2, 0x5000
	global_store_short v[66:67], v0, off offset:3968
	v_add_co_u32_e32 v0, vcc, s2, v64
	v_cvt_pk_bf16_f32 v2, -v33, s0
	s_nop 0
	v_addc_co_u32_e32 v1, vcc, 0, v65, vcc
	global_store_short v[0:1], v2, off
	v_cvt_pk_bf16_f32 v2, -v34, s0
	global_store_short v[0:1], v2, off offset:128
	v_cvt_pk_bf16_f32 v2, -v35, s0
	global_store_short v[0:1], v2, off offset:256
	v_cvt_pk_bf16_f32 v2, -v36, s0
	global_store_short v[0:1], v2, off offset:384
	v_cvt_pk_bf16_f32 v2, -v37, s0
	global_store_short v[0:1], v2, off offset:512
	v_cvt_pk_bf16_f32 v2, -v38, s0
	global_store_short v[0:1], v2, off offset:640
	v_cvt_pk_bf16_f32 v2, -v39, s0
	global_store_short v[0:1], v2, off offset:768
	v_cvt_pk_bf16_f32 v2, -v40, s0
	global_store_short v[0:1], v2, off offset:896
	v_cvt_pk_bf16_f32 v2, -v41, s0
	global_store_short v[0:1], v2, off offset:1024
	v_cvt_pk_bf16_f32 v2, -v42, s0
	global_store_short v[0:1], v2, off offset:1152
	v_cvt_pk_bf16_f32 v2, -v43, s0
	global_store_short v[0:1], v2, off offset:1280
	v_cvt_pk_bf16_f32 v2, -v44, s0
	global_store_short v[0:1], v2, off offset:1408
	v_cvt_pk_bf16_f32 v2, -v45, s0
	global_store_short v[0:1], v2, off offset:1536
	v_cvt_pk_bf16_f32 v2, -v46, s0
	global_store_short v[0:1], v2, off offset:1664
	v_cvt_pk_bf16_f32 v2, -v47, s0
	global_store_short v[0:1], v2, off offset:1792
	v_cvt_pk_bf16_f32 v2, -v48, s0
	global_store_short v[0:1], v2, off offset:1920
	v_cvt_pk_bf16_f32 v2, -v49, s0
	global_store_short v[0:1], v2, off offset:2048
	v_cvt_pk_bf16_f32 v2, -v50, s0
	global_store_short v[0:1], v2, off offset:2176
	v_cvt_pk_bf16_f32 v2, -v51, s0
	global_store_short v[0:1], v2, off offset:2304
	v_cvt_pk_bf16_f32 v2, -v52, s0
	global_store_short v[0:1], v2, off offset:2432
	v_cvt_pk_bf16_f32 v2, -v53, s0
	global_store_short v[0:1], v2, off offset:2560
	v_cvt_pk_bf16_f32 v2, -v54, s0
	global_store_short v[0:1], v2, off offset:2688
	v_cvt_pk_bf16_f32 v2, -v55, s0
	global_store_short v[0:1], v2, off offset:2816
	v_cvt_pk_bf16_f32 v2, -v56, s0
	global_store_short v[0:1], v2, off offset:2944
	v_cvt_pk_bf16_f32 v2, -v57, s0
	global_store_short v[0:1], v2, off offset:3072
	v_cvt_pk_bf16_f32 v2, -v58, s0
	global_store_short v[0:1], v2, off offset:3200
	v_cvt_pk_bf16_f32 v2, -v59, s0
	global_store_short v[0:1], v2, off offset:3328
	v_cvt_pk_bf16_f32 v2, -v60, s0
	global_store_short v[0:1], v2, off offset:3456
	v_cvt_pk_bf16_f32 v2, -v61, s0
	global_store_short v[0:1], v2, off offset:3584
	v_cvt_pk_bf16_f32 v2, -v62, s0
	global_store_short v[0:1], v2, off offset:3712
	v_cvt_pk_bf16_f32 v2, -v63, s0
	global_store_short v[0:1], v2, off offset:3840

.LBB0_481:
	s_lshl_b32 s3, s25, 2
	s_and_b32 s60, s3, -16
	v_subrev_u32_e32 v0, s60, v96
	s_and_b32 s2, s25, 1
	v_add_u32_e32 v107, 0x3ff0, v0
	v_lshl_or_b32 v87, s2, 2, v98
	v_or_b32_e32 v0, v107, v97
	s_lshl_b32 s2, s25, 13
	s_and_b32 s84, s2, 0x4000
	v_ashrrev_i32_e32 v1, 31, v0
	v_lshl_add_u64 v[88:89], v[0:1], 0, s[84:85]
	v_mov_b64_e32 v[0:1], s[36:37]
	v_mad_u64_u32 v[0:1], s[2:3], v88, s10, v[0:1]
	v_mad_i32_i24 v1, v89, s10, v1
	v_lshlrev_b32_e32 v128, 7, v87
	v_lshl_add_u64 v[0:1], v[0:1], 0, v[128:129]
	v_mov_b32_e32 v85, v129
	v_lshl_add_u64 v[0:1], v[0:1], 0, v[84:85]
	s_mov_b64 s[2:3], 0x4000800
	v_lshl_add_u64 v[4:5], v[0:1], 0, s[2:3]
	v_add_co_u32_e32 v0, vcc, s11, v0
	s_sub_i32 s3, 0x3fe0, s60
	s_nop 0
	v_addc_co_u32_e32 v1, vcc, 0, v1, vcc
	global_load_dwordx4 v[0:3], v[0:1], off offset:2048
	s_nop 0
	global_load_dwordx4 v[4:7], v[4:5], off offset:64
	v_mul_u32_u24_e32 v134, 3, v87
	v_lshlrev_b64 v[132:133], 7, v[88:89]
	v_lshl_add_u64 v[132:133], s[40:41], 0, v[132:133]
	v_lshlrev_b32_e32 v134, 2, v134
	v_mov_b32_e32 v135, 0
	v_lshl_add_u64 v[132:133], v[132:133], 0, v[134:135]
	global_load_dword v136, v[132:133], off
	s_ashr_i32 s3, s3, 4
	s_add_i32 s3, s3, 32
	s_lshr_b32 s3, s3, 5
	s_and_b32 s72, s94, 3
	s_add_i32 s2, s60, 0xffffc000
	s_add_i32 s3, s3, -1
	s_cmpk_lt_i32 s2, 0xffe1
	s_cselect_b32 s66, s3, -1
	s_cmp_lt_i32 s66, 0
	s_waitcnt vmcnt(1)
	ds_write_b128 v99, v[0:3] offset:32768
	s_waitcnt vmcnt(0)
	ds_write_b128 v99, v[4:7] offset:32832
	s_cbranch_scc1 .LBB0_570
	s_and_b32 s2, s25, 3
	v_mov_b32_e32 v3, v218
	s_lshl_b32 s74, s2, 17
	s_add_u32 s64, s26, s74
	v_ashrrev_i32_e32 v0, 3, v3
	v_ashrrev_i32_e32 v1, 31, v0
	s_addc_u32 s65, s27, 0
	v_lshlrev_b64 v[4:5], 7, v[0:1]
	v_lshl_add_u64 v[6:7], s[64:65], 0, v[4:5]
	v_lshlrev_b32_e32 v4, 4, v3
	v_and_b32_e32 v128, 0x70, v4
	v_lshl_add_u64 v[40:41], v[6:7], 0, v[128:129]
	v_add_co_u32_e32 v6, vcc, 0x1000, v40
	s_cmp_gt_u32 s66, 1
	s_nop 0
	v_addc_co_u32_e32 v7, vcc, 0, v41, vcc
	global_load_dwordx4 v[8:11], v[40:41], off
	global_load_dwordx4 v[12:15], v[6:7], off
	s_cselect_b64 s[62:63], -1, 0
	s_cmp_lt_u32 s66, 2
	s_cbranch_scc1 .LBB0_484
	v_add_co_u32_e32 v6, vcc, 0x2000, v40
	s_nop 1
	v_addc_co_u32_e32 v7, vcc, 0, v41, vcc
	v_add_co_u32_e32 v20, vcc, 0x3000, v40
	s_nop 1
	v_addc_co_u32_e32 v21, vcc, 0, v41, vcc
	global_load_dwordx4 v[16:19], v[6:7], off
	s_nop 0
	global_load_dwordx4 v[20:23], v[20:21], off

.LBB0_571:
	s_lshl_b32 s2, s72, 19
	s_and_b32 s84, s2, 0x100000
	s_and_b32 s2, s82, -16
	v_subrev_u32_e32 v0, s2, v106
	v_ashrrev_i32_e32 v1, 31, v0
	v_lshlrev_b64 v[0:1], 6, v[0:1]
	v_lshl_add_u64 v[0:1], s[84:85], 0, v[0:1]
	v_cndmask_b32_e64 v3, 0, 1, s[80:81]
	v_lshl_or_b32 v0, v3, 5, v0
	v_mul_u32_u24_e32 v3, 3, v87
	v_lshlrev_b64 v[4:5], 7, v[88:89]
	v_lshl_add_u64 v[4:5], s[40:41], 0, v[4:5]
	v_lshlrev_b32_e32 v128, 2, v3
	v_lshl_add_u64 v[4:5], v[4:5], 0, v[128:129]
	v_lshlrev_b32_e32 v2, 6, v87
	v_lshlrev_b64 v[4:5], 11, v[88:89]
	v_lshl_add_u64 v[4:5], s[38:39], 0, v[4:5]
	v_lshlrev_b32_e32 v128, 2, v2
	v_mov_b32_e32 v87, v129
	v_lshl_add_u64 v[0:1], v[82:83], 0, v[0:1]
	s_mov_b32 s84, 0
	s_waitcnt vmcnt(0)
	v_mul_f32_e32 v3, 0xbfb8aa3b, v136
	v_exp_f32_e32 v3, v3
	s_nop 0
	v_add_f32_e32 v3, 1.0, v3
	v_rcp_f32_e32 v6, v3
	v_lshl_add_u64 v[2:3], v[4:5], 0, v[128:129]
	v_lshl_add_u64 v[8:9], v[2:3], 0, v[86:87]
	v_pk_mul_f32 v[2:3], v[48:49], v[6:7] op_sel_hi:[1,0]
	v_pk_mul_f32 v[4:5], v[50:51], v[6:7] op_sel_hi:[1,0]
	global_store_dwordx4 v[8:9], v[2:5], off
	s_nop 1
	v_pk_mul_f32 v[2:3], v[56:57], v[6:7] op_sel_hi:[1,0]
	v_pk_mul_f32 v[4:5], v[58:59], v[6:7] op_sel_hi:[1,0]
	global_store_dwordx4 v[8:9], v[2:5], off offset:64
	s_nop 1
	v_pk_mul_f32 v[2:3], v[52:53], v[6:7] op_sel_hi:[1,0]
	v_pk_mul_f32 v[4:5], v[54:55], v[6:7] op_sel_hi:[1,0]
	global_store_dwordx4 v[8:9], v[2:5], off offset:128
	s_nop 1
	v_pk_mul_f32 v[2:3], v[60:61], v[6:7] op_sel_hi:[1,0]
	v_pk_mul_f32 v[4:5], v[62:63], v[6:7] op_sel_hi:[1,0]
	global_store_dwordx4 v[8:9], v[2:5], off offset:192
	s_nop 1
	v_ashrrev_i32_e32 v3, 6, v107
	v_lshrrev_b32_e32 v2, 5, v3
	v_add_u32_e32 v5, -1, v3
	v_cmp_eq_u32_e64 s[60:61], v94, v2
	v_lshlrev_b32_e64 v2, v3, 1
	v_lshrrev_b32_e32 v6, 5, v5
	v_add_u32_e32 v4, -2, v3
	v_cndmask_b32_e64 v2, 0, v2, s[60:61]
	v_cmp_eq_u32_e64 s[60:61], v94, v6
	v_lshlrev_b32_e64 v5, v5, 1
	v_cmp_lt_i32_e32 vcc, 15, v3
	v_cndmask_b32_e64 v5, 0, v5, s[60:61]
	v_lshl_add_u32 v3, 2, v3, -1
	v_cmp_gt_i32_e64 s[60:61], v94, v4
	v_or3_b32 v2, v2, v100, v5
	v_cndmask_b32_e64 v3, 0, v3, s[44:45]
	s_or_b64 s[86:87], s[44:45], s[60:61]
	v_cmp_gt_i32_e64 s[60:61], v101, v4
	v_cmp_gt_i32_e64 s[62:63], v102, v4
	v_cmp_gt_i32_e64 s[64:65], v103, v4
	s_branch .LBB0_573

.LBB0_638:
	global_load_dword v104, v[210:211], off offset:36
	global_load_dwordx4 v[106:109], v[202:203], off
	global_load_dwordx4 v[110:113], v[202:203], off offset:64
	global_load_dwordx4 v[114:117], v[202:203], off offset:128
	global_load_dwordx4 v[118:121], v[202:203], off offset:192
	global_load_dword v105, v[212:213], off offset:36
	global_load_dwordx4 v[122:125], v[192:193], off
	global_load_dwordx4 v[130:133], v[192:193], off offset:64
	global_load_dwordx4 v[134:137], v[192:193], off offset:128
	global_load_dwordx4 v[158:161], v[192:193], off offset:192
	global_load_dword v126, v[196:197], off offset:36
	global_load_dwordx4 v[162:165], v[194:195], off
	global_load_dwordx4 v[166:169], v[194:195], off offset:64
	global_load_dwordx4 v[170:173], v[194:195], off offset:128
	global_load_dwordx4 v[174:177], v[194:195], off offset:192
	global_load_dword v127, v[200:201], off offset:36
	global_load_dwordx4 v[178:181], v[190:191], off
	global_load_dwordx4 v[182:185], v[190:191], off offset:64
	global_load_dwordx4 v[186:189], v[190:191], off offset:128
	global_load_dwordx4 v[248:251], v[190:191], off offset:192
	v_add_f32_e32 v0, 0, v154
	v_add_f32_e32 v4, 0, v150
	v_add_f32_e32 v5, 0, v142
	v_add_f32_e32 v6, 0, v146
	s_mov_b64 s[40:41], 0
	s_waitcnt vmcnt(19)
	v_mul_f32_e32 v1, 0xbfb8aa3b, v104
	v_exp_f32_e32 v1, v1
	s_nop 0
	v_add_f32_e32 v1, 1.0, v1
	v_rcp_f32_e32 v1, v1
	s_nop 0
	v_div_scale_f32 v2, s[2:3], v0, v0, v1
	v_rcp_f32_e32 v3, v2
	s_nop 0
	v_fma_f32 v7, -v2, v3, 1.0
	v_fmac_f32_e32 v3, v7, v3
	v_div_scale_f32 v7, vcc, v1, v0, v1
	v_mul_f32_e32 v56, v7, v3
	v_fma_f32 v57, -v2, v56, v7
	v_fmac_f32_e32 v56, v57, v3
	v_fma_f32 v2, -v2, v56, v7
	v_div_fmas_f32 v2, v2, v3, v56
	v_div_fixup_f32 v2, v2, v0, v1
	v_lshl_add_u64 v[0:1], s[36:37], 0, v[214:215]
	v_lshl_add_u64 v[56:57], v[0:1], 0, v[128:129]
	v_lshlrev_b32_e32 v0, 1, v241
	v_mov_b32_e32 v1, v129
	v_lshl_add_u64 v[68:69], v[56:57], 0, v[0:1]
	s_waitcnt vmcnt(18)
	v_pk_fma_f32 v[56:57], v[100:101], v[2:3], v[106:107] op_sel_hi:[1,0,1]
	v_pk_fma_f32 v[58:59], v[102:103], v[2:3], v[108:109] op_sel_hi:[1,0,1]
	v_cvt_pk_bf16_f32 v56, v56, v57
	v_cvt_pk_bf16_f32 v57, v58, v59
	global_store_dwordx2 v[68:69], v[56:57], off offset:512
	s_waitcnt vmcnt(18)
	v_pk_fma_f32 v[56:57], v[72:73], v[2:3], v[110:111] op_sel_hi:[1,0,1]
	v_pk_fma_f32 v[58:59], v[74:75], v[2:3], v[112:113] op_sel_hi:[1,0,1]
	v_cvt_pk_bf16_f32 v56, v56, v57
	v_cvt_pk_bf16_f32 v57, v58, v59
	global_store_dwordx2 v[68:69], v[56:57], off offset:544
	s_waitcnt vmcnt(18)
	v_pk_fma_f32 v[56:57], v[64:65], v[2:3], v[114:115] op_sel_hi:[1,0,1]
	v_pk_fma_f32 v[58:59], v[66:67], v[2:3], v[116:117] op_sel_hi:[1,0,1]
	v_cvt_pk_bf16_f32 v56, v56, v57
	v_cvt_pk_bf16_f32 v57, v58, v59
	global_store_dwordx2 v[68:69], v[56:57], off offset:576
	s_waitcnt vmcnt(18)
	v_pk_fma_f32 v[56:57], v[60:61], v[2:3], v[118:119] op_sel_hi:[1,0,1]
	v_pk_fma_f32 v[2:3], v[62:63], v[2:3], v[120:121] op_sel_hi:[1,0,1]
	v_cvt_pk_bf16_f32 v56, v56, v57
	v_cvt_pk_bf16_f32 v57, v2, v3
	global_store_dwordx2 v[68:69], v[56:57], off offset:608
	s_waitcnt vmcnt(18)
	v_mul_f32_e32 v2, 0xbfb8aa3b, v105
	v_exp_f32_e32 v2, v2
	s_nop 0
	v_add_f32_e32 v2, 1.0, v2
	v_rcp_f32_e32 v2, v2
	s_nop 0
	v_div_scale_f32 v3, s[2:3], v4, v4, v2
	v_rcp_f32_e32 v7, v3
	s_nop 0
	v_fma_f32 v56, -v3, v7, 1.0
	v_fmac_f32_e32 v7, v56, v7
	v_div_scale_f32 v56, vcc, v2, v4, v2
	v_mul_f32_e32 v57, v56, v7
	v_fma_f32 v58, -v3, v57, v56
	v_fmac_f32_e32 v57, v58, v7
	v_fma_f32 v3, -v3, v57, v56
	v_div_fmas_f32 v3, v3, v7, v57
	v_div_fixup_f32 v4, v3, v4, v2
	v_lshl_add_u64 v[2:3], s[36:37], 0, v[216:217]
	v_lshl_add_u64 v[2:3], v[2:3], 0, v[128:129]
	v_lshl_add_u64 v[2:3], v[2:3], 0, v[0:1]
	s_waitcnt vmcnt(17)
	v_pk_fma_f32 v[52:53], v[52:53], v[4:5], v[122:123] op_sel_hi:[1,0,1]
	v_pk_fma_f32 v[54:55], v[54:55], v[4:5], v[124:125] op_sel_hi:[1,0,1]
	v_cvt_pk_bf16_f32 v52, v52, v53
	v_cvt_pk_bf16_f32 v53, v54, v55
	global_store_dwordx2 v[2:3], v[52:53], off offset:512
	s_waitcnt vmcnt(17)
	v_pk_fma_f32 v[48:49], v[48:49], v[4:5], v[130:131] op_sel_hi:[1,0,1]
	v_pk_fma_f32 v[50:51], v[50:51], v[4:5], v[132:133] op_sel_hi:[1,0,1]
	v_cvt_pk_bf16_f32 v48, v48, v49
	v_cvt_pk_bf16_f32 v49, v50, v51
	global_store_dwordx2 v[2:3], v[48:49], off offset:544
	s_waitcnt vmcnt(17)
	v_pk_fma_f32 v[44:45], v[44:45], v[4:5], v[134:135] op_sel_hi:[1,0,1]
	v_pk_fma_f32 v[46:47], v[46:47], v[4:5], v[136:137] op_sel_hi:[1,0,1]
	v_cvt_pk_bf16_f32 v44, v44, v45
	v_cvt_pk_bf16_f32 v45, v46, v47
	global_store_dwordx2 v[2:3], v[44:45], off offset:576
	s_waitcnt vmcnt(17)
	v_pk_fma_f32 v[40:41], v[40:41], v[4:5], v[158:159] op_sel_hi:[1,0,1]
	v_pk_fma_f32 v[42:43], v[42:43], v[4:5], v[160:161] op_sel_hi:[1,0,1]
	v_cvt_pk_bf16_f32 v40, v40, v41
	v_cvt_pk_bf16_f32 v41, v42, v43
	global_store_dwordx2 v[2:3], v[40:41], off offset:608
	s_waitcnt vmcnt(17)
	v_mul_f32_e32 v2, 0xbfb8aa3b, v126
	v_exp_f32_e32 v2, v2
	s_nop 0
	v_add_f32_e32 v2, 1.0, v2
	v_rcp_f32_e32 v2, v2
	s_nop 0
	v_div_scale_f32 v3, s[2:3], v6, v6, v2
	v_rcp_f32_e32 v4, v3
	s_nop 0
	v_fma_f32 v7, -v3, v4, 1.0
	v_fmac_f32_e32 v4, v7, v4
	v_div_scale_f32 v7, vcc, v2, v6, v2
	v_mul_f32_e32 v40, v7, v4
	v_fma_f32 v41, -v3, v40, v7
	v_fmac_f32_e32 v40, v41, v4
	v_fma_f32 v3, -v3, v40, v7
	v_div_fmas_f32 v3, v3, v4, v40
	v_div_fixup_f32 v2, v3, v6, v2
	v_lshl_add_u64 v[6:7], s[36:37], 0, v[204:205]
	v_lshl_add_u64 v[6:7], v[6:7], 0, v[128:129]
	v_lshl_add_u64 v[6:7], v[6:7], 0, v[0:1]
	s_waitcnt vmcnt(16)
	v_pk_fma_f32 v[36:37], v[36:37], v[2:3], v[162:163] op_sel_hi:[1,0,1]
	v_pk_fma_f32 v[38:39], v[38:39], v[2:3], v[164:165] op_sel_hi:[1,0,1]
	v_cvt_pk_bf16_f32 v36, v36, v37
	v_cvt_pk_bf16_f32 v37, v38, v39
	global_store_dwordx2 v[6:7], v[36:37], off offset:512
	s_waitcnt vmcnt(16)
	v_pk_fma_f32 v[32:33], v[32:33], v[2:3], v[166:167] op_sel_hi:[1,0,1]
	v_pk_fma_f32 v[34:35], v[34:35], v[2:3], v[168:169] op_sel_hi:[1,0,1]
	v_cvt_pk_bf16_f32 v32, v32, v33
	v_cvt_pk_bf16_f32 v33, v34, v35
	global_store_dwordx2 v[6:7], v[32:33], off offset:544
	s_waitcnt vmcnt(16)
	v_pk_fma_f32 v[28:29], v[28:29], v[2:3], v[170:171] op_sel_hi:[1,0,1]
	v_pk_fma_f32 v[30:31], v[30:31], v[2:3], v[172:173] op_sel_hi:[1,0,1]
	v_cvt_pk_bf16_f32 v28, v28, v29
	v_cvt_pk_bf16_f32 v29, v30, v31
	global_store_dwordx2 v[6:7], v[28:29], off offset:576
	s_waitcnt vmcnt(16)
	v_pk_fma_f32 v[24:25], v[24:25], v[2:3], v[174:175] op_sel_hi:[1,0,1]
	v_pk_fma_f32 v[2:3], v[26:27], v[2:3], v[176:177] op_sel_hi:[1,0,1]
	v_cvt_pk_bf16_f32 v24, v24, v25
	v_cvt_pk_bf16_f32 v25, v2, v3
	global_store_dwordx2 v[6:7], v[24:25], off offset:608
	s_waitcnt vmcnt(16)
	v_mul_f32_e32 v2, 0xbfb8aa3b, v127
	v_exp_f32_e32 v2, v2
	s_nop 0
	v_add_f32_e32 v2, 1.0, v2
	v_rcp_f32_e32 v2, v2
	s_nop 0
	v_div_scale_f32 v3, s[2:3], v5, v5, v2
	v_rcp_f32_e32 v4, v3
	s_nop 0
	v_fma_f32 v6, -v3, v4, 1.0
	v_fmac_f32_e32 v4, v6, v4
	v_div_scale_f32 v6, vcc, v2, v5, v2
	v_mul_f32_e32 v7, v6, v4
	v_fma_f32 v24, -v3, v7, v6
	v_fmac_f32_e32 v7, v24, v4
	v_fma_f32 v3, -v3, v7, v6
	v_div_fmas_f32 v3, v3, v4, v7
	v_div_fixup_f32 v2, v3, v5, v2
	v_lshl_add_u64 v[4:5], s[36:37], 0, v[206:207]
	v_lshl_add_u64 v[4:5], v[4:5], 0, v[128:129]
	v_lshl_add_u64 v[0:1], v[4:5], 0, v[0:1]
	s_waitcnt vmcnt(15)
	v_pk_fma_f32 v[4:5], v[20:21], v[2:3], v[178:179] op_sel_hi:[1,0,1]
	v_pk_fma_f32 v[6:7], v[22:23], v[2:3], v[180:181] op_sel_hi:[1,0,1]
	v_cvt_pk_bf16_f32 v4, v4, v5
	v_cvt_pk_bf16_f32 v5, v6, v7
	global_store_dwordx2 v[0:1], v[4:5], off offset:512
	s_waitcnt vmcnt(15)
	v_pk_fma_f32 v[4:5], v[16:17], v[2:3], v[182:183] op_sel_hi:[1,0,1]
	v_pk_fma_f32 v[6:7], v[18:19], v[2:3], v[184:185] op_sel_hi:[1,0,1]
	v_cvt_pk_bf16_f32 v4, v4, v5
	v_cvt_pk_bf16_f32 v5, v6, v7
	global_store_dwordx2 v[0:1], v[4:5], off offset:544
	s_waitcnt vmcnt(15)
	v_pk_fma_f32 v[4:5], v[12:13], v[2:3], v[186:187] op_sel_hi:[1,0,1]
	v_pk_fma_f32 v[6:7], v[14:15], v[2:3], v[188:189] op_sel_hi:[1,0,1]
	v_cvt_pk_bf16_f32 v4, v4, v5
	v_cvt_pk_bf16_f32 v5, v6, v7
	global_store_dwordx2 v[0:1], v[4:5], off offset:576
	s_waitcnt vmcnt(15)
	v_pk_fma_f32 v[4:5], v[8:9], v[2:3], v[248:249] op_sel_hi:[1,0,1]
	v_pk_fma_f32 v[2:3], v[10:11], v[2:3], v[250:251] op_sel_hi:[1,0,1]
	v_cvt_pk_bf16_f32 v4, v4, v5
	v_cvt_pk_bf16_f32 v5, v2, v3
	global_store_dwordx2 v[0:1], v[4:5], off offset:608

.LBB0_748:
	s_waitcnt vmcnt(3)
	v_mul_u32_u24_e32 v0, 3, v214
	v_lshlrev_b32_e32 v0, 2, v0
	v_mov_b32_e32 v1, v129
	v_lshl_add_u64 v[2:3], s[58:59], 0, v[0:1]
	s_waitcnt vmcnt(1)
	v_lshlrev_b64 v[8:9], 7, v[200:201]
	v_lshl_add_u64 v[210:211], v[2:3], 0, v[8:9]
	global_load_dword v14, v[210:211], off offset:40
	v_add_f32_e32 v4, 0, v162
	v_lshlrev_b32_e32 v0, 2, v203
	v_lshl_add_u64 v[0:1], s[60:61], 0, v[0:1]
	v_mov_b32_e32 v203, v129
	v_lshl_add_u64 v[0:1], v[0:1], 0, v[202:203]
	v_lshlrev_b64 v[214:215], 11, v[200:201]
	v_lshl_add_u64 v[202:203], v[0:1], 0, v[214:215]
	global_load_dwordx4 v[56:59], v[202:203], off
	global_load_dwordx4 v[104:107], v[202:203], off offset:64
	global_load_dwordx4 v[108:111], v[202:203], off offset:128
	global_load_dwordx4 v[112:115], v[202:203], off offset:192
	v_add_f32_e32 v5, 0, v150
	v_add_f32_e32 v7, 0, v158
	v_lshlrev_b64 v[216:217], 11, v[204:205]
	v_lshl_add_u64 v[192:193], v[0:1], 0, v[216:217]
	global_load_dwordx4 v[174:177], v[192:193], off
	global_load_dwordx4 v[178:181], v[192:193], off offset:64
	global_load_dwordx4 v[182:185], v[192:193], off offset:128
	global_load_dwordx4 v[186:189], v[192:193], off offset:192
	v_add_f32_e32 v6, 0, v154
	s_lshl_b32 s29, s45, 6
	s_lshl_b32 s28, s28, 20
	s_waitcnt vmcnt(8)
	v_mul_f32_e32 v8, 0xbfb8aa3b, v14
	v_exp_f32_e32 v8, v8
	s_nop 0
	v_add_f32_e32 v8, 1.0, v8
	v_rcp_f32_e32 v8, v8
	s_nop 0
	v_div_scale_f32 v9, s[2:3], v4, v4, v8
	v_rcp_f32_e32 v10, v9
	s_nop 0
	v_fma_f32 v11, -v9, v10, 1.0
	v_fmac_f32_e32 v10, v11, v10
	v_div_scale_f32 v11, vcc, v8, v4, v8
	v_mul_f32_e32 v12, v11, v10
	v_fma_f32 v13, -v9, v12, v11
	v_fmac_f32_e32 v12, v13, v10
	v_fma_f32 v9, -v9, v12, v11
	v_div_fmas_f32 v9, v9, v10, v12
	v_div_fixup_f32 v4, v9, v4, v8
	v_mov_b32_e32 v13, v129
	s_waitcnt vmcnt(7)
	v_pk_fma_f32 v[8:9], v[146:147], v[4:5], v[56:57] op_sel_hi:[1,0,1]
	v_pk_fma_f32 v[10:11], v[148:149], v[4:5], v[58:59] op_sel_hi:[1,0,1]
	global_store_dwordx4 v[202:203], v[8:11], off
	s_nop 1
	s_waitcnt vmcnt(7)
	v_pk_fma_f32 v[8:9], v[142:143], v[4:5], v[104:105] op_sel_hi:[1,0,1]
	v_pk_fma_f32 v[10:11], v[144:145], v[4:5], v[106:107] op_sel_hi:[1,0,1]
	global_store_dwordx4 v[202:203], v[8:11], off offset:64
	s_nop 1
	s_waitcnt vmcnt(7)
	v_pk_fma_f32 v[8:9], v[138:139], v[4:5], v[108:109] op_sel_hi:[1,0,1]
	v_pk_fma_f32 v[10:11], v[140:141], v[4:5], v[110:111] op_sel_hi:[1,0,1]
	global_store_dwordx4 v[202:203], v[8:11], off offset:128
	s_nop 1
	s_waitcnt vmcnt(7)
	v_pk_fma_f32 v[8:9], v[134:135], v[4:5], v[112:113] op_sel_hi:[1,0,1]
	v_pk_fma_f32 v[10:11], v[136:137], v[4:5], v[114:115] op_sel_hi:[1,0,1]
	global_store_dwordx4 v[202:203], v[8:11], off offset:192
	s_nop 1
	s_nop 1
	v_lshlrev_b64 v[8:9], 7, v[204:205]
	v_lshl_add_u64 v[212:213], v[2:3], 0, v[8:9]
	global_load_dword v15, v[212:213], off offset:40
	v_lshlrev_b64 v[204:205], 11, v[206:207]
	v_lshl_add_u64 v[194:195], v[0:1], 0, v[204:205]
	global_load_dwordx4 v[242:245], v[194:195], off
	global_load_dwordx4 v[246:249], v[194:195], off offset:64
	global_load_dwordx4 v[56:59], v[194:195], off offset:128
	global_load_dwordx4 v[104:107], v[194:195], off offset:192
	s_waitcnt vmcnt(4)
	v_mul_f32_e32 v4, 0xbfb8aa3b, v15
	v_exp_f32_e32 v4, v4
	s_nop 0
	v_add_f32_e32 v4, 1.0, v4
	v_rcp_f32_e32 v4, v4
	s_nop 0
	v_div_scale_f32 v8, s[2:3], v7, v7, v4
	v_rcp_f32_e32 v9, v8
	s_nop 0
	v_fma_f32 v10, -v8, v9, 1.0
	v_fmac_f32_e32 v9, v10, v9
	v_div_scale_f32 v10, vcc, v4, v7, v4
	v_mul_f32_e32 v11, v10, v9
	v_fma_f32 v12, -v8, v11, v10
	v_fmac_f32_e32 v11, v12, v9
	v_fma_f32 v8, -v8, v11, v10
	v_div_fmas_f32 v8, v8, v9, v11
	v_div_fixup_f32 v4, v8, v7, v4
	v_pk_fma_f32 v[8:9], v[130:131], v[4:5], v[174:175] op_sel_hi:[1,0,1]
	v_pk_fma_f32 v[10:11], v[132:133], v[4:5], v[176:177] op_sel_hi:[1,0,1]
	global_store_dwordx4 v[192:193], v[8:11], off
	s_nop 1
	v_pk_fma_f32 v[8:9], v[124:125], v[4:5], v[178:179] op_sel_hi:[1,0,1]
	v_pk_fma_f32 v[10:11], v[126:127], v[4:5], v[180:181] op_sel_hi:[1,0,1]
	global_store_dwordx4 v[192:193], v[8:11], off offset:64
	s_nop 1
	v_pk_fma_f32 v[8:9], v[120:121], v[4:5], v[182:183] op_sel_hi:[1,0,1]
	v_pk_fma_f32 v[10:11], v[122:123], v[4:5], v[184:185] op_sel_hi:[1,0,1]
	global_store_dwordx4 v[192:193], v[8:11], off offset:128
	s_nop 1
	v_pk_fma_f32 v[8:9], v[116:117], v[4:5], v[186:187] op_sel_hi:[1,0,1]
	v_pk_fma_f32 v[10:11], v[118:119], v[4:5], v[188:189] op_sel_hi:[1,0,1]
	global_store_dwordx4 v[192:193], v[8:11], off offset:192
	s_nop 1
	s_nop 1
	v_lshlrev_b64 v[8:9], 7, v[206:207]
	v_lshl_add_u64 v[196:197], v[2:3], 0, v[8:9]
	global_load_dword v151, v[196:197], off offset:40
	v_lshlrev_b64 v[206:207], 11, v[208:209]
	v_lshl_add_u64 v[190:191], v[0:1], 0, v[206:207]
	global_load_dwordx4 v[108:111], v[190:191], off
	global_load_dwordx4 v[112:115], v[190:191], off offset:64
	global_load_dwordx4 v[174:177], v[190:191], off offset:128
	global_load_dwordx4 v[178:181], v[190:191], off offset:192
	s_waitcnt vmcnt(4)
	v_mul_f32_e32 v4, 0xbfb8aa3b, v151
	v_exp_f32_e32 v4, v4
	s_nop 0
	v_add_f32_e32 v4, 1.0, v4
	v_rcp_f32_e32 v4, v4
	s_nop 0
	v_div_scale_f32 v7, s[2:3], v6, v6, v4
	v_rcp_f32_e32 v8, v7
	s_nop 0
	v_fma_f32 v9, -v7, v8, 1.0
	v_fmac_f32_e32 v8, v9, v8
	v_div_scale_f32 v9, vcc, v4, v6, v4
	v_mul_f32_e32 v10, v9, v8
	v_fma_f32 v11, -v7, v10, v9
	v_fmac_f32_e32 v10, v11, v8
	v_fma_f32 v7, -v7, v10, v9
	v_div_fmas_f32 v7, v7, v8, v10
	v_div_fixup_f32 v4, v7, v6, v4
	v_pk_fma_f32 v[6:7], v[96:97], v[4:5], v[242:243] op_sel_hi:[1,0,1]
	v_pk_fma_f32 v[8:9], v[98:99], v[4:5], v[244:245] op_sel_hi:[1,0,1]
	global_store_dwordx4 v[194:195], v[6:9], off
	s_nop 1
	v_pk_fma_f32 v[6:7], v[92:93], v[4:5], v[246:247] op_sel_hi:[1,0,1]
	v_pk_fma_f32 v[8:9], v[94:95], v[4:5], v[248:249] op_sel_hi:[1,0,1]
	global_store_dwordx4 v[194:195], v[6:9], off offset:64
	s_nop 1
	v_pk_fma_f32 v[6:7], v[88:89], v[4:5], v[56:57] op_sel_hi:[1,0,1]
	v_pk_fma_f32 v[8:9], v[90:91], v[4:5], v[58:59] op_sel_hi:[1,0,1]
	global_store_dwordx4 v[194:195], v[6:9], off offset:128
	s_nop 1
	v_pk_fma_f32 v[6:7], v[84:85], v[4:5], v[104:105] op_sel_hi:[1,0,1]
	v_pk_fma_f32 v[8:9], v[86:87], v[4:5], v[106:107] op_sel_hi:[1,0,1]
	global_store_dwordx4 v[194:195], v[6:9], off offset:192
	s_nop 1
	s_nop 1
	v_lshlrev_b64 v[6:7], 7, v[208:209]
	v_lshl_add_u64 v[200:201], v[2:3], 0, v[6:7]
	global_load_dword v152, v[200:201], off offset:40
	s_waitcnt vmcnt(0)
	v_mul_f32_e32 v2, 0xbfb8aa3b, v152
	v_exp_f32_e32 v2, v2
	s_nop 0
	v_add_f32_e32 v2, 1.0, v2
	v_rcp_f32_e32 v2, v2
	s_nop 0
	v_div_scale_f32 v3, s[2:3], v5, v5, v2
	v_rcp_f32_e32 v4, v3
	s_lshl_b32 s2, s29, 1
	s_add_u32 s2, s26, s2
	s_addc_u32 s3, s27, 0
	v_fma_f32 v6, -v3, v4, 1.0
	v_fmac_f32_e32 v4, v6, v4
	v_div_scale_f32 v6, vcc, v2, v5, v2
	v_mul_f32_e32 v7, v6, v4
	v_fma_f32 v8, -v3, v7, v6
	v_fmac_f32_e32 v7, v8, v4
	v_fma_f32 v3, -v3, v7, v6
	v_div_fmas_f32 v3, v3, v4, v7
	v_div_fixup_f32 v2, v3, v5, v2
	v_mov_b32_e32 v8, v218
	s_lshl_b32 s26, s28, 1
	s_add_u32 s26, s67, s26
	s_addc_u32 s27, s68, 0
	s_cmpk_eq_i32 s64, 0xff
	v_pk_fma_f32 v[4:5], v[80:81], v[2:3], v[108:109] op_sel_hi:[1,0,1]
	v_pk_fma_f32 v[6:7], v[82:83], v[2:3], v[110:111] op_sel_hi:[1,0,1]
	global_store_dwordx4 v[190:191], v[4:7], off
	s_nop 1
	v_pk_fma_f32 v[4:5], v[76:77], v[2:3], v[112:113] op_sel_hi:[1,0,1]
	v_pk_fma_f32 v[6:7], v[78:79], v[2:3], v[114:115] op_sel_hi:[1,0,1]
	global_store_dwordx4 v[190:191], v[4:7], off offset:64
	s_nop 1
	v_pk_fma_f32 v[4:5], v[68:69], v[2:3], v[174:175] op_sel_hi:[1,0,1]
	v_pk_fma_f32 v[6:7], v[70:71], v[2:3], v[176:177] op_sel_hi:[1,0,1]
	global_store_dwordx4 v[190:191], v[4:7], off offset:128
	s_nop 1
	v_pk_fma_f32 v[0:1], v[32:33], v[2:3], v[178:179] op_sel_hi:[1,0,1]
	v_pk_fma_f32 v[2:3], v[34:35], v[2:3], v[180:181] op_sel_hi:[1,0,1]
	global_store_dwordx4 v[190:191], v[0:3], off offset:192
	s_nop 1
	s_nop 0
	v_ashrrev_i32_e32 v9, 3, v8
	v_mov_b64_e32 v[0:1], s[2:3]
	v_lshlrev_b32_e32 v10, 4, v8
	v_ashrrev_i32_e32 v6, 2, v8
	v_mad_i64_i32 v[0:1], s[2:3], v9, s10, v[0:1]
	v_and_b32_e32 v2, 0x70, v10
	v_mov_b32_e32 v3, v129
	v_ashrrev_i32_e32 v7, 31, v6
	v_lshl_add_u64 v[208:209], v[0:1], 0, v[2:3]
	v_lshlrev_b64 v[0:1], 7, v[6:7]
	v_lshl_add_u64 v[4:5], s[26:27], 0, v[0:1]
	v_and_b32_e32 v12, 48, v10
	v_lshl_add_u64 v[4:5], v[4:5], 0, v[12:13]
	v_add_co_u32_e32 v12, vcc, 0x30000, v208
	s_waitcnt lgkmcnt(2)
	global_load_dwordx4 v[56:59], v[208:209], off offset:3584
	v_addc_co_u32_e32 v13, vcc, 0, v209, vcc
	global_load_dwordx4 v[68:71], v[12:13], off offset:3584
	global_load_dwordx4 v[84:87], v[4:5], off
	global_load_dwordx4 v[96:99], v[4:5], off offset:64
	s_mov_b64 s[2:3], 0xe00
	v_lshl_add_u64 v[2:3], v[208:209], 0, s[2:3]
	s_cbranch_scc1 .LBB0_750
	v_add_co_u32_e32 v12, vcc, 0x60000, v2
	s_nop 1
	v_addc_co_u32_e32 v13, vcc, 0, v3, vcc
	v_add_co_u32_e32 v14, vcc, 0x90000, v2
	s_nop 1
	v_addc_co_u32_e32 v15, vcc, 0, v3, vcc
	global_load_dwordx4 v[76:79], v[12:13], off
	global_load_dwordx4 v[80:83], v[14:15], off
	v_add_co_u32_e32 v12, vcc, 0x2000, v4
	s_nop 1
	v_addc_co_u32_e32 v13, vcc, 0, v5, vcc
	global_load_dwordx4 v[88:91], v[12:13], off
	global_load_dwordx4 v[92:95], v[12:13], off offset:64

.LBB0_973:
	v_add_u32_e32 v190, s26, v196
	v_or_b32_e32 v188, s27, v197
	v_ashrrev_i32_e32 v191, 31, v190
	v_ashrrev_i32_e32 v189, 31, v188
	v_lshlrev_b64 v[198:199], 10, v[190:191]
	v_lshl_add_u64 v[198:199], v[198:199], 0, v[188:189]
	v_lshlrev_b64 v[202:203], 2, v[198:199]
	v_lshl_add_u64 v[204:205], s[36:37], 0, v[202:203]
	v_lshl_add_u64 v[202:203], s[44:45], 0, v[202:203]
	s_mov_b32 s26, s29
	s_andn2_b64 vcc, exec, s[38:39]
	s_mov_b32 s27, s28
	v_mov_b32_e32 v190, 0x20000
	v_mov_b32_e32 v191, 0
	global_load_dwordx4 v[198:201], v[204:205], off
	global_load_dwordx4 v[206:209], v[204:205], off offset:32
	global_load_dwordx4 v[210:213], v[204:205], off offset:64
	global_load_dwordx4 v[214:217], v[204:205], off offset:96
	global_load_dwordx4 v[234:237], v[204:205], off offset:128
	global_load_dwordx4 v[240:243], v[204:205], off offset:160
	global_load_dwordx4 v[244:247], v[204:205], off offset:192
	global_load_dwordx4 v[248:251], v[204:205], off offset:224
	s_waitcnt vmcnt(0)
	v_pk_add_f32 v[112:113], v[112:113], v[198:199]
	v_pk_add_f32 v[114:115], v[114:115], v[200:201]
	v_pk_add_f32 v[116:117], v[116:117], v[206:207]
	v_pk_add_f32 v[118:119], v[118:119], v[208:209]
	v_pk_add_f32 v[120:121], v[120:121], v[210:211]
	v_pk_add_f32 v[122:123], v[122:123], v[212:213]
	v_pk_add_f32 v[124:125], v[124:125], v[214:215]
	v_pk_add_f32 v[126:127], v[126:127], v[216:217]
	v_pk_add_f32 v[96:97], v[96:97], v[234:235]
	v_pk_add_f32 v[98:99], v[98:99], v[236:237]
	v_pk_add_f32 v[100:101], v[100:101], v[240:241]
	v_pk_add_f32 v[102:103], v[102:103], v[242:243]
	v_pk_add_f32 v[104:105], v[104:105], v[244:245]
	v_pk_add_f32 v[106:107], v[106:107], v[246:247]
	v_pk_add_f32 v[108:109], v[108:109], v[248:249]
	v_pk_add_f32 v[110:111], v[110:111], v[250:251]
	v_lshl_add_u64 v[204:205], v[204:205], 0, v[190:191]
	global_load_dwordx4 v[198:201], v[204:205], off
	global_load_dwordx4 v[206:209], v[204:205], off offset:32
	global_load_dwordx4 v[210:213], v[204:205], off offset:64
	global_load_dwordx4 v[214:217], v[204:205], off offset:96
	global_load_dwordx4 v[234:237], v[204:205], off offset:128
	global_load_dwordx4 v[240:243], v[204:205], off offset:160
	global_load_dwordx4 v[244:247], v[204:205], off offset:192
	global_load_dwordx4 v[248:251], v[204:205], off offset:224
	global_store_dwordx4 v[202:203], v[112:115], off
	global_store_dwordx4 v[202:203], v[116:119], off offset:32
	global_store_dwordx4 v[202:203], v[120:123], off offset:64
	global_store_dwordx4 v[202:203], v[124:127], off offset:96
	global_store_dwordx4 v[202:203], v[96:99], off offset:128
	global_store_dwordx4 v[202:203], v[100:103], off offset:160
	global_store_dwordx4 v[202:203], v[104:107], off offset:192
	global_store_dwordx4 v[202:203], v[108:111], off offset:224
	s_waitcnt vmcnt(8)
	v_lshl_add_u64 v[202:203], v[202:203], 0, v[190:191]
	v_pk_add_f32 v[80:81], v[80:81], v[198:199]
	v_pk_add_f32 v[82:83], v[82:83], v[200:201]
	v_pk_add_f32 v[84:85], v[84:85], v[206:207]
	v_pk_add_f32 v[86:87], v[86:87], v[208:209]
	v_pk_add_f32 v[88:89], v[88:89], v[210:211]
	v_pk_add_f32 v[90:91], v[90:91], v[212:213]
	v_pk_add_f32 v[92:93], v[92:93], v[214:215]
	v_pk_add_f32 v[94:95], v[94:95], v[216:217]
	v_pk_add_f32 v[64:65], v[64:65], v[234:235]
	v_pk_add_f32 v[66:67], v[66:67], v[236:237]
	v_pk_add_f32 v[68:69], v[68:69], v[240:241]
	v_pk_add_f32 v[70:71], v[70:71], v[242:243]
	v_pk_add_f32 v[72:73], v[72:73], v[244:245]
	v_pk_add_f32 v[74:75], v[74:75], v[246:247]
	v_pk_add_f32 v[76:77], v[76:77], v[248:249]
	v_pk_add_f32 v[78:79], v[78:79], v[250:251]
	v_lshl_add_u64 v[204:205], v[204:205], 0, v[190:191]
	global_load_dwordx4 v[198:201], v[204:205], off
	global_load_dwordx4 v[206:209], v[204:205], off offset:32
	global_load_dwordx4 v[210:213], v[204:205], off offset:64
	global_load_dwordx4 v[214:217], v[204:205], off offset:96
	global_load_dwordx4 v[234:237], v[204:205], off offset:128
	global_load_dwordx4 v[240:243], v[204:205], off offset:160
	global_load_dwordx4 v[244:247], v[204:205], off offset:192
	global_load_dwordx4 v[248:251], v[204:205], off offset:224
	global_store_dwordx4 v[202:203], v[80:83], off
	global_store_dwordx4 v[202:203], v[84:87], off offset:32
	global_store_dwordx4 v[202:203], v[88:91], off offset:64
	global_store_dwordx4 v[202:203], v[92:95], off offset:96
	global_store_dwordx4 v[202:203], v[64:67], off offset:128
	global_store_dwordx4 v[202:203], v[68:71], off offset:160
	global_store_dwordx4 v[202:203], v[72:75], off offset:192
	global_store_dwordx4 v[202:203], v[76:79], off offset:224
	s_waitcnt vmcnt(8)
	v_lshl_add_u64 v[202:203], v[202:203], 0, v[190:191]
	v_pk_add_f32 v[48:49], v[48:49], v[198:199]
	v_pk_add_f32 v[50:51], v[50:51], v[200:201]
	v_pk_add_f32 v[52:53], v[52:53], v[206:207]
	v_pk_add_f32 v[54:55], v[54:55], v[208:209]
	v_pk_add_f32 v[56:57], v[56:57], v[210:211]
	v_pk_add_f32 v[58:59], v[58:59], v[212:213]
	v_pk_add_f32 v[60:61], v[60:61], v[214:215]
	v_pk_add_f32 v[62:63], v[62:63], v[216:217]
	v_pk_add_f32 v[32:33], v[32:33], v[234:235]
	v_pk_add_f32 v[34:35], v[34:35], v[236:237]
	v_pk_add_f32 v[36:37], v[36:37], v[240:241]
	v_pk_add_f32 v[38:39], v[38:39], v[242:243]
	v_pk_add_f32 v[40:41], v[40:41], v[244:245]
	v_pk_add_f32 v[42:43], v[42:43], v[246:247]
	v_pk_add_f32 v[44:45], v[44:45], v[248:249]
	v_pk_add_f32 v[46:47], v[46:47], v[250:251]
	v_lshl_add_u64 v[204:205], v[204:205], 0, v[190:191]
	global_load_dwordx4 v[198:201], v[204:205], off
	global_load_dwordx4 v[206:209], v[204:205], off offset:32
	global_load_dwordx4 v[210:213], v[204:205], off offset:64
	global_load_dwordx4 v[214:217], v[204:205], off offset:96
	global_load_dwordx4 v[234:237], v[204:205], off offset:128
	global_load_dwordx4 v[240:243], v[204:205], off offset:160
	global_load_dwordx4 v[244:247], v[204:205], off offset:192
	global_load_dwordx4 v[248:251], v[204:205], off offset:224
	global_store_dwordx4 v[202:203], v[48:51], off
	global_store_dwordx4 v[202:203], v[52:55], off offset:32
	global_store_dwordx4 v[202:203], v[56:59], off offset:64
	global_store_dwordx4 v[202:203], v[60:63], off offset:96
	global_store_dwordx4 v[202:203], v[32:35], off offset:128
	global_store_dwordx4 v[202:203], v[36:39], off offset:160
	global_store_dwordx4 v[202:203], v[40:43], off offset:192
	global_store_dwordx4 v[202:203], v[44:47], off offset:224
	s_waitcnt vmcnt(8)
	v_lshl_add_u64 v[202:203], v[202:203], 0, v[190:191]
	v_pk_add_f32 v[16:17], v[16:17], v[198:199]
	v_pk_add_f32 v[18:19], v[18:19], v[200:201]
	v_pk_add_f32 v[20:21], v[20:21], v[206:207]
	v_pk_add_f32 v[22:23], v[22:23], v[208:209]
	v_pk_add_f32 v[24:25], v[24:25], v[210:211]
	v_pk_add_f32 v[26:27], v[26:27], v[212:213]
	v_pk_add_f32 v[28:29], v[28:29], v[214:215]
	v_pk_add_f32 v[30:31], v[30:31], v[216:217]
	v_pk_add_f32 v[0:1], v[0:1], v[234:235]
	v_pk_add_f32 v[2:3], v[2:3], v[236:237]
	v_pk_add_f32 v[4:5], v[4:5], v[240:241]
	v_pk_add_f32 v[6:7], v[6:7], v[242:243]
	v_pk_add_f32 v[8:9], v[8:9], v[244:245]
	v_pk_add_f32 v[10:11], v[10:11], v[246:247]
	v_pk_add_f32 v[12:13], v[12:13], v[248:249]
	v_pk_add_f32 v[14:15], v[14:15], v[250:251]
	global_store_dwordx4 v[202:203], v[16:19], off
	global_store_dwordx4 v[202:203], v[20:23], off offset:32
	global_store_dwordx4 v[202:203], v[24:27], off offset:64
	global_store_dwordx4 v[202:203], v[28:31], off offset:96
	global_store_dwordx4 v[202:203], v[0:3], off offset:128
	global_store_dwordx4 v[202:203], v[4:7], off offset:160
	global_store_dwordx4 v[202:203], v[8:11], off offset:192
	global_store_dwordx4 v[202:203], v[12:15], off offset:224
	s_cbranch_vccz .LBB0_978

.LBB0_1148:
	v_add_u32_e32 v190, s26, v196
	v_or_b32_e32 v188, s27, v197
	v_ashrrev_i32_e32 v191, 31, v190
	v_ashrrev_i32_e32 v189, 31, v188
	v_lshlrev_b64 v[198:199], 12, v[190:191]
	v_lshl_add_u64 v[198:199], s[44:45], 0, v[198:199]
	v_lshlrev_b64 v[188:189], 2, v[188:189]
	v_lshl_add_u64 v[202:203], v[198:199], 0, v[188:189]
	s_andn2_b64 vcc, exec, s[36:37]
	s_mov_b32 s26, s29
	s_mov_b32 s27, s28
	v_mov_b32_e32 v190, 0x20000
	v_mov_b32_e32 v191, 0
	v_mov_b32_e32 v204, v202
	v_mov_b32_e32 v205, v203
	global_load_dwordx4 v[198:201], v[204:205], off
	global_load_dwordx4 v[206:209], v[204:205], off offset:32
	global_load_dwordx4 v[210:213], v[204:205], off offset:64
	global_load_dwordx4 v[214:217], v[204:205], off offset:96
	global_load_dwordx4 v[234:237], v[204:205], off offset:128
	global_load_dwordx4 v[240:243], v[204:205], off offset:160
	global_load_dwordx4 v[244:247], v[204:205], off offset:192
	global_load_dwordx4 v[248:251], v[204:205], off offset:224
	s_waitcnt vmcnt(0)
	v_pk_add_f32 v[112:113], v[112:113], v[198:199]
	v_pk_add_f32 v[114:115], v[114:115], v[200:201]
	v_pk_add_f32 v[116:117], v[116:117], v[206:207]
	v_pk_add_f32 v[118:119], v[118:119], v[208:209]
	v_pk_add_f32 v[120:121], v[120:121], v[210:211]
	v_pk_add_f32 v[122:123], v[122:123], v[212:213]
	v_pk_add_f32 v[124:125], v[124:125], v[214:215]
	v_pk_add_f32 v[126:127], v[126:127], v[216:217]
	v_pk_add_f32 v[96:97], v[96:97], v[234:235]
	v_pk_add_f32 v[98:99], v[98:99], v[236:237]
	v_pk_add_f32 v[100:101], v[100:101], v[240:241]
	v_pk_add_f32 v[102:103], v[102:103], v[242:243]
	v_pk_add_f32 v[104:105], v[104:105], v[244:245]
	v_pk_add_f32 v[106:107], v[106:107], v[246:247]
	v_pk_add_f32 v[108:109], v[108:109], v[248:249]
	v_pk_add_f32 v[110:111], v[110:111], v[250:251]
	v_lshl_add_u64 v[204:205], v[204:205], 0, v[190:191]
	global_load_dwordx4 v[198:201], v[204:205], off
	global_load_dwordx4 v[206:209], v[204:205], off offset:32
	global_load_dwordx4 v[210:213], v[204:205], off offset:64
	global_load_dwordx4 v[214:217], v[204:205], off offset:96
	global_load_dwordx4 v[234:237], v[204:205], off offset:128
	global_load_dwordx4 v[240:243], v[204:205], off offset:160
	global_load_dwordx4 v[244:247], v[204:205], off offset:192
	global_load_dwordx4 v[248:251], v[204:205], off offset:224
	global_store_dwordx4 v[202:203], v[112:115], off
	global_store_dwordx4 v[202:203], v[116:119], off offset:32
	global_store_dwordx4 v[202:203], v[120:123], off offset:64
	global_store_dwordx4 v[202:203], v[124:127], off offset:96
	global_store_dwordx4 v[202:203], v[96:99], off offset:128
	global_store_dwordx4 v[202:203], v[100:103], off offset:160
	global_store_dwordx4 v[202:203], v[104:107], off offset:192
	global_store_dwordx4 v[202:203], v[108:111], off offset:224
	s_waitcnt vmcnt(8)
	v_lshl_add_u64 v[202:203], v[202:203], 0, v[190:191]
	v_pk_add_f32 v[80:81], v[80:81], v[198:199]
	v_pk_add_f32 v[82:83], v[82:83], v[200:201]
	v_pk_add_f32 v[84:85], v[84:85], v[206:207]
	v_pk_add_f32 v[86:87], v[86:87], v[208:209]
	v_pk_add_f32 v[88:89], v[88:89], v[210:211]
	v_pk_add_f32 v[90:91], v[90:91], v[212:213]
	v_pk_add_f32 v[92:93], v[92:93], v[214:215]
	v_pk_add_f32 v[94:95], v[94:95], v[216:217]
	v_pk_add_f32 v[64:65], v[64:65], v[234:235]
	v_pk_add_f32 v[66:67], v[66:67], v[236:237]
	v_pk_add_f32 v[68:69], v[68:69], v[240:241]
	v_pk_add_f32 v[70:71], v[70:71], v[242:243]
	v_pk_add_f32 v[72:73], v[72:73], v[244:245]
	v_pk_add_f32 v[74:75], v[74:75], v[246:247]
	v_pk_add_f32 v[76:77], v[76:77], v[248:249]
	v_pk_add_f32 v[78:79], v[78:79], v[250:251]
	v_lshl_add_u64 v[204:205], v[204:205], 0, v[190:191]
	global_load_dwordx4 v[198:201], v[204:205], off
	global_load_dwordx4 v[206:209], v[204:205], off offset:32
	global_load_dwordx4 v[210:213], v[204:205], off offset:64
	global_load_dwordx4 v[214:217], v[204:205], off offset:96
	global_load_dwordx4 v[234:237], v[204:205], off offset:128
	global_load_dwordx4 v[240:243], v[204:205], off offset:160
	global_load_dwordx4 v[244:247], v[204:205], off offset:192
	global_load_dwordx4 v[248:251], v[204:205], off offset:224
	global_store_dwordx4 v[202:203], v[80:83], off
	global_store_dwordx4 v[202:203], v[84:87], off offset:32
	global_store_dwordx4 v[202:203], v[88:91], off offset:64
	global_store_dwordx4 v[202:203], v[92:95], off offset:96
	global_store_dwordx4 v[202:203], v[64:67], off offset:128
	global_store_dwordx4 v[202:203], v[68:71], off offset:160
	global_store_dwordx4 v[202:203], v[72:75], off offset:192
	global_store_dwordx4 v[202:203], v[76:79], off offset:224
	s_waitcnt vmcnt(8)
	v_lshl_add_u64 v[202:203], v[202:203], 0, v[190:191]
	v_pk_add_f32 v[48:49], v[48:49], v[198:199]
	v_pk_add_f32 v[50:51], v[50:51], v[200:201]
	v_pk_add_f32 v[52:53], v[52:53], v[206:207]
	v_pk_add_f32 v[54:55], v[54:55], v[208:209]
	v_pk_add_f32 v[56:57], v[56:57], v[210:211]
	v_pk_add_f32 v[58:59], v[58:59], v[212:213]
	v_pk_add_f32 v[60:61], v[60:61], v[214:215]
	v_pk_add_f32 v[62:63], v[62:63], v[216:217]
	v_pk_add_f32 v[32:33], v[32:33], v[234:235]
	v_pk_add_f32 v[34:35], v[34:35], v[236:237]
	v_pk_add_f32 v[36:37], v[36:37], v[240:241]
	v_pk_add_f32 v[38:39], v[38:39], v[242:243]
	v_pk_add_f32 v[40:41], v[40:41], v[244:245]
	v_pk_add_f32 v[42:43], v[42:43], v[246:247]
	v_pk_add_f32 v[44:45], v[44:45], v[248:249]
	v_pk_add_f32 v[46:47], v[46:47], v[250:251]
	v_lshl_add_u64 v[204:205], v[204:205], 0, v[190:191]
	global_load_dwordx4 v[198:201], v[204:205], off
	global_load_dwordx4 v[206:209], v[204:205], off offset:32
	global_load_dwordx4 v[210:213], v[204:205], off offset:64
	global_load_dwordx4 v[214:217], v[204:205], off offset:96
	global_load_dwordx4 v[234:237], v[204:205], off offset:128
	global_load_dwordx4 v[240:243], v[204:205], off offset:160
	global_load_dwordx4 v[244:247], v[204:205], off offset:192
	global_load_dwordx4 v[248:251], v[204:205], off offset:224
	global_store_dwordx4 v[202:203], v[48:51], off
	global_store_dwordx4 v[202:203], v[52:55], off offset:32
	global_store_dwordx4 v[202:203], v[56:59], off offset:64
	global_store_dwordx4 v[202:203], v[60:63], off offset:96
	global_store_dwordx4 v[202:203], v[32:35], off offset:128
	global_store_dwordx4 v[202:203], v[36:39], off offset:160
	global_store_dwordx4 v[202:203], v[40:43], off offset:192
	global_store_dwordx4 v[202:203], v[44:47], off offset:224
	s_waitcnt vmcnt(8)
	v_lshl_add_u64 v[202:203], v[202:203], 0, v[190:191]
	v_pk_add_f32 v[16:17], v[16:17], v[198:199]
	v_pk_add_f32 v[18:19], v[18:19], v[200:201]
	v_pk_add_f32 v[20:21], v[20:21], v[206:207]
	v_pk_add_f32 v[22:23], v[22:23], v[208:209]
	v_pk_add_f32 v[24:25], v[24:25], v[210:211]
	v_pk_add_f32 v[26:27], v[26:27], v[212:213]
	v_pk_add_f32 v[28:29], v[28:29], v[214:215]
	v_pk_add_f32 v[30:31], v[30:31], v[216:217]
	v_pk_add_f32 v[0:1], v[0:1], v[234:235]
	v_pk_add_f32 v[2:3], v[2:3], v[236:237]
	v_pk_add_f32 v[4:5], v[4:5], v[240:241]
	v_pk_add_f32 v[6:7], v[6:7], v[242:243]
	v_pk_add_f32 v[8:9], v[8:9], v[244:245]
	v_pk_add_f32 v[10:11], v[10:11], v[246:247]
	v_pk_add_f32 v[12:13], v[12:13], v[248:249]
	v_pk_add_f32 v[14:15], v[14:15], v[250:251]
	global_store_dwordx4 v[202:203], v[16:19], off
	global_store_dwordx4 v[202:203], v[20:23], off offset:32
	global_store_dwordx4 v[202:203], v[24:27], off offset:64
	global_store_dwordx4 v[202:203], v[28:31], off offset:96
	global_store_dwordx4 v[202:203], v[0:3], off offset:128
	global_store_dwordx4 v[202:203], v[4:7], off offset:160
	global_store_dwordx4 v[202:203], v[8:11], off offset:192
	global_store_dwordx4 v[202:203], v[12:15], off offset:224
	s_cbranch_vccz .LBB0_1153
